# P4 block mapping: a row tile's four column blocks on two XCDs (A re-read 2x instead of 4x), on top of unified P1 job loop + next-job first-slab request
# speedup vs baseline: 1.0080x; 1.0070x over previous
; template <bool SWAP, class Epi>
; DI void gemm_tile(const u16* __restrict__ A, int lda, const u16* __restrict__ Bw, int ldb, int K, char* lds, Epi epi) {
;   const int tid = opaque_tid(), lane = tid & 63, w = tid >> 6, r = lane & 31, h = lane >> 5;
;   const int wm = w & 3, wn = w >> 2;
;   f32x16 acc[2][2];
; #pragma unroll
;   for (int a = 0; a < 2; ++a)
; #pragma unroll
;     for (int b = 0; b < 2; ++b)
; #pragma unroll
;       for (int i = 0; i < 16; ++i) acc[a][b][i] = 0.f;
;   const int lrow = tid >> 3, lkc = tid & 7;
;   u32x4 ra0[4], rb0[2], ra1[4], rb1[2];
;   const u16* ap = A + (size_t)lrow * lda + lkc * 8;
;   const u16* bp = Bw + (size_t)lrow * ldb + lkc * 8;
;   const int nk = K >> 6;
;   auto gload = [&](int kt, u32x4* ra, u32x4* rb) {
; #pragma unroll
;     for (int j = 0; j < 4; ++j) ra[j] = *(const u32x4*)(ap + (size_t)(64 * j) * lda + kt * 64);
; #pragma unroll
;     for (int j = 0; j < 2; ++j) rb[j] = *(const u32x4*)(bp + (size_t)(64 * j) * ldb + kt * 64);
;   };
;   auto lstore = [&](int st, const u32x4* ra, const u32x4* rb) {
;     char* base = lds + st * GEMM_STAGE;
; #pragma unroll
;     for (int j = 0; j < 4; ++j) *(u32x4*)(base + ((lrow + 64 * j) * 72 + lkc * 8) * 2) = ra[j];
; #pragma unroll
;     for (int j = 0; j < 2; ++j) *(u32x4*)(base + 36864 + ((lrow + 64 * j) * 72 + lkc * 8) * 2) = rb[j];
;   };
;   auto compute = [&](int st) {
;     const char* as = lds + st * GEMM_STAGE;
;     const char* bs = as + 36864;
; #pragma unroll
;     for (int ks = 0; ks < 4; ++ks) {
;       bf16x8 af[2], bfr[2];
; #pragma unroll
;       for (int mi = 0; mi < 2; ++mi) af[mi] = *(const bf16x8*)(as + ((wm * 64 + mi * 32 + r) * 72 + ks * 16 + 8 * h) * 2);
; #pragma unroll
;       for (int ni = 0; ni < 2; ++ni) bfr[ni] = *(const bf16x8*)(bs + ((wn * 64 + ni * 32 + r) * 72 + ks * 16 + 8 * h) * 2);
; #pragma unroll
;       for (int mi = 0; mi < 2; ++mi)
; #pragma unroll
;         for (int ni = 0; ni < 2; ++ni) {
;           if (SWAP) acc[mi][ni] = MFMA32(bfr[ni], af[mi], acc[mi][ni]);
;           else acc[mi][ni] = MFMA32(af[mi], bfr[ni], acc[mi][ni]);
;         }
;     }
;   };
;   gload(0, ra0, rb0);
; __global__ void __launch_bounds__(NTHREADS) mega(Params p) {
;     ...
;     for (int j = blockIdx.x; j < 512; j += gridDim.x) {
;       const int x = j & 7, a = j >> 3;
;       outproj_tile(p, l, 2 * (a >> 1) + (x >> 2), 2 * (x & 3) + (a & 1), lds, -1);
.LBB0_2481:
	s_or_b64 exec, exec, s[0:1]
	v_readlane_b32 s0, v239, 3
	v_readlane_b32 s1, v239, 4
	s_and_b64 vcc, exec, s[0:1]
	s_waitcnt lgkmcnt(0)
	s_barrier
	s_cbranch_vccz .LBB0_2492
	v_readlane_b32 s0, v238, 35
	v_readlane_b32 s1, v238, 36
	s_nop 0
	v_readlane_b32 s10, v241, 18
	v_cndmask_b32_e64 v0, 0, 1, s[0:1]
	s_lshl_b32 s0, s38, 22
	s_and_b32 s0, s0, 0x400000
	v_lshlrev_b32_e32 v2, 22, v0
	v_readlane_b32 s11, v241, 19
	s_add_u32 s6, s10, s0
	s_addc_u32 s7, s11, 0
	v_lshl_add_u64 v[0:1], s[10:11], 0, v[2:3]
	v_readlane_b32 s8, v238, 15
	v_readlane_b32 s17, v241, 25
	v_readlane_b32 s0, v238, 16
	s_and_b32 s1, s0, 1
	s_lshl_b32 s2, s1, 1
	s_bfe_u32 s1, s0, 0x10003
	s_add_i32 s2, s2, s1
	s_lshr_b32 s26, s0, 4
	s_lshl_b32 s26, s26, 2
	s_bfe_u32 s1, s0, 0x20001
	s_add_i32 s26, s26, s1
	v_readlane_b32 s4, v241, 28
	v_readlane_b32 s5, v241, 29
	v_readlane_b32 s24, v240, 15
	v_readlane_b32 s25, v240, 16
	v_lshrrev_b32_e32 v2, 6, v152
	v_and_b32_e32 v4, 63, v152
	s_lshl_b32 s0, s26, 20
	s_add_u32 s4, s4, s0
	s_addc_u32 s5, s5, 0
	s_lshl_b32 s0, s2, 20
	s_add_u32 s14, s6, s0
	s_addc_u32 s15, s7, 0
	v_readfirstlane_b32 s3, v2
	s_lshl_b32 s0, s3, 17
	s_add_u32 s68, s4, s0
	s_addc_u32 s69, s5, 0
	s_add_u32 s70, s68, 0x7c00
	s_addc_u32 s71, s69, 0
	s_add_u32 s72, s70, 0x7c00
	s_addc_u32 s73, s71, 0
	s_add_u32 s74, s72, 0x7c00
	s_addc_u32 s75, s73, 0
	s_add_u32 s76, s14, s0
	s_addc_u32 s77, s15, 0
	s_add_u32 s78, s76, 0x7c00
	s_addc_u32 s79, s77, 0
	s_add_u32 s80, s78, 0x7c00
	s_addc_u32 s81, s79, 0
	s_add_u32 s82, s80, 0x7c00
	s_addc_u32 s83, s81, 0
	s_lshl_b32 s40, s3, 12
	s_add_i32 s44, s40, 0
	s_add_i32 s45, s40, 0x8000
	s_add_i32 s46, s40, 0x10000
	s_add_i32 s47, s40, 0x18000
	v_lshrrev_b32_e32 v2, 4, v4
	v_and_b32_e32 v5, 7, v4
	v_xor_b32_e32 v2, v2, v5
	v_lshlrev_b32_e32 v2, 4, v2
	v_lshrrev_b32_e32 v5, 3, v4
	v_lshlrev_b32_e32 v5, 12, v5
	v_add_u32_e32 v178, v2, v5
	v_xor_b32_e32 v179, 64, v178
	s_mov_b32 m0, s44
	s_nop 0
	global_load_lds_dwordx4 v178, s[68:69]
	global_load_lds_dwordx4 v179, s[70:71] offset:1024
	global_load_lds_dwordx4 v178, s[72:73] offset:2048
	global_load_lds_dwordx4 v179, s[74:75] offset:3072
	s_mov_b32 m0, s46
	s_nop 0
	global_load_lds_dwordx4 v178, s[76:77]
	global_load_lds_dwordx4 v179, s[78:79] offset:1024
	global_load_lds_dwordx4 v178, s[80:81] offset:2048
	global_load_lds_dwordx4 v179, s[82:83] offset:3072
	v_add_u32_e32 v178, 0x80, v178
	v_add_u32_e32 v179, 0x80, v179
	v_and_b32_e32 v5, 31, v4
	v_lshrrev_b32_e32 v2, 1, v5
	v_and_b32_e32 v2, 7, v2
	v_lshrrev_b32_e32 v4, 5, v4
	v_xor_b32_e32 v2, v2, v4
	v_lshlrev_b32_e32 v5, 7, v5
	s_and_b32 s0, s3, 3
	s_lshr_b32 s1, s3, 2
	s_lshl_b32 s10, s0, 13
	s_lshl_b32 s11, s1, 13
	s_add_i32 s11, s11, 0x10000
	v_xor_b32_e32 v232, 0, v2
	v_lshl_add_u32 v232, v232, 4, v5
	v_add_u32_e32 v228, s10, v232
	v_add_u32_e32 v232, s11, v232
	v_xor_b32_e32 v233, 2, v2
	v_lshl_add_u32 v233, v233, 4, v5
	v_add_u32_e32 v229, s10, v233
	v_add_u32_e32 v233, s11, v233
	v_xor_b32_e32 v234, 4, v2
	v_lshl_add_u32 v234, v234, 4, v5
	v_add_u32_e32 v230, s10, v234
	v_add_u32_e32 v234, s11, v234
	v_xor_b32_e32 v235, 6, v2
	v_lshl_add_u32 v235, v235, 4, v5
	v_add_u32_e32 v231, s10, v235
	v_add_u32_e32 v235, s11, v235
	s_lshl_b32 s12, s26, 8
	s_lshl_b32 s0, s0, 6
	s_add_i32 s12, s12, s0
	v_lshrrev_b32_e32 v5, 7, v5
	v_add_u32_e32 v5, s12, v5
	v_lshlrev_b32_e32 v5, 12, v5
	s_lshl_b32 s12, s2, 10
	s_lshl_b32 s1, s1, 8
	s_add_i32 s12, s12, s1
	v_lshlrev_b32_e32 v4, 4, v4
	v_add3_u32 v242, v5, v4, s12
	v_add_u32_e32 v243, 0x20000, v242
	s_waitcnt vmcnt(0) lgkmcnt(0)
	s_barrier
	ds_read_b128 v[132:135], v228 offset:0
	ds_read_b128 v[136:139], v228 offset:4096
	ds_read_b128 v[140:143], v232 offset:0
	ds_read_b128 v[144:147], v232 offset:4096
	ds_read_b128 v[148:151], v232 offset:16384
	ds_read_b128 v[180:183], v232 offset:20480
	s_mov_b32 m0, s45
	s_nop 0
	global_load_lds_dwordx4 v178, s[68:69]
	global_load_lds_dwordx4 v179, s[70:71] offset:1024
	global_load_lds_dwordx4 v178, s[72:73] offset:2048
	global_load_lds_dwordx4 v179, s[74:75] offset:3072
	ds_read_b128 v[184:187], v229 offset:0
	ds_read_b128 v[208:211], v229 offset:4096
	ds_read_b128 v[212:215], v233 offset:0
	ds_read_b128 v[216:219], v233 offset:4096
	ds_read_b128 v[220:223], v233 offset:16384
	ds_read_b128 v[224:227], v233 offset:20480
	s_waitcnt lgkmcnt(6)
	v_mfma_f32_32x32x16_bf16 v[4:19], v[140:143], v[132:135], 0
	v_mfma_f32_32x32x16_bf16 v[68:83], v[140:143], v[136:139], 0
	v_mfma_f32_32x32x16_bf16 v[20:35], v[144:147], v[132:135], 0
	v_mfma_f32_32x32x16_bf16 v[84:99], v[144:147], v[136:139], 0
	v_mfma_f32_32x32x16_bf16 v[36:51], v[148:151], v[132:135], 0
	v_mfma_f32_32x32x16_bf16 v[100:115], v[148:151], v[136:139], 0
	v_mfma_f32_32x32x16_bf16 v[52:67], v[180:183], v[132:135], 0
	v_mfma_f32_32x32x16_bf16 v[116:131], v[180:183], v[136:139], 0
	s_mov_b32 m0, s47
	s_nop 0
	global_load_lds_dwordx4 v178, s[76:77]
	global_load_lds_dwordx4 v179, s[78:79] offset:1024
	global_load_lds_dwordx4 v178, s[80:81] offset:2048
	global_load_lds_dwordx4 v179, s[82:83] offset:3072
	v_add_u32_e32 v178, 0x80, v178
	v_add_u32_e32 v179, 0x80, v179
	ds_read_b128 v[132:135], v230 offset:0
	ds_read_b128 v[136:139], v230 offset:4096
	ds_read_b128 v[140:143], v234 offset:0
	ds_read_b128 v[144:147], v234 offset:4096
	ds_read_b128 v[148:151], v234 offset:16384
	ds_read_b128 v[180:183], v234 offset:20480
	s_waitcnt lgkmcnt(6)
; #define MFMA32(a, b, c) __builtin_amdgcn_mfma_f32_32x32x16_bf16((a), (b), (c), 0, 0, 0)
; template <bool SWAP, class Epi>
; DI void gemm_tile(const u16* __restrict__ A, int lda, const u16* __restrict__ Bw, int ldb, int K, char* lds, Epi epi) {
;     ...
;   auto compute = [&](int st) {
;     const char* as = lds + st * GEMM_STAGE;
;     const char* bs = as + 36864;
; #pragma unroll
;     for (int ks = 0; ks < 4; ++ks) {
;       bf16x8 af[2], bfr[2];
; #pragma unroll
;       for (int mi = 0; mi < 2; ++mi) af[mi] = *(const bf16x8*)(as + ((wm * 64 + mi * 32 + r) * 72 + ks * 16 + 8 * h) * 2);
; #pragma unroll
;       for (int ni = 0; ni < 2; ++ni) bfr[ni] = *(const bf16x8*)(bs + ((wn * 64 + ni * 32 + r) * 72 + ks * 16 + 8 * h) * 2);
; #pragma unroll
;       for (int mi = 0; mi < 2; ++mi)
; #pragma unroll
;         for (int ni = 0; ni < 2; ++ni) {
;           if (SWAP) acc[mi][ni] = MFMA32(bfr[ni], af[mi], acc[mi][ni]);
;           else acc[mi][ni] = MFMA32(af[mi], bfr[ni], acc[mi][ni]);
;         }
;     }
;   };
;   gload(0, ra0, rb0);
;   lstore(0, ra0, rb0);
;   gload(1, ra1, rb1);
;   __syncthreads();
;   for (int kt = 0; kt < nk; kt += 2) {
;     if (kt + 2 < nk) gload(kt + 2, ra0, rb0);
;     compute(0);
;     lstore(1, ra1, rb1);
;     __syncthreads();
;     if (kt + 3 < nk) gload(kt + 3, ra1, rb1);
;     compute(1);
;     if (kt + 2 < nk) lstore(0, ra0, rb0);
;     __syncthreads();
	v_mfma_f32_32x32x16_bf16 v[4:19], v[212:215], v[184:187], v[4:19]
	v_mfma_f32_32x32x16_bf16 v[68:83], v[212:215], v[208:211], v[68:83]
	v_mfma_f32_32x32x16_bf16 v[20:35], v[216:219], v[184:187], v[20:35]
	v_mfma_f32_32x32x16_bf16 v[84:99], v[216:219], v[208:211], v[84:99]
	v_mfma_f32_32x32x16_bf16 v[36:51], v[220:223], v[184:187], v[36:51]
	v_mfma_f32_32x32x16_bf16 v[100:115], v[220:223], v[208:211], v[100:115]
	v_mfma_f32_32x32x16_bf16 v[52:67], v[224:227], v[184:187], v[52:67]
	v_mfma_f32_32x32x16_bf16 v[116:131], v[224:227], v[208:211], v[116:131]
	ds_read_b128 v[184:187], v231 offset:0
	ds_read_b128 v[208:211], v231 offset:4096
	ds_read_b128 v[212:215], v235 offset:0
	ds_read_b128 v[216:219], v235 offset:4096
	ds_read_b128 v[220:223], v235 offset:16384
	ds_read_b128 v[224:227], v235 offset:20480
	s_waitcnt lgkmcnt(6)
	v_mfma_f32_32x32x16_bf16 v[4:19], v[140:143], v[132:135], v[4:19]
	v_mfma_f32_32x32x16_bf16 v[68:83], v[140:143], v[136:139], v[68:83]
	v_mfma_f32_32x32x16_bf16 v[20:35], v[144:147], v[132:135], v[20:35]
	v_mfma_f32_32x32x16_bf16 v[84:99], v[144:147], v[136:139], v[84:99]
	v_mfma_f32_32x32x16_bf16 v[36:51], v[148:151], v[132:135], v[36:51]
	v_mfma_f32_32x32x16_bf16 v[100:115], v[148:151], v[136:139], v[100:115]
	v_mfma_f32_32x32x16_bf16 v[52:67], v[180:183], v[132:135], v[52:67]
	v_mfma_f32_32x32x16_bf16 v[116:131], v[180:183], v[136:139], v[116:131]
	s_waitcnt lgkmcnt(0)
	v_mfma_f32_32x32x16_bf16 v[4:19], v[212:215], v[184:187], v[4:19]
	v_mfma_f32_32x32x16_bf16 v[68:83], v[212:215], v[208:211], v[68:83]
	v_mfma_f32_32x32x16_bf16 v[20:35], v[216:219], v[184:187], v[20:35]
	v_mfma_f32_32x32x16_bf16 v[84:99], v[216:219], v[208:211], v[84:99]
	v_mfma_f32_32x32x16_bf16 v[36:51], v[220:223], v[184:187], v[36:51]
	v_mfma_f32_32x32x16_bf16 v[100:115], v[220:223], v[208:211], v[100:115]
	v_mfma_f32_32x32x16_bf16 v[52:67], v[224:227], v[184:187], v[52:67]
	v_mfma_f32_32x32x16_bf16 v[116:131], v[224:227], v[208:211], v[116:131]
	s_waitcnt vmcnt(0) lgkmcnt(0)
	s_barrier
	ds_read_b128 v[132:135], v228 offset:32768
	ds_read_b128 v[136:139], v228 offset:36864
	ds_read_b128 v[140:143], v232 offset:32768
	ds_read_b128 v[144:147], v232 offset:36864
	ds_read_b128 v[148:151], v232 offset:49152
	ds_read_b128 v[180:183], v232 offset:53248
	s_mov_b32 m0, s44
	s_nop 0
	global_load_lds_dwordx4 v178, s[68:69]
	global_load_lds_dwordx4 v179, s[70:71] offset:1024
	global_load_lds_dwordx4 v178, s[72:73] offset:2048
	global_load_lds_dwordx4 v179, s[74:75] offset:3072
	ds_read_b128 v[184:187], v229 offset:32768
	ds_read_b128 v[208:211], v229 offset:36864
	ds_read_b128 v[212:215], v233 offset:32768
	ds_read_b128 v[216:219], v233 offset:36864
	ds_read_b128 v[220:223], v233 offset:49152
	ds_read_b128 v[224:227], v233 offset:53248
	s_waitcnt lgkmcnt(6)
	v_mfma_f32_32x32x16_bf16 v[4:19], v[140:143], v[132:135], v[4:19]
	v_mfma_f32_32x32x16_bf16 v[68:83], v[140:143], v[136:139], v[68:83]
	v_mfma_f32_32x32x16_bf16 v[20:35], v[144:147], v[132:135], v[20:35]
	v_mfma_f32_32x32x16_bf16 v[84:99], v[144:147], v[136:139], v[84:99]
	v_mfma_f32_32x32x16_bf16 v[36:51], v[148:151], v[132:135], v[36:51]
	v_mfma_f32_32x32x16_bf16 v[100:115], v[148:151], v[136:139], v[100:115]
	v_mfma_f32_32x32x16_bf16 v[52:67], v[180:183], v[132:135], v[52:67]
	v_mfma_f32_32x32x16_bf16 v[116:131], v[180:183], v[136:139], v[116:131]
	s_mov_b32 m0, s46
	s_nop 0
	global_load_lds_dwordx4 v178, s[76:77]
	global_load_lds_dwordx4 v179, s[78:79] offset:1024
	global_load_lds_dwordx4 v178, s[80:81] offset:2048
	global_load_lds_dwordx4 v179, s[82:83] offset:3072
	v_add_u32_e32 v178, 0x80, v178
	v_add_u32_e32 v179, 0x80, v179
	ds_read_b128 v[132:135], v230 offset:32768
	ds_read_b128 v[136:139], v230 offset:36864
	ds_read_b128 v[140:143], v234 offset:32768
	ds_read_b128 v[144:147], v234 offset:36864
	ds_read_b128 v[148:151], v234 offset:49152
	ds_read_b128 v[180:183], v234 offset:53248
	s_waitcnt lgkmcnt(6)
	v_mfma_f32_32x32x16_bf16 v[4:19], v[212:215], v[184:187], v[4:19]
	v_mfma_f32_32x32x16_bf16 v[68:83], v[212:215], v[208:211], v[68:83]
	v_mfma_f32_32x32x16_bf16 v[20:35], v[216:219], v[184:187], v[20:35]
	v_mfma_f32_32x32x16_bf16 v[84:99], v[216:219], v[208:211], v[84:99]
	v_mfma_f32_32x32x16_bf16 v[36:51], v[220:223], v[184:187], v[36:51]
	v_mfma_f32_32x32x16_bf16 v[100:115], v[220:223], v[208:211], v[100:115]
	v_mfma_f32_32x32x16_bf16 v[52:67], v[224:227], v[184:187], v[52:67]
	v_mfma_f32_32x32x16_bf16 v[116:131], v[224:227], v[208:211], v[116:131]
	ds_read_b128 v[184:187], v231 offset:32768
	ds_read_b128 v[208:211], v231 offset:36864
	ds_read_b128 v[212:215], v235 offset:32768
	ds_read_b128 v[216:219], v235 offset:36864
	ds_read_b128 v[220:223], v235 offset:49152
	ds_read_b128 v[224:227], v235 offset:53248
	s_waitcnt lgkmcnt(6)
	v_mfma_f32_32x32x16_bf16 v[4:19], v[140:143], v[132:135], v[4:19]
	v_mfma_f32_32x32x16_bf16 v[68:83], v[140:143], v[136:139], v[68:83]
	v_mfma_f32_32x32x16_bf16 v[20:35], v[144:147], v[132:135], v[20:35]
	v_mfma_f32_32x32x16_bf16 v[84:99], v[144:147], v[136:139], v[84:99]
	v_mfma_f32_32x32x16_bf16 v[36:51], v[148:151], v[132:135], v[36:51]
	v_mfma_f32_32x32x16_bf16 v[100:115], v[148:151], v[136:139], v[100:115]
	v_mfma_f32_32x32x16_bf16 v[52:67], v[180:183], v[132:135], v[52:67]
	v_mfma_f32_32x32x16_bf16 v[116:131], v[180:183], v[136:139], v[116:131]
	s_waitcnt lgkmcnt(0)
	v_mfma_f32_32x32x16_bf16 v[4:19], v[212:215], v[184:187], v[4:19]
	v_mfma_f32_32x32x16_bf16 v[68:83], v[212:215], v[208:211], v[68:83]
	v_mfma_f32_32x32x16_bf16 v[20:35], v[216:219], v[184:187], v[20:35]
	v_mfma_f32_32x32x16_bf16 v[84:99], v[216:219], v[208:211], v[84:99]
	v_mfma_f32_32x32x16_bf16 v[36:51], v[220:223], v[184:187], v[36:51]
	v_mfma_f32_32x32x16_bf16 v[100:115], v[220:223], v[208:211], v[100:115]
	v_mfma_f32_32x32x16_bf16 v[52:67], v[224:227], v[184:187], v[52:67]
	v_mfma_f32_32x32x16_bf16 v[116:131], v[224:227], v[208:211], v[116:131]
	s_waitcnt vmcnt(0) lgkmcnt(0)
	s_barrier
; #define MFMA32(a, b, c) __builtin_amdgcn_mfma_f32_32x32x16_bf16((a), (b), (c), 0, 0, 0)
; template <bool SWAP, class Epi>
; DI void gemm_tile(const u16* __restrict__ A, int lda, const u16* __restrict__ Bw, int ldb, int K, char* lds, Epi epi) {
;     ...
;   auto compute = [&](int st) {
;     const char* as = lds + st * GEMM_STAGE;
;     const char* bs = as + 36864;
; #pragma unroll
;     for (int ks = 0; ks < 4; ++ks) {
;       bf16x8 af[2], bfr[2];
; #pragma unroll
;       for (int mi = 0; mi < 2; ++mi) af[mi] = *(const bf16x8*)(as + ((wm * 64 + mi * 32 + r) * 72 + ks * 16 + 8 * h) * 2);
; #pragma unroll
;       for (int ni = 0; ni < 2; ++ni) bfr[ni] = *(const bf16x8*)(bs + ((wn * 64 + ni * 32 + r) * 72 + ks * 16 + 8 * h) * 2);
; #pragma unroll
;       for (int mi = 0; mi < 2; ++mi)
; #pragma unroll
;         for (int ni = 0; ni < 2; ++ni) {
;           if (SWAP) acc[mi][ni] = MFMA32(bfr[ni], af[mi], acc[mi][ni]);
;           else acc[mi][ni] = MFMA32(af[mi], bfr[ni], acc[mi][ni]);
;         }
;     }
;   };
;   gload(0, ra0, rb0);
;   lstore(0, ra0, rb0);
;   gload(1, ra1, rb1);
;   __syncthreads();
;   for (int kt = 0; kt < nk; kt += 2) {
;     if (kt + 2 < nk) gload(kt + 2, ra0, rb0);
;     compute(0);
;     lstore(1, ra1, rb1);
;     __syncthreads();
;     if (kt + 3 < nk) gload(kt + 3, ra1, rb1);
;     compute(1);
;     if (kt + 2 < nk) lstore(0, ra0, rb0);
;     __syncthreads();
	ds_read_b128 v[132:135], v228 offset:0
	ds_read_b128 v[136:139], v228 offset:4096
	ds_read_b128 v[140:143], v232 offset:0
	ds_read_b128 v[144:147], v232 offset:4096
	ds_read_b128 v[148:151], v232 offset:16384
	ds_read_b128 v[180:183], v232 offset:20480
	s_mov_b32 m0, s45
	s_nop 0
	global_load_lds_dwordx4 v178, s[68:69]
	global_load_lds_dwordx4 v179, s[70:71] offset:1024
	global_load_lds_dwordx4 v178, s[72:73] offset:2048
	global_load_lds_dwordx4 v179, s[74:75] offset:3072
	ds_read_b128 v[184:187], v229 offset:0
	ds_read_b128 v[208:211], v229 offset:4096
	ds_read_b128 v[212:215], v233 offset:0
	ds_read_b128 v[216:219], v233 offset:4096
	ds_read_b128 v[220:223], v233 offset:16384
	ds_read_b128 v[224:227], v233 offset:20480
	s_waitcnt lgkmcnt(6)
	v_mfma_f32_32x32x16_bf16 v[4:19], v[140:143], v[132:135], v[4:19]
	v_mfma_f32_32x32x16_bf16 v[68:83], v[140:143], v[136:139], v[68:83]
	v_mfma_f32_32x32x16_bf16 v[20:35], v[144:147], v[132:135], v[20:35]
	v_mfma_f32_32x32x16_bf16 v[84:99], v[144:147], v[136:139], v[84:99]
	v_mfma_f32_32x32x16_bf16 v[36:51], v[148:151], v[132:135], v[36:51]
	v_mfma_f32_32x32x16_bf16 v[100:115], v[148:151], v[136:139], v[100:115]
	v_mfma_f32_32x32x16_bf16 v[52:67], v[180:183], v[132:135], v[52:67]
	v_mfma_f32_32x32x16_bf16 v[116:131], v[180:183], v[136:139], v[116:131]
	s_mov_b32 m0, s47
	s_nop 0
	global_load_lds_dwordx4 v178, s[76:77]
	global_load_lds_dwordx4 v179, s[78:79] offset:1024
	global_load_lds_dwordx4 v178, s[80:81] offset:2048
	global_load_lds_dwordx4 v179, s[82:83] offset:3072
	v_add_u32_e32 v178, 0x80, v178
	v_add_u32_e32 v179, 0x80, v179
	ds_read_b128 v[132:135], v230 offset:0
	ds_read_b128 v[136:139], v230 offset:4096
	ds_read_b128 v[140:143], v234 offset:0
	ds_read_b128 v[144:147], v234 offset:4096
	ds_read_b128 v[148:151], v234 offset:16384
	ds_read_b128 v[180:183], v234 offset:20480
	s_waitcnt lgkmcnt(6)
	v_mfma_f32_32x32x16_bf16 v[4:19], v[212:215], v[184:187], v[4:19]
	v_mfma_f32_32x32x16_bf16 v[68:83], v[212:215], v[208:211], v[68:83]
	v_mfma_f32_32x32x16_bf16 v[20:35], v[216:219], v[184:187], v[20:35]
	v_mfma_f32_32x32x16_bf16 v[84:99], v[216:219], v[208:211], v[84:99]
	v_mfma_f32_32x32x16_bf16 v[36:51], v[220:223], v[184:187], v[36:51]
	v_mfma_f32_32x32x16_bf16 v[100:115], v[220:223], v[208:211], v[100:115]
	v_mfma_f32_32x32x16_bf16 v[52:67], v[224:227], v[184:187], v[52:67]
	v_mfma_f32_32x32x16_bf16 v[116:131], v[224:227], v[208:211], v[116:131]
	ds_read_b128 v[184:187], v231 offset:0
	ds_read_b128 v[208:211], v231 offset:4096
	ds_read_b128 v[212:215], v235 offset:0
	ds_read_b128 v[216:219], v235 offset:4096
	ds_read_b128 v[220:223], v235 offset:16384
	ds_read_b128 v[224:227], v235 offset:20480
	s_waitcnt lgkmcnt(6)
	v_mfma_f32_32x32x16_bf16 v[4:19], v[140:143], v[132:135], v[4:19]
	v_mfma_f32_32x32x16_bf16 v[68:83], v[140:143], v[136:139], v[68:83]
	v_mfma_f32_32x32x16_bf16 v[20:35], v[144:147], v[132:135], v[20:35]
	v_mfma_f32_32x32x16_bf16 v[84:99], v[144:147], v[136:139], v[84:99]
	v_mfma_f32_32x32x16_bf16 v[36:51], v[148:151], v[132:135], v[36:51]
	v_mfma_f32_32x32x16_bf16 v[100:115], v[148:151], v[136:139], v[100:115]
	v_mfma_f32_32x32x16_bf16 v[52:67], v[180:183], v[132:135], v[52:67]
	v_mfma_f32_32x32x16_bf16 v[116:131], v[180:183], v[136:139], v[116:131]
	s_waitcnt lgkmcnt(0)
	v_mfma_f32_32x32x16_bf16 v[4:19], v[212:215], v[184:187], v[4:19]
	v_mfma_f32_32x32x16_bf16 v[68:83], v[212:215], v[208:211], v[68:83]
	v_mfma_f32_32x32x16_bf16 v[20:35], v[216:219], v[184:187], v[20:35]
	v_mfma_f32_32x32x16_bf16 v[84:99], v[216:219], v[208:211], v[84:99]
	v_mfma_f32_32x32x16_bf16 v[36:51], v[220:223], v[184:187], v[36:51]
	v_mfma_f32_32x32x16_bf16 v[100:115], v[220:223], v[208:211], v[100:115]
	v_mfma_f32_32x32x16_bf16 v[52:67], v[224:227], v[184:187], v[52:67]
	v_mfma_f32_32x32x16_bf16 v[116:131], v[224:227], v[208:211], v[116:131]
	s_waitcnt vmcnt(0) lgkmcnt(0)
	s_barrier
	ds_read_b128 v[132:135], v228 offset:32768
	ds_read_b128 v[136:139], v228 offset:36864
	ds_read_b128 v[140:143], v232 offset:32768
	ds_read_b128 v[144:147], v232 offset:36864
	ds_read_b128 v[148:151], v232 offset:49152
	ds_read_b128 v[180:183], v232 offset:53248
	s_mov_b32 m0, s44
	s_nop 0
	global_load_lds_dwordx4 v178, s[68:69]
	global_load_lds_dwordx4 v179, s[70:71] offset:1024
	global_load_lds_dwordx4 v178, s[72:73] offset:2048
	global_load_lds_dwordx4 v179, s[74:75] offset:3072
	ds_read_b128 v[184:187], v229 offset:32768
	ds_read_b128 v[208:211], v229 offset:36864
	ds_read_b128 v[212:215], v233 offset:32768
	ds_read_b128 v[216:219], v233 offset:36864
	ds_read_b128 v[220:223], v233 offset:49152
	ds_read_b128 v[224:227], v233 offset:53248
	s_waitcnt lgkmcnt(6)
	v_mfma_f32_32x32x16_bf16 v[4:19], v[140:143], v[132:135], v[4:19]
	v_mfma_f32_32x32x16_bf16 v[68:83], v[140:143], v[136:139], v[68:83]
	v_mfma_f32_32x32x16_bf16 v[20:35], v[144:147], v[132:135], v[20:35]
	v_mfma_f32_32x32x16_bf16 v[84:99], v[144:147], v[136:139], v[84:99]
	v_mfma_f32_32x32x16_bf16 v[36:51], v[148:151], v[132:135], v[36:51]
	v_mfma_f32_32x32x16_bf16 v[100:115], v[148:151], v[136:139], v[100:115]
	v_mfma_f32_32x32x16_bf16 v[52:67], v[180:183], v[132:135], v[52:67]
	v_mfma_f32_32x32x16_bf16 v[116:131], v[180:183], v[136:139], v[116:131]
	s_mov_b32 m0, s46
	s_nop 0
	global_load_lds_dwordx4 v178, s[76:77]
	global_load_lds_dwordx4 v179, s[78:79] offset:1024
	global_load_lds_dwordx4 v178, s[80:81] offset:2048
	global_load_lds_dwordx4 v179, s[82:83] offset:3072
	v_add_u32_e32 v178, 0x80, v178
	v_add_u32_e32 v179, 0x80, v179
	ds_read_b128 v[132:135], v230 offset:32768
	ds_read_b128 v[136:139], v230 offset:36864
	ds_read_b128 v[140:143], v234 offset:32768
	ds_read_b128 v[144:147], v234 offset:36864
	ds_read_b128 v[148:151], v234 offset:49152
	ds_read_b128 v[180:183], v234 offset:53248
	s_waitcnt lgkmcnt(6)
; #define MFMA32(a, b, c) __builtin_amdgcn_mfma_f32_32x32x16_bf16((a), (b), (c), 0, 0, 0)
; template <bool SWAP, class Epi>
; DI void gemm_tile(const u16* __restrict__ A, int lda, const u16* __restrict__ Bw, int ldb, int K, char* lds, Epi epi) {
;     ...
;   auto compute = [&](int st) {
;     const char* as = lds + st * GEMM_STAGE;
;     const char* bs = as + 36864;
; #pragma unroll
;     for (int ks = 0; ks < 4; ++ks) {
;       bf16x8 af[2], bfr[2];
; #pragma unroll
;       for (int mi = 0; mi < 2; ++mi) af[mi] = *(const bf16x8*)(as + ((wm * 64 + mi * 32 + r) * 72 + ks * 16 + 8 * h) * 2);
; #pragma unroll
;       for (int ni = 0; ni < 2; ++ni) bfr[ni] = *(const bf16x8*)(bs + ((wn * 64 + ni * 32 + r) * 72 + ks * 16 + 8 * h) * 2);
; #pragma unroll
;       for (int mi = 0; mi < 2; ++mi)
; #pragma unroll
;         for (int ni = 0; ni < 2; ++ni) {
;           if (SWAP) acc[mi][ni] = MFMA32(bfr[ni], af[mi], acc[mi][ni]);
;           else acc[mi][ni] = MFMA32(af[mi], bfr[ni], acc[mi][ni]);
;         }
;     }
;   };
;   gload(0, ra0, rb0);
;   lstore(0, ra0, rb0);
;   gload(1, ra1, rb1);
;   __syncthreads();
;   for (int kt = 0; kt < nk; kt += 2) {
;     if (kt + 2 < nk) gload(kt + 2, ra0, rb0);
;     compute(0);
;     lstore(1, ra1, rb1);
;     __syncthreads();
;     if (kt + 3 < nk) gload(kt + 3, ra1, rb1);
;     compute(1);
;     if (kt + 2 < nk) lstore(0, ra0, rb0);
;     __syncthreads();
	v_mfma_f32_32x32x16_bf16 v[4:19], v[212:215], v[184:187], v[4:19]
	v_mfma_f32_32x32x16_bf16 v[68:83], v[212:215], v[208:211], v[68:83]
	v_mfma_f32_32x32x16_bf16 v[20:35], v[216:219], v[184:187], v[20:35]
	v_mfma_f32_32x32x16_bf16 v[84:99], v[216:219], v[208:211], v[84:99]
	v_mfma_f32_32x32x16_bf16 v[36:51], v[220:223], v[184:187], v[36:51]
	v_mfma_f32_32x32x16_bf16 v[100:115], v[220:223], v[208:211], v[100:115]
	v_mfma_f32_32x32x16_bf16 v[52:67], v[224:227], v[184:187], v[52:67]
	v_mfma_f32_32x32x16_bf16 v[116:131], v[224:227], v[208:211], v[116:131]
	ds_read_b128 v[184:187], v231 offset:32768
	ds_read_b128 v[208:211], v231 offset:36864
	ds_read_b128 v[212:215], v235 offset:32768
	ds_read_b128 v[216:219], v235 offset:36864
	ds_read_b128 v[220:223], v235 offset:49152
	ds_read_b128 v[224:227], v235 offset:53248
	s_waitcnt lgkmcnt(6)
	v_mfma_f32_32x32x16_bf16 v[4:19], v[140:143], v[132:135], v[4:19]
	v_mfma_f32_32x32x16_bf16 v[68:83], v[140:143], v[136:139], v[68:83]
	v_mfma_f32_32x32x16_bf16 v[20:35], v[144:147], v[132:135], v[20:35]
	v_mfma_f32_32x32x16_bf16 v[84:99], v[144:147], v[136:139], v[84:99]
	v_mfma_f32_32x32x16_bf16 v[36:51], v[148:151], v[132:135], v[36:51]
	v_mfma_f32_32x32x16_bf16 v[100:115], v[148:151], v[136:139], v[100:115]
	v_mfma_f32_32x32x16_bf16 v[52:67], v[180:183], v[132:135], v[52:67]
	v_mfma_f32_32x32x16_bf16 v[116:131], v[180:183], v[136:139], v[116:131]
	s_waitcnt lgkmcnt(0)
	v_mfma_f32_32x32x16_bf16 v[4:19], v[212:215], v[184:187], v[4:19]
	v_mfma_f32_32x32x16_bf16 v[68:83], v[212:215], v[208:211], v[68:83]
	v_mfma_f32_32x32x16_bf16 v[20:35], v[216:219], v[184:187], v[20:35]
	v_mfma_f32_32x32x16_bf16 v[84:99], v[216:219], v[208:211], v[84:99]
	v_mfma_f32_32x32x16_bf16 v[36:51], v[220:223], v[184:187], v[36:51]
	v_mfma_f32_32x32x16_bf16 v[100:115], v[220:223], v[208:211], v[100:115]
	v_mfma_f32_32x32x16_bf16 v[52:67], v[224:227], v[184:187], v[52:67]
	v_mfma_f32_32x32x16_bf16 v[116:131], v[224:227], v[208:211], v[116:131]
	s_waitcnt vmcnt(0) lgkmcnt(0)
	s_barrier
	ds_read_b128 v[132:135], v228 offset:0
	ds_read_b128 v[136:139], v228 offset:4096
	ds_read_b128 v[140:143], v232 offset:0
	ds_read_b128 v[144:147], v232 offset:4096
	ds_read_b128 v[148:151], v232 offset:16384
	ds_read_b128 v[180:183], v232 offset:20480
	s_mov_b32 m0, s45
	s_nop 0
	global_load_lds_dwordx4 v178, s[68:69]
	global_load_lds_dwordx4 v179, s[70:71] offset:1024
	global_load_lds_dwordx4 v178, s[72:73] offset:2048
	global_load_lds_dwordx4 v179, s[74:75] offset:3072
	ds_read_b128 v[184:187], v229 offset:0
	ds_read_b128 v[208:211], v229 offset:4096
	ds_read_b128 v[212:215], v233 offset:0
	ds_read_b128 v[216:219], v233 offset:4096
	ds_read_b128 v[220:223], v233 offset:16384
	ds_read_b128 v[224:227], v233 offset:20480
	s_waitcnt lgkmcnt(6)
	v_mfma_f32_32x32x16_bf16 v[4:19], v[140:143], v[132:135], v[4:19]
	v_mfma_f32_32x32x16_bf16 v[68:83], v[140:143], v[136:139], v[68:83]
	v_mfma_f32_32x32x16_bf16 v[20:35], v[144:147], v[132:135], v[20:35]
	v_mfma_f32_32x32x16_bf16 v[84:99], v[144:147], v[136:139], v[84:99]
	v_mfma_f32_32x32x16_bf16 v[36:51], v[148:151], v[132:135], v[36:51]
	v_mfma_f32_32x32x16_bf16 v[100:115], v[148:151], v[136:139], v[100:115]
	v_mfma_f32_32x32x16_bf16 v[52:67], v[180:183], v[132:135], v[52:67]
	v_mfma_f32_32x32x16_bf16 v[116:131], v[180:183], v[136:139], v[116:131]
	s_mov_b32 m0, s47
	s_nop 0
	global_load_lds_dwordx4 v178, s[76:77]
	global_load_lds_dwordx4 v179, s[78:79] offset:1024
	global_load_lds_dwordx4 v178, s[80:81] offset:2048
	global_load_lds_dwordx4 v179, s[82:83] offset:3072
	v_add_u32_e32 v178, 0x80, v178
	v_add_u32_e32 v179, 0x80, v179
	ds_read_b128 v[132:135], v230 offset:0
	ds_read_b128 v[136:139], v230 offset:4096
	ds_read_b128 v[140:143], v234 offset:0
	ds_read_b128 v[144:147], v234 offset:4096
	ds_read_b128 v[148:151], v234 offset:16384
	ds_read_b128 v[180:183], v234 offset:20480
	s_waitcnt lgkmcnt(6)
	v_mfma_f32_32x32x16_bf16 v[4:19], v[212:215], v[184:187], v[4:19]
	v_mfma_f32_32x32x16_bf16 v[68:83], v[212:215], v[208:211], v[68:83]
	v_mfma_f32_32x32x16_bf16 v[20:35], v[216:219], v[184:187], v[20:35]
	v_mfma_f32_32x32x16_bf16 v[84:99], v[216:219], v[208:211], v[84:99]
	v_mfma_f32_32x32x16_bf16 v[36:51], v[220:223], v[184:187], v[36:51]
	v_mfma_f32_32x32x16_bf16 v[100:115], v[220:223], v[208:211], v[100:115]
	v_mfma_f32_32x32x16_bf16 v[52:67], v[224:227], v[184:187], v[52:67]
	v_mfma_f32_32x32x16_bf16 v[116:131], v[224:227], v[208:211], v[116:131]
	ds_read_b128 v[184:187], v231 offset:0
	ds_read_b128 v[208:211], v231 offset:4096
	ds_read_b128 v[212:215], v235 offset:0
	ds_read_b128 v[216:219], v235 offset:4096
	ds_read_b128 v[220:223], v235 offset:16384
	ds_read_b128 v[224:227], v235 offset:20480
	s_waitcnt lgkmcnt(6)
	v_mfma_f32_32x32x16_bf16 v[4:19], v[140:143], v[132:135], v[4:19]
	v_mfma_f32_32x32x16_bf16 v[68:83], v[140:143], v[136:139], v[68:83]
	v_mfma_f32_32x32x16_bf16 v[20:35], v[144:147], v[132:135], v[20:35]
	v_mfma_f32_32x32x16_bf16 v[84:99], v[144:147], v[136:139], v[84:99]
	v_mfma_f32_32x32x16_bf16 v[36:51], v[148:151], v[132:135], v[36:51]
	v_mfma_f32_32x32x16_bf16 v[100:115], v[148:151], v[136:139], v[100:115]
	v_mfma_f32_32x32x16_bf16 v[52:67], v[180:183], v[132:135], v[52:67]
	v_mfma_f32_32x32x16_bf16 v[116:131], v[180:183], v[136:139], v[116:131]
	s_waitcnt lgkmcnt(0)
	v_mfma_f32_32x32x16_bf16 v[4:19], v[212:215], v[184:187], v[4:19]
	v_mfma_f32_32x32x16_bf16 v[68:83], v[212:215], v[208:211], v[68:83]
	v_mfma_f32_32x32x16_bf16 v[20:35], v[216:219], v[184:187], v[20:35]
	v_mfma_f32_32x32x16_bf16 v[84:99], v[216:219], v[208:211], v[84:99]
	v_mfma_f32_32x32x16_bf16 v[36:51], v[220:223], v[184:187], v[36:51]
	v_mfma_f32_32x32x16_bf16 v[100:115], v[220:223], v[208:211], v[100:115]
	v_mfma_f32_32x32x16_bf16 v[52:67], v[224:227], v[184:187], v[52:67]
	v_mfma_f32_32x32x16_bf16 v[116:131], v[224:227], v[208:211], v[116:131]
	s_waitcnt vmcnt(0) lgkmcnt(0)
	s_barrier
; #define MFMA32(a, b, c) __builtin_amdgcn_mfma_f32_32x32x16_bf16((a), (b), (c), 0, 0, 0)
; template <bool SWAP, class Epi>
; DI void gemm_tile(const u16* __restrict__ A, int lda, const u16* __restrict__ Bw, int ldb, int K, char* lds, Epi epi) {
;     ...
;   auto compute = [&](int st) {
;     const char* as = lds + st * GEMM_STAGE;
;     const char* bs = as + 36864;
; #pragma unroll
;     for (int ks = 0; ks < 4; ++ks) {
;       bf16x8 af[2], bfr[2];
; #pragma unroll
;       for (int mi = 0; mi < 2; ++mi) af[mi] = *(const bf16x8*)(as + ((wm * 64 + mi * 32 + r) * 72 + ks * 16 + 8 * h) * 2);
; #pragma unroll
;       for (int ni = 0; ni < 2; ++ni) bfr[ni] = *(const bf16x8*)(bs + ((wn * 64 + ni * 32 + r) * 72 + ks * 16 + 8 * h) * 2);
; #pragma unroll
;       for (int mi = 0; mi < 2; ++mi)
; #pragma unroll
;         for (int ni = 0; ni < 2; ++ni) {
;           if (SWAP) acc[mi][ni] = MFMA32(bfr[ni], af[mi], acc[mi][ni]);
;           else acc[mi][ni] = MFMA32(af[mi], bfr[ni], acc[mi][ni]);
;         }
;     }
;   };
;   gload(0, ra0, rb0);
;   lstore(0, ra0, rb0);
;   gload(1, ra1, rb1);
;   __syncthreads();
;   for (int kt = 0; kt < nk; kt += 2) {
;     if (kt + 2 < nk) gload(kt + 2, ra0, rb0);
;     compute(0);
;     lstore(1, ra1, rb1);
;     __syncthreads();
;     if (kt + 3 < nk) gload(kt + 3, ra1, rb1);
;     compute(1);
;     if (kt + 2 < nk) lstore(0, ra0, rb0);
;     __syncthreads();
	ds_read_b128 v[132:135], v228 offset:32768
	ds_read_b128 v[136:139], v228 offset:36864
	ds_read_b128 v[140:143], v232 offset:32768
	ds_read_b128 v[144:147], v232 offset:36864
	ds_read_b128 v[148:151], v232 offset:49152
	ds_read_b128 v[180:183], v232 offset:53248
	s_mov_b32 m0, s44
	s_nop 0
	global_load_lds_dwordx4 v178, s[68:69]
	global_load_lds_dwordx4 v179, s[70:71] offset:1024
	global_load_lds_dwordx4 v178, s[72:73] offset:2048
	global_load_lds_dwordx4 v179, s[74:75] offset:3072
	ds_read_b128 v[184:187], v229 offset:32768
	ds_read_b128 v[208:211], v229 offset:36864
	ds_read_b128 v[212:215], v233 offset:32768
	ds_read_b128 v[216:219], v233 offset:36864
	ds_read_b128 v[220:223], v233 offset:49152
	ds_read_b128 v[224:227], v233 offset:53248
	s_waitcnt lgkmcnt(6)
	v_mfma_f32_32x32x16_bf16 v[4:19], v[140:143], v[132:135], v[4:19]
	v_mfma_f32_32x32x16_bf16 v[68:83], v[140:143], v[136:139], v[68:83]
	v_mfma_f32_32x32x16_bf16 v[20:35], v[144:147], v[132:135], v[20:35]
	v_mfma_f32_32x32x16_bf16 v[84:99], v[144:147], v[136:139], v[84:99]
	v_mfma_f32_32x32x16_bf16 v[36:51], v[148:151], v[132:135], v[36:51]
	v_mfma_f32_32x32x16_bf16 v[100:115], v[148:151], v[136:139], v[100:115]
	v_mfma_f32_32x32x16_bf16 v[52:67], v[180:183], v[132:135], v[52:67]
	v_mfma_f32_32x32x16_bf16 v[116:131], v[180:183], v[136:139], v[116:131]
	s_mov_b32 m0, s46
	s_nop 0
	global_load_lds_dwordx4 v178, s[76:77]
	global_load_lds_dwordx4 v179, s[78:79] offset:1024
	global_load_lds_dwordx4 v178, s[80:81] offset:2048
	global_load_lds_dwordx4 v179, s[82:83] offset:3072
	v_add_u32_e32 v178, 0x80, v178
	v_add_u32_e32 v179, 0x80, v179
	ds_read_b128 v[132:135], v230 offset:32768
	ds_read_b128 v[136:139], v230 offset:36864
	ds_read_b128 v[140:143], v234 offset:32768
	ds_read_b128 v[144:147], v234 offset:36864
	ds_read_b128 v[148:151], v234 offset:49152
	ds_read_b128 v[180:183], v234 offset:53248
	s_waitcnt lgkmcnt(6)
	v_mfma_f32_32x32x16_bf16 v[4:19], v[212:215], v[184:187], v[4:19]
	v_mfma_f32_32x32x16_bf16 v[68:83], v[212:215], v[208:211], v[68:83]
	v_mfma_f32_32x32x16_bf16 v[20:35], v[216:219], v[184:187], v[20:35]
	v_mfma_f32_32x32x16_bf16 v[84:99], v[216:219], v[208:211], v[84:99]
	v_mfma_f32_32x32x16_bf16 v[36:51], v[220:223], v[184:187], v[36:51]
	v_mfma_f32_32x32x16_bf16 v[100:115], v[220:223], v[208:211], v[100:115]
	v_mfma_f32_32x32x16_bf16 v[52:67], v[224:227], v[184:187], v[52:67]
	v_mfma_f32_32x32x16_bf16 v[116:131], v[224:227], v[208:211], v[116:131]
	ds_read_b128 v[184:187], v231 offset:32768
	ds_read_b128 v[208:211], v231 offset:36864
	ds_read_b128 v[212:215], v235 offset:32768
	ds_read_b128 v[216:219], v235 offset:36864
	ds_read_b128 v[220:223], v235 offset:49152
	ds_read_b128 v[224:227], v235 offset:53248
	s_waitcnt lgkmcnt(6)
	v_mfma_f32_32x32x16_bf16 v[4:19], v[140:143], v[132:135], v[4:19]
	v_mfma_f32_32x32x16_bf16 v[68:83], v[140:143], v[136:139], v[68:83]
	v_mfma_f32_32x32x16_bf16 v[20:35], v[144:147], v[132:135], v[20:35]
	v_mfma_f32_32x32x16_bf16 v[84:99], v[144:147], v[136:139], v[84:99]
	v_mfma_f32_32x32x16_bf16 v[36:51], v[148:151], v[132:135], v[36:51]
	v_mfma_f32_32x32x16_bf16 v[100:115], v[148:151], v[136:139], v[100:115]
	v_mfma_f32_32x32x16_bf16 v[52:67], v[180:183], v[132:135], v[52:67]
	v_mfma_f32_32x32x16_bf16 v[116:131], v[180:183], v[136:139], v[116:131]
	s_waitcnt lgkmcnt(0)
	v_mfma_f32_32x32x16_bf16 v[4:19], v[212:215], v[184:187], v[4:19]
	v_mfma_f32_32x32x16_bf16 v[68:83], v[212:215], v[208:211], v[68:83]
	v_mfma_f32_32x32x16_bf16 v[20:35], v[216:219], v[184:187], v[20:35]
	v_mfma_f32_32x32x16_bf16 v[84:99], v[216:219], v[208:211], v[84:99]
	v_mfma_f32_32x32x16_bf16 v[36:51], v[220:223], v[184:187], v[36:51]
	v_mfma_f32_32x32x16_bf16 v[100:115], v[220:223], v[208:211], v[100:115]
	v_mfma_f32_32x32x16_bf16 v[52:67], v[224:227], v[184:187], v[52:67]
	v_mfma_f32_32x32x16_bf16 v[116:131], v[224:227], v[208:211], v[116:131]
	s_waitcnt vmcnt(0) lgkmcnt(0)
	s_barrier
	ds_read_b128 v[132:135], v228 offset:0
	ds_read_b128 v[136:139], v228 offset:4096
	ds_read_b128 v[140:143], v232 offset:0
	ds_read_b128 v[144:147], v232 offset:4096
	ds_read_b128 v[148:151], v232 offset:16384
	ds_read_b128 v[180:183], v232 offset:20480
	s_mov_b32 m0, s45
	s_nop 0
	global_load_lds_dwordx4 v178, s[68:69]
	global_load_lds_dwordx4 v179, s[70:71] offset:1024
	global_load_lds_dwordx4 v178, s[72:73] offset:2048
	global_load_lds_dwordx4 v179, s[74:75] offset:3072
	ds_read_b128 v[184:187], v229 offset:0
	ds_read_b128 v[208:211], v229 offset:4096
	ds_read_b128 v[212:215], v233 offset:0
	ds_read_b128 v[216:219], v233 offset:4096
	ds_read_b128 v[220:223], v233 offset:16384
	ds_read_b128 v[224:227], v233 offset:20480
	s_waitcnt lgkmcnt(6)
	v_mfma_f32_32x32x16_bf16 v[4:19], v[140:143], v[132:135], v[4:19]
	v_mfma_f32_32x32x16_bf16 v[68:83], v[140:143], v[136:139], v[68:83]
	v_mfma_f32_32x32x16_bf16 v[20:35], v[144:147], v[132:135], v[20:35]
	v_mfma_f32_32x32x16_bf16 v[84:99], v[144:147], v[136:139], v[84:99]
	v_mfma_f32_32x32x16_bf16 v[36:51], v[148:151], v[132:135], v[36:51]
	v_mfma_f32_32x32x16_bf16 v[100:115], v[148:151], v[136:139], v[100:115]
	v_mfma_f32_32x32x16_bf16 v[52:67], v[180:183], v[132:135], v[52:67]
	v_mfma_f32_32x32x16_bf16 v[116:131], v[180:183], v[136:139], v[116:131]
	s_mov_b32 m0, s47
	s_nop 0
	global_load_lds_dwordx4 v178, s[76:77]
	global_load_lds_dwordx4 v179, s[78:79] offset:1024
	global_load_lds_dwordx4 v178, s[80:81] offset:2048
	global_load_lds_dwordx4 v179, s[82:83] offset:3072
	v_add_u32_e32 v178, 0x80, v178
	v_add_u32_e32 v179, 0x80, v179
	ds_read_b128 v[132:135], v230 offset:0
	ds_read_b128 v[136:139], v230 offset:4096
	ds_read_b128 v[140:143], v234 offset:0
	ds_read_b128 v[144:147], v234 offset:4096
	ds_read_b128 v[148:151], v234 offset:16384
	ds_read_b128 v[180:183], v234 offset:20480
	s_waitcnt lgkmcnt(6)
; #define MFMA32(a, b, c) __builtin_amdgcn_mfma_f32_32x32x16_bf16((a), (b), (c), 0, 0, 0)
; template <bool SWAP, class Epi>
; DI void gemm_tile(const u16* __restrict__ A, int lda, const u16* __restrict__ Bw, int ldb, int K, char* lds, Epi epi) {
;     ...
;   auto compute = [&](int st) {
;     const char* as = lds + st * GEMM_STAGE;
;     const char* bs = as + 36864;
; #pragma unroll
;     for (int ks = 0; ks < 4; ++ks) {
;       bf16x8 af[2], bfr[2];
; #pragma unroll
;       for (int mi = 0; mi < 2; ++mi) af[mi] = *(const bf16x8*)(as + ((wm * 64 + mi * 32 + r) * 72 + ks * 16 + 8 * h) * 2);
; #pragma unroll
;       for (int ni = 0; ni < 2; ++ni) bfr[ni] = *(const bf16x8*)(bs + ((wn * 64 + ni * 32 + r) * 72 + ks * 16 + 8 * h) * 2);
; #pragma unroll
;       for (int mi = 0; mi < 2; ++mi)
; #pragma unroll
;         for (int ni = 0; ni < 2; ++ni) {
;           if (SWAP) acc[mi][ni] = MFMA32(bfr[ni], af[mi], acc[mi][ni]);
;           else acc[mi][ni] = MFMA32(af[mi], bfr[ni], acc[mi][ni]);
;         }
;     }
;   };
;   gload(0, ra0, rb0);
;   lstore(0, ra0, rb0);
;   gload(1, ra1, rb1);
;   __syncthreads();
;   for (int kt = 0; kt < nk; kt += 2) {
;     if (kt + 2 < nk) gload(kt + 2, ra0, rb0);
;     compute(0);
;     lstore(1, ra1, rb1);
;     __syncthreads();
;     if (kt + 3 < nk) gload(kt + 3, ra1, rb1);
;     compute(1);
;     if (kt + 2 < nk) lstore(0, ra0, rb0);
;     __syncthreads();
	v_mfma_f32_32x32x16_bf16 v[4:19], v[212:215], v[184:187], v[4:19]
	v_mfma_f32_32x32x16_bf16 v[68:83], v[212:215], v[208:211], v[68:83]
	v_mfma_f32_32x32x16_bf16 v[20:35], v[216:219], v[184:187], v[20:35]
	v_mfma_f32_32x32x16_bf16 v[84:99], v[216:219], v[208:211], v[84:99]
	v_mfma_f32_32x32x16_bf16 v[36:51], v[220:223], v[184:187], v[36:51]
	v_mfma_f32_32x32x16_bf16 v[100:115], v[220:223], v[208:211], v[100:115]
	v_mfma_f32_32x32x16_bf16 v[52:67], v[224:227], v[184:187], v[52:67]
	v_mfma_f32_32x32x16_bf16 v[116:131], v[224:227], v[208:211], v[116:131]
	ds_read_b128 v[184:187], v231 offset:0
	ds_read_b128 v[208:211], v231 offset:4096
	ds_read_b128 v[212:215], v235 offset:0
	ds_read_b128 v[216:219], v235 offset:4096
	ds_read_b128 v[220:223], v235 offset:16384
	ds_read_b128 v[224:227], v235 offset:20480
	s_waitcnt lgkmcnt(6)
	v_mfma_f32_32x32x16_bf16 v[4:19], v[140:143], v[132:135], v[4:19]
	v_mfma_f32_32x32x16_bf16 v[68:83], v[140:143], v[136:139], v[68:83]
	v_mfma_f32_32x32x16_bf16 v[20:35], v[144:147], v[132:135], v[20:35]
	v_mfma_f32_32x32x16_bf16 v[84:99], v[144:147], v[136:139], v[84:99]
	v_mfma_f32_32x32x16_bf16 v[36:51], v[148:151], v[132:135], v[36:51]
	v_mfma_f32_32x32x16_bf16 v[100:115], v[148:151], v[136:139], v[100:115]
	v_mfma_f32_32x32x16_bf16 v[52:67], v[180:183], v[132:135], v[52:67]
	v_mfma_f32_32x32x16_bf16 v[116:131], v[180:183], v[136:139], v[116:131]
	s_waitcnt lgkmcnt(0)
	v_mfma_f32_32x32x16_bf16 v[4:19], v[212:215], v[184:187], v[4:19]
	v_mfma_f32_32x32x16_bf16 v[68:83], v[212:215], v[208:211], v[68:83]
	v_mfma_f32_32x32x16_bf16 v[20:35], v[216:219], v[184:187], v[20:35]
	v_mfma_f32_32x32x16_bf16 v[84:99], v[216:219], v[208:211], v[84:99]
	v_mfma_f32_32x32x16_bf16 v[36:51], v[220:223], v[184:187], v[36:51]
	v_mfma_f32_32x32x16_bf16 v[100:115], v[220:223], v[208:211], v[100:115]
	v_mfma_f32_32x32x16_bf16 v[52:67], v[224:227], v[184:187], v[52:67]
	v_mfma_f32_32x32x16_bf16 v[116:131], v[224:227], v[208:211], v[116:131]
	s_waitcnt vmcnt(0) lgkmcnt(0)
	s_barrier
	ds_read_b128 v[132:135], v228 offset:32768
	ds_read_b128 v[136:139], v228 offset:36864
	ds_read_b128 v[140:143], v232 offset:32768
	ds_read_b128 v[144:147], v232 offset:36864
	ds_read_b128 v[148:151], v232 offset:49152
	ds_read_b128 v[180:183], v232 offset:53248
	s_mov_b32 m0, s44
	s_nop 0
	global_load_lds_dwordx4 v178, s[68:69]
	global_load_lds_dwordx4 v179, s[70:71] offset:1024
	global_load_lds_dwordx4 v178, s[72:73] offset:2048
	global_load_lds_dwordx4 v179, s[74:75] offset:3072
	ds_read_b128 v[184:187], v229 offset:32768
	ds_read_b128 v[208:211], v229 offset:36864
	ds_read_b128 v[212:215], v233 offset:32768
	ds_read_b128 v[216:219], v233 offset:36864
	ds_read_b128 v[220:223], v233 offset:49152
	ds_read_b128 v[224:227], v233 offset:53248
	s_waitcnt lgkmcnt(6)
	v_mfma_f32_32x32x16_bf16 v[4:19], v[140:143], v[132:135], v[4:19]
	v_mfma_f32_32x32x16_bf16 v[68:83], v[140:143], v[136:139], v[68:83]
	v_mfma_f32_32x32x16_bf16 v[20:35], v[144:147], v[132:135], v[20:35]
	v_mfma_f32_32x32x16_bf16 v[84:99], v[144:147], v[136:139], v[84:99]
	v_mfma_f32_32x32x16_bf16 v[36:51], v[148:151], v[132:135], v[36:51]
	v_mfma_f32_32x32x16_bf16 v[100:115], v[148:151], v[136:139], v[100:115]
	v_mfma_f32_32x32x16_bf16 v[52:67], v[180:183], v[132:135], v[52:67]
	v_mfma_f32_32x32x16_bf16 v[116:131], v[180:183], v[136:139], v[116:131]
	s_mov_b32 m0, s46
	s_nop 0
	global_load_lds_dwordx4 v178, s[76:77]
	global_load_lds_dwordx4 v179, s[78:79] offset:1024
	global_load_lds_dwordx4 v178, s[80:81] offset:2048
	global_load_lds_dwordx4 v179, s[82:83] offset:3072
	v_add_u32_e32 v178, 0x80, v178
	v_add_u32_e32 v179, 0x80, v179
	ds_read_b128 v[132:135], v230 offset:32768
	ds_read_b128 v[136:139], v230 offset:36864
	ds_read_b128 v[140:143], v234 offset:32768
	ds_read_b128 v[144:147], v234 offset:36864
	ds_read_b128 v[148:151], v234 offset:49152
	ds_read_b128 v[180:183], v234 offset:53248
	s_waitcnt lgkmcnt(6)
	v_mfma_f32_32x32x16_bf16 v[4:19], v[212:215], v[184:187], v[4:19]
	v_mfma_f32_32x32x16_bf16 v[68:83], v[212:215], v[208:211], v[68:83]
	v_mfma_f32_32x32x16_bf16 v[20:35], v[216:219], v[184:187], v[20:35]
	v_mfma_f32_32x32x16_bf16 v[84:99], v[216:219], v[208:211], v[84:99]
	v_mfma_f32_32x32x16_bf16 v[36:51], v[220:223], v[184:187], v[36:51]
	v_mfma_f32_32x32x16_bf16 v[100:115], v[220:223], v[208:211], v[100:115]
	v_mfma_f32_32x32x16_bf16 v[52:67], v[224:227], v[184:187], v[52:67]
	v_mfma_f32_32x32x16_bf16 v[116:131], v[224:227], v[208:211], v[116:131]
	ds_read_b128 v[184:187], v231 offset:32768
	ds_read_b128 v[208:211], v231 offset:36864
	ds_read_b128 v[212:215], v235 offset:32768
	ds_read_b128 v[216:219], v235 offset:36864
	ds_read_b128 v[220:223], v235 offset:49152
	ds_read_b128 v[224:227], v235 offset:53248
	s_waitcnt lgkmcnt(6)
	v_mfma_f32_32x32x16_bf16 v[4:19], v[140:143], v[132:135], v[4:19]
	v_mfma_f32_32x32x16_bf16 v[68:83], v[140:143], v[136:139], v[68:83]
	v_mfma_f32_32x32x16_bf16 v[20:35], v[144:147], v[132:135], v[20:35]
	v_mfma_f32_32x32x16_bf16 v[84:99], v[144:147], v[136:139], v[84:99]
	v_mfma_f32_32x32x16_bf16 v[36:51], v[148:151], v[132:135], v[36:51]
	v_mfma_f32_32x32x16_bf16 v[100:115], v[148:151], v[136:139], v[100:115]
	v_mfma_f32_32x32x16_bf16 v[52:67], v[180:183], v[132:135], v[52:67]
	v_mfma_f32_32x32x16_bf16 v[116:131], v[180:183], v[136:139], v[116:131]
	s_waitcnt lgkmcnt(0)
	v_mfma_f32_32x32x16_bf16 v[4:19], v[212:215], v[184:187], v[4:19]
	v_mfma_f32_32x32x16_bf16 v[68:83], v[212:215], v[208:211], v[68:83]
	v_mfma_f32_32x32x16_bf16 v[20:35], v[216:219], v[184:187], v[20:35]
	v_mfma_f32_32x32x16_bf16 v[84:99], v[216:219], v[208:211], v[84:99]
	v_mfma_f32_32x32x16_bf16 v[36:51], v[220:223], v[184:187], v[36:51]
	v_mfma_f32_32x32x16_bf16 v[100:115], v[220:223], v[208:211], v[100:115]
	v_mfma_f32_32x32x16_bf16 v[52:67], v[224:227], v[184:187], v[52:67]
	v_mfma_f32_32x32x16_bf16 v[116:131], v[224:227], v[208:211], v[116:131]
	s_waitcnt vmcnt(0) lgkmcnt(0)
	s_barrier
; #define MFMA32(a, b, c) __builtin_amdgcn_mfma_f32_32x32x16_bf16((a), (b), (c), 0, 0, 0)
; template <bool SWAP, class Epi>
; DI void gemm_tile(const u16* __restrict__ A, int lda, const u16* __restrict__ Bw, int ldb, int K, char* lds, Epi epi) {
;     ...
;   auto compute = [&](int st) {
;     const char* as = lds + st * GEMM_STAGE;
;     const char* bs = as + 36864;
; #pragma unroll
;     for (int ks = 0; ks < 4; ++ks) {
;       bf16x8 af[2], bfr[2];
; #pragma unroll
;       for (int mi = 0; mi < 2; ++mi) af[mi] = *(const bf16x8*)(as + ((wm * 64 + mi * 32 + r) * 72 + ks * 16 + 8 * h) * 2);
; #pragma unroll
;       for (int ni = 0; ni < 2; ++ni) bfr[ni] = *(const bf16x8*)(bs + ((wn * 64 + ni * 32 + r) * 72 + ks * 16 + 8 * h) * 2);
; #pragma unroll
;       for (int mi = 0; mi < 2; ++mi)
; #pragma unroll
;         for (int ni = 0; ni < 2; ++ni) {
;           if (SWAP) acc[mi][ni] = MFMA32(bfr[ni], af[mi], acc[mi][ni]);
;           else acc[mi][ni] = MFMA32(af[mi], bfr[ni], acc[mi][ni]);
;         }
;     }
;   };
;   gload(0, ra0, rb0);
;   lstore(0, ra0, rb0);
;   gload(1, ra1, rb1);
;   __syncthreads();
;   for (int kt = 0; kt < nk; kt += 2) {
;     if (kt + 2 < nk) gload(kt + 2, ra0, rb0);
;     compute(0);
;     lstore(1, ra1, rb1);
;     __syncthreads();
;     if (kt + 3 < nk) gload(kt + 3, ra1, rb1);
;     compute(1);
;     if (kt + 2 < nk) lstore(0, ra0, rb0);
;     __syncthreads();
	ds_read_b128 v[132:135], v228 offset:0
	ds_read_b128 v[136:139], v228 offset:4096
	ds_read_b128 v[140:143], v232 offset:0
	ds_read_b128 v[144:147], v232 offset:4096
	ds_read_b128 v[148:151], v232 offset:16384
	ds_read_b128 v[180:183], v232 offset:20480
	s_mov_b32 m0, s45
	s_nop 0
	global_load_lds_dwordx4 v178, s[68:69]
	global_load_lds_dwordx4 v179, s[70:71] offset:1024
	global_load_lds_dwordx4 v178, s[72:73] offset:2048
	global_load_lds_dwordx4 v179, s[74:75] offset:3072
	ds_read_b128 v[184:187], v229 offset:0
	ds_read_b128 v[208:211], v229 offset:4096
	ds_read_b128 v[212:215], v233 offset:0
	ds_read_b128 v[216:219], v233 offset:4096
	ds_read_b128 v[220:223], v233 offset:16384
	ds_read_b128 v[224:227], v233 offset:20480
	s_waitcnt lgkmcnt(6)
	v_mfma_f32_32x32x16_bf16 v[4:19], v[140:143], v[132:135], v[4:19]
	v_mfma_f32_32x32x16_bf16 v[68:83], v[140:143], v[136:139], v[68:83]
	v_mfma_f32_32x32x16_bf16 v[20:35], v[144:147], v[132:135], v[20:35]
	v_mfma_f32_32x32x16_bf16 v[84:99], v[144:147], v[136:139], v[84:99]
	v_mfma_f32_32x32x16_bf16 v[36:51], v[148:151], v[132:135], v[36:51]
	v_mfma_f32_32x32x16_bf16 v[100:115], v[148:151], v[136:139], v[100:115]
	v_mfma_f32_32x32x16_bf16 v[52:67], v[180:183], v[132:135], v[52:67]
	v_mfma_f32_32x32x16_bf16 v[116:131], v[180:183], v[136:139], v[116:131]
	s_mov_b32 m0, s47
	s_nop 0
	global_load_lds_dwordx4 v178, s[76:77]
	global_load_lds_dwordx4 v179, s[78:79] offset:1024
	global_load_lds_dwordx4 v178, s[80:81] offset:2048
	global_load_lds_dwordx4 v179, s[82:83] offset:3072
	v_add_u32_e32 v178, 0x80, v178
	v_add_u32_e32 v179, 0x80, v179
	ds_read_b128 v[132:135], v230 offset:0
	ds_read_b128 v[136:139], v230 offset:4096
	ds_read_b128 v[140:143], v234 offset:0
	ds_read_b128 v[144:147], v234 offset:4096
	ds_read_b128 v[148:151], v234 offset:16384
	ds_read_b128 v[180:183], v234 offset:20480
	s_waitcnt lgkmcnt(6)
	v_mfma_f32_32x32x16_bf16 v[4:19], v[212:215], v[184:187], v[4:19]
	v_mfma_f32_32x32x16_bf16 v[68:83], v[212:215], v[208:211], v[68:83]
	v_mfma_f32_32x32x16_bf16 v[20:35], v[216:219], v[184:187], v[20:35]
	v_mfma_f32_32x32x16_bf16 v[84:99], v[216:219], v[208:211], v[84:99]
	v_mfma_f32_32x32x16_bf16 v[36:51], v[220:223], v[184:187], v[36:51]
	v_mfma_f32_32x32x16_bf16 v[100:115], v[220:223], v[208:211], v[100:115]
	v_mfma_f32_32x32x16_bf16 v[52:67], v[224:227], v[184:187], v[52:67]
	v_mfma_f32_32x32x16_bf16 v[116:131], v[224:227], v[208:211], v[116:131]
	ds_read_b128 v[184:187], v231 offset:0
	ds_read_b128 v[208:211], v231 offset:4096
	ds_read_b128 v[212:215], v235 offset:0
	ds_read_b128 v[216:219], v235 offset:4096
	ds_read_b128 v[220:223], v235 offset:16384
	ds_read_b128 v[224:227], v235 offset:20480
	s_waitcnt lgkmcnt(6)
	v_mfma_f32_32x32x16_bf16 v[4:19], v[140:143], v[132:135], v[4:19]
	v_mfma_f32_32x32x16_bf16 v[68:83], v[140:143], v[136:139], v[68:83]
	v_mfma_f32_32x32x16_bf16 v[20:35], v[144:147], v[132:135], v[20:35]
	v_mfma_f32_32x32x16_bf16 v[84:99], v[144:147], v[136:139], v[84:99]
	v_mfma_f32_32x32x16_bf16 v[36:51], v[148:151], v[132:135], v[36:51]
	v_mfma_f32_32x32x16_bf16 v[100:115], v[148:151], v[136:139], v[100:115]
	v_mfma_f32_32x32x16_bf16 v[52:67], v[180:183], v[132:135], v[52:67]
	v_mfma_f32_32x32x16_bf16 v[116:131], v[180:183], v[136:139], v[116:131]
	s_waitcnt lgkmcnt(0)
	v_mfma_f32_32x32x16_bf16 v[4:19], v[212:215], v[184:187], v[4:19]
	v_mfma_f32_32x32x16_bf16 v[68:83], v[212:215], v[208:211], v[68:83]
	v_mfma_f32_32x32x16_bf16 v[20:35], v[216:219], v[184:187], v[20:35]
	v_mfma_f32_32x32x16_bf16 v[84:99], v[216:219], v[208:211], v[84:99]
	v_mfma_f32_32x32x16_bf16 v[36:51], v[220:223], v[184:187], v[36:51]
	v_mfma_f32_32x32x16_bf16 v[100:115], v[220:223], v[208:211], v[100:115]
	v_mfma_f32_32x32x16_bf16 v[52:67], v[224:227], v[184:187], v[52:67]
	v_mfma_f32_32x32x16_bf16 v[116:131], v[224:227], v[208:211], v[116:131]
	s_waitcnt vmcnt(0) lgkmcnt(0)
	s_barrier
	ds_read_b128 v[132:135], v228 offset:32768
	ds_read_b128 v[136:139], v228 offset:36864
	ds_read_b128 v[140:143], v232 offset:32768
	ds_read_b128 v[144:147], v232 offset:36864
	ds_read_b128 v[148:151], v232 offset:49152
	ds_read_b128 v[180:183], v232 offset:53248
	s_mov_b32 m0, s44
	s_nop 0
	global_load_lds_dwordx4 v178, s[68:69]
	global_load_lds_dwordx4 v179, s[70:71] offset:1024
	global_load_lds_dwordx4 v178, s[72:73] offset:2048
	global_load_lds_dwordx4 v179, s[74:75] offset:3072
	ds_read_b128 v[184:187], v229 offset:32768
	ds_read_b128 v[208:211], v229 offset:36864
	ds_read_b128 v[212:215], v233 offset:32768
	ds_read_b128 v[216:219], v233 offset:36864
	ds_read_b128 v[220:223], v233 offset:49152
	ds_read_b128 v[224:227], v233 offset:53248
	s_waitcnt lgkmcnt(6)
	v_mfma_f32_32x32x16_bf16 v[4:19], v[140:143], v[132:135], v[4:19]
	v_mfma_f32_32x32x16_bf16 v[68:83], v[140:143], v[136:139], v[68:83]
	v_mfma_f32_32x32x16_bf16 v[20:35], v[144:147], v[132:135], v[20:35]
	v_mfma_f32_32x32x16_bf16 v[84:99], v[144:147], v[136:139], v[84:99]
	v_mfma_f32_32x32x16_bf16 v[36:51], v[148:151], v[132:135], v[36:51]
	v_mfma_f32_32x32x16_bf16 v[100:115], v[148:151], v[136:139], v[100:115]
	v_mfma_f32_32x32x16_bf16 v[52:67], v[180:183], v[132:135], v[52:67]
	v_mfma_f32_32x32x16_bf16 v[116:131], v[180:183], v[136:139], v[116:131]
	s_mov_b32 m0, s46
	s_nop 0
	global_load_lds_dwordx4 v178, s[76:77]
	global_load_lds_dwordx4 v179, s[78:79] offset:1024
	global_load_lds_dwordx4 v178, s[80:81] offset:2048
	global_load_lds_dwordx4 v179, s[82:83] offset:3072
	v_add_u32_e32 v178, 0x80, v178
	v_add_u32_e32 v179, 0x80, v179
	ds_read_b128 v[132:135], v230 offset:32768
	ds_read_b128 v[136:139], v230 offset:36864
	ds_read_b128 v[140:143], v234 offset:32768
	ds_read_b128 v[144:147], v234 offset:36864
	ds_read_b128 v[148:151], v234 offset:49152
	ds_read_b128 v[180:183], v234 offset:53248
	s_waitcnt lgkmcnt(6)
; #define MFMA32(a, b, c) __builtin_amdgcn_mfma_f32_32x32x16_bf16((a), (b), (c), 0, 0, 0)
; template <bool SWAP, class Epi>
; DI void gemm_tile(const u16* __restrict__ A, int lda, const u16* __restrict__ Bw, int ldb, int K, char* lds, Epi epi) {
;     ...
;   auto compute = [&](int st) {
;     const char* as = lds + st * GEMM_STAGE;
;     const char* bs = as + 36864;
; #pragma unroll
;     for (int ks = 0; ks < 4; ++ks) {
;       bf16x8 af[2], bfr[2];
; #pragma unroll
;       for (int mi = 0; mi < 2; ++mi) af[mi] = *(const bf16x8*)(as + ((wm * 64 + mi * 32 + r) * 72 + ks * 16 + 8 * h) * 2);
; #pragma unroll
;       for (int ni = 0; ni < 2; ++ni) bfr[ni] = *(const bf16x8*)(bs + ((wn * 64 + ni * 32 + r) * 72 + ks * 16 + 8 * h) * 2);
; #pragma unroll
;       for (int mi = 0; mi < 2; ++mi)
; #pragma unroll
;         for (int ni = 0; ni < 2; ++ni) {
;           if (SWAP) acc[mi][ni] = MFMA32(bfr[ni], af[mi], acc[mi][ni]);
;           else acc[mi][ni] = MFMA32(af[mi], bfr[ni], acc[mi][ni]);
;         }
;     }
;   };
;   gload(0, ra0, rb0);
;   lstore(0, ra0, rb0);
;   gload(1, ra1, rb1);
;   __syncthreads();
;   for (int kt = 0; kt < nk; kt += 2) {
;     if (kt + 2 < nk) gload(kt + 2, ra0, rb0);
;     compute(0);
;     lstore(1, ra1, rb1);
;     __syncthreads();
;     if (kt + 3 < nk) gload(kt + 3, ra1, rb1);
;     compute(1);
;     if (kt + 2 < nk) lstore(0, ra0, rb0);
;     __syncthreads();
	v_mfma_f32_32x32x16_bf16 v[4:19], v[212:215], v[184:187], v[4:19]
	v_mfma_f32_32x32x16_bf16 v[68:83], v[212:215], v[208:211], v[68:83]
	v_mfma_f32_32x32x16_bf16 v[20:35], v[216:219], v[184:187], v[20:35]
	v_mfma_f32_32x32x16_bf16 v[84:99], v[216:219], v[208:211], v[84:99]
	v_mfma_f32_32x32x16_bf16 v[36:51], v[220:223], v[184:187], v[36:51]
	v_mfma_f32_32x32x16_bf16 v[100:115], v[220:223], v[208:211], v[100:115]
	v_mfma_f32_32x32x16_bf16 v[52:67], v[224:227], v[184:187], v[52:67]
	v_mfma_f32_32x32x16_bf16 v[116:131], v[224:227], v[208:211], v[116:131]
	ds_read_b128 v[184:187], v231 offset:32768
	ds_read_b128 v[208:211], v231 offset:36864
	ds_read_b128 v[212:215], v235 offset:32768
	ds_read_b128 v[216:219], v235 offset:36864
	ds_read_b128 v[220:223], v235 offset:49152
	ds_read_b128 v[224:227], v235 offset:53248
	s_waitcnt lgkmcnt(6)
	v_mfma_f32_32x32x16_bf16 v[4:19], v[140:143], v[132:135], v[4:19]
	v_mfma_f32_32x32x16_bf16 v[68:83], v[140:143], v[136:139], v[68:83]
	v_mfma_f32_32x32x16_bf16 v[20:35], v[144:147], v[132:135], v[20:35]
	v_mfma_f32_32x32x16_bf16 v[84:99], v[144:147], v[136:139], v[84:99]
	v_mfma_f32_32x32x16_bf16 v[36:51], v[148:151], v[132:135], v[36:51]
	v_mfma_f32_32x32x16_bf16 v[100:115], v[148:151], v[136:139], v[100:115]
	v_mfma_f32_32x32x16_bf16 v[52:67], v[180:183], v[132:135], v[52:67]
	v_mfma_f32_32x32x16_bf16 v[116:131], v[180:183], v[136:139], v[116:131]
	s_waitcnt lgkmcnt(0)
	v_mfma_f32_32x32x16_bf16 v[4:19], v[212:215], v[184:187], v[4:19]
	v_mfma_f32_32x32x16_bf16 v[68:83], v[212:215], v[208:211], v[68:83]
	v_mfma_f32_32x32x16_bf16 v[20:35], v[216:219], v[184:187], v[20:35]
	v_mfma_f32_32x32x16_bf16 v[84:99], v[216:219], v[208:211], v[84:99]
	v_mfma_f32_32x32x16_bf16 v[36:51], v[220:223], v[184:187], v[36:51]
	v_mfma_f32_32x32x16_bf16 v[100:115], v[220:223], v[208:211], v[100:115]
	v_mfma_f32_32x32x16_bf16 v[52:67], v[224:227], v[184:187], v[52:67]
	v_mfma_f32_32x32x16_bf16 v[116:131], v[224:227], v[208:211], v[116:131]
	s_waitcnt vmcnt(0) lgkmcnt(0)
	s_barrier
	ds_read_b128 v[132:135], v228 offset:0
	ds_read_b128 v[136:139], v228 offset:4096
	ds_read_b128 v[140:143], v232 offset:0
	ds_read_b128 v[144:147], v232 offset:4096
	ds_read_b128 v[148:151], v232 offset:16384
	ds_read_b128 v[180:183], v232 offset:20480
	s_mov_b32 m0, s45
	s_nop 0
	global_load_lds_dwordx4 v178, s[68:69]
	global_load_lds_dwordx4 v179, s[70:71] offset:1024
	global_load_lds_dwordx4 v178, s[72:73] offset:2048
	global_load_lds_dwordx4 v179, s[74:75] offset:3072
	ds_read_b128 v[184:187], v229 offset:0
	ds_read_b128 v[208:211], v229 offset:4096
	ds_read_b128 v[212:215], v233 offset:0
	ds_read_b128 v[216:219], v233 offset:4096
	ds_read_b128 v[220:223], v233 offset:16384
	ds_read_b128 v[224:227], v233 offset:20480
	s_waitcnt lgkmcnt(6)
	v_mfma_f32_32x32x16_bf16 v[4:19], v[140:143], v[132:135], v[4:19]
	v_mfma_f32_32x32x16_bf16 v[68:83], v[140:143], v[136:139], v[68:83]
	v_mfma_f32_32x32x16_bf16 v[20:35], v[144:147], v[132:135], v[20:35]
	v_mfma_f32_32x32x16_bf16 v[84:99], v[144:147], v[136:139], v[84:99]
	v_mfma_f32_32x32x16_bf16 v[36:51], v[148:151], v[132:135], v[36:51]
	v_mfma_f32_32x32x16_bf16 v[100:115], v[148:151], v[136:139], v[100:115]
	v_mfma_f32_32x32x16_bf16 v[52:67], v[180:183], v[132:135], v[52:67]
	v_mfma_f32_32x32x16_bf16 v[116:131], v[180:183], v[136:139], v[116:131]
	s_mov_b32 m0, s47
	s_nop 0
	global_load_lds_dwordx4 v178, s[76:77]
	global_load_lds_dwordx4 v179, s[78:79] offset:1024
	global_load_lds_dwordx4 v178, s[80:81] offset:2048
	global_load_lds_dwordx4 v179, s[82:83] offset:3072
	v_add_u32_e32 v178, 0x80, v178
	v_add_u32_e32 v179, 0x80, v179
	ds_read_b128 v[132:135], v230 offset:0
	ds_read_b128 v[136:139], v230 offset:4096
	ds_read_b128 v[140:143], v234 offset:0
	ds_read_b128 v[144:147], v234 offset:4096
	ds_read_b128 v[148:151], v234 offset:16384
	ds_read_b128 v[180:183], v234 offset:20480
	s_waitcnt lgkmcnt(6)
	v_mfma_f32_32x32x16_bf16 v[4:19], v[212:215], v[184:187], v[4:19]
	v_mfma_f32_32x32x16_bf16 v[68:83], v[212:215], v[208:211], v[68:83]
	v_mfma_f32_32x32x16_bf16 v[20:35], v[216:219], v[184:187], v[20:35]
	v_mfma_f32_32x32x16_bf16 v[84:99], v[216:219], v[208:211], v[84:99]
	v_mfma_f32_32x32x16_bf16 v[36:51], v[220:223], v[184:187], v[36:51]
	v_mfma_f32_32x32x16_bf16 v[100:115], v[220:223], v[208:211], v[100:115]
	v_mfma_f32_32x32x16_bf16 v[52:67], v[224:227], v[184:187], v[52:67]
	v_mfma_f32_32x32x16_bf16 v[116:131], v[224:227], v[208:211], v[116:131]
	ds_read_b128 v[184:187], v231 offset:0
	ds_read_b128 v[208:211], v231 offset:4096
	ds_read_b128 v[212:215], v235 offset:0
	ds_read_b128 v[216:219], v235 offset:4096
	ds_read_b128 v[220:223], v235 offset:16384
	ds_read_b128 v[224:227], v235 offset:20480
	s_waitcnt lgkmcnt(6)
	v_mfma_f32_32x32x16_bf16 v[4:19], v[140:143], v[132:135], v[4:19]
	v_mfma_f32_32x32x16_bf16 v[68:83], v[140:143], v[136:139], v[68:83]
	v_mfma_f32_32x32x16_bf16 v[20:35], v[144:147], v[132:135], v[20:35]
	v_mfma_f32_32x32x16_bf16 v[84:99], v[144:147], v[136:139], v[84:99]
	v_mfma_f32_32x32x16_bf16 v[36:51], v[148:151], v[132:135], v[36:51]
	v_mfma_f32_32x32x16_bf16 v[100:115], v[148:151], v[136:139], v[100:115]
	v_mfma_f32_32x32x16_bf16 v[52:67], v[180:183], v[132:135], v[52:67]
	v_mfma_f32_32x32x16_bf16 v[116:131], v[180:183], v[136:139], v[116:131]
	s_waitcnt lgkmcnt(0)
	v_mfma_f32_32x32x16_bf16 v[4:19], v[212:215], v[184:187], v[4:19]
	v_mfma_f32_32x32x16_bf16 v[68:83], v[212:215], v[208:211], v[68:83]
	v_mfma_f32_32x32x16_bf16 v[20:35], v[216:219], v[184:187], v[20:35]
	v_mfma_f32_32x32x16_bf16 v[84:99], v[216:219], v[208:211], v[84:99]
	v_mfma_f32_32x32x16_bf16 v[36:51], v[220:223], v[184:187], v[36:51]
	v_mfma_f32_32x32x16_bf16 v[100:115], v[220:223], v[208:211], v[100:115]
	v_mfma_f32_32x32x16_bf16 v[52:67], v[224:227], v[184:187], v[52:67]
	v_mfma_f32_32x32x16_bf16 v[116:131], v[224:227], v[208:211], v[116:131]
	s_waitcnt vmcnt(0) lgkmcnt(0)
	s_barrier
; #define MFMA32(a, b, c) __builtin_amdgcn_mfma_f32_32x32x16_bf16((a), (b), (c), 0, 0, 0)
; template <bool SWAP, class Epi>
; DI void gemm_tile(const u16* __restrict__ A, int lda, const u16* __restrict__ Bw, int ldb, int K, char* lds, Epi epi) {
;     ...
;   auto compute = [&](int st) {
;     const char* as = lds + st * GEMM_STAGE;
;     const char* bs = as + 36864;
; #pragma unroll
;     for (int ks = 0; ks < 4; ++ks) {
;       bf16x8 af[2], bfr[2];
; #pragma unroll
;       for (int mi = 0; mi < 2; ++mi) af[mi] = *(const bf16x8*)(as + ((wm * 64 + mi * 32 + r) * 72 + ks * 16 + 8 * h) * 2);
; #pragma unroll
;       for (int ni = 0; ni < 2; ++ni) bfr[ni] = *(const bf16x8*)(bs + ((wn * 64 + ni * 32 + r) * 72 + ks * 16 + 8 * h) * 2);
; #pragma unroll
;       for (int mi = 0; mi < 2; ++mi)
; #pragma unroll
;         for (int ni = 0; ni < 2; ++ni) {
;           if (SWAP) acc[mi][ni] = MFMA32(bfr[ni], af[mi], acc[mi][ni]);
;           else acc[mi][ni] = MFMA32(af[mi], bfr[ni], acc[mi][ni]);
;         }
;     }
;   };
;   gload(0, ra0, rb0);
;   lstore(0, ra0, rb0);
;   gload(1, ra1, rb1);
;   __syncthreads();
;   for (int kt = 0; kt < nk; kt += 2) {
;     if (kt + 2 < nk) gload(kt + 2, ra0, rb0);
;     compute(0);
;     lstore(1, ra1, rb1);
;     __syncthreads();
;     if (kt + 3 < nk) gload(kt + 3, ra1, rb1);
;     compute(1);
;     if (kt + 2 < nk) lstore(0, ra0, rb0);
;     __syncthreads();
	ds_read_b128 v[132:135], v228 offset:32768
	ds_read_b128 v[136:139], v228 offset:36864
	ds_read_b128 v[140:143], v232 offset:32768
	ds_read_b128 v[144:147], v232 offset:36864
	ds_read_b128 v[148:151], v232 offset:49152
	ds_read_b128 v[180:183], v232 offset:53248
	s_mov_b32 m0, s44
	s_nop 0
	global_load_lds_dwordx4 v178, s[68:69]
	global_load_lds_dwordx4 v179, s[70:71] offset:1024
	global_load_lds_dwordx4 v178, s[72:73] offset:2048
	global_load_lds_dwordx4 v179, s[74:75] offset:3072
	ds_read_b128 v[184:187], v229 offset:32768
	ds_read_b128 v[208:211], v229 offset:36864
	ds_read_b128 v[212:215], v233 offset:32768
	ds_read_b128 v[216:219], v233 offset:36864
	ds_read_b128 v[220:223], v233 offset:49152
	ds_read_b128 v[224:227], v233 offset:53248
	s_waitcnt lgkmcnt(6)
	v_mfma_f32_32x32x16_bf16 v[4:19], v[140:143], v[132:135], v[4:19]
	v_mfma_f32_32x32x16_bf16 v[68:83], v[140:143], v[136:139], v[68:83]
	v_mfma_f32_32x32x16_bf16 v[20:35], v[144:147], v[132:135], v[20:35]
	v_mfma_f32_32x32x16_bf16 v[84:99], v[144:147], v[136:139], v[84:99]
	v_mfma_f32_32x32x16_bf16 v[36:51], v[148:151], v[132:135], v[36:51]
	v_mfma_f32_32x32x16_bf16 v[100:115], v[148:151], v[136:139], v[100:115]
	v_mfma_f32_32x32x16_bf16 v[52:67], v[180:183], v[132:135], v[52:67]
	v_mfma_f32_32x32x16_bf16 v[116:131], v[180:183], v[136:139], v[116:131]
	s_mov_b32 m0, s46
	s_nop 0
	global_load_lds_dwordx4 v178, s[76:77]
	global_load_lds_dwordx4 v179, s[78:79] offset:1024
	global_load_lds_dwordx4 v178, s[80:81] offset:2048
	global_load_lds_dwordx4 v179, s[82:83] offset:3072
	v_add_u32_e32 v178, 0x80, v178
	v_add_u32_e32 v179, 0x80, v179
	ds_read_b128 v[132:135], v230 offset:32768
	ds_read_b128 v[136:139], v230 offset:36864
	ds_read_b128 v[140:143], v234 offset:32768
	ds_read_b128 v[144:147], v234 offset:36864
	ds_read_b128 v[148:151], v234 offset:49152
	ds_read_b128 v[180:183], v234 offset:53248
	s_waitcnt lgkmcnt(6)
	v_mfma_f32_32x32x16_bf16 v[4:19], v[212:215], v[184:187], v[4:19]
	v_mfma_f32_32x32x16_bf16 v[68:83], v[212:215], v[208:211], v[68:83]
	v_mfma_f32_32x32x16_bf16 v[20:35], v[216:219], v[184:187], v[20:35]
	v_mfma_f32_32x32x16_bf16 v[84:99], v[216:219], v[208:211], v[84:99]
	v_mfma_f32_32x32x16_bf16 v[36:51], v[220:223], v[184:187], v[36:51]
	v_mfma_f32_32x32x16_bf16 v[100:115], v[220:223], v[208:211], v[100:115]
	v_mfma_f32_32x32x16_bf16 v[52:67], v[224:227], v[184:187], v[52:67]
	v_mfma_f32_32x32x16_bf16 v[116:131], v[224:227], v[208:211], v[116:131]
	ds_read_b128 v[184:187], v231 offset:32768
	ds_read_b128 v[208:211], v231 offset:36864
	ds_read_b128 v[212:215], v235 offset:32768
	ds_read_b128 v[216:219], v235 offset:36864
	ds_read_b128 v[220:223], v235 offset:49152
	ds_read_b128 v[224:227], v235 offset:53248
	s_waitcnt lgkmcnt(6)
	v_mfma_f32_32x32x16_bf16 v[4:19], v[140:143], v[132:135], v[4:19]
	v_mfma_f32_32x32x16_bf16 v[68:83], v[140:143], v[136:139], v[68:83]
	v_mfma_f32_32x32x16_bf16 v[20:35], v[144:147], v[132:135], v[20:35]
	v_mfma_f32_32x32x16_bf16 v[84:99], v[144:147], v[136:139], v[84:99]
	v_mfma_f32_32x32x16_bf16 v[36:51], v[148:151], v[132:135], v[36:51]
	v_mfma_f32_32x32x16_bf16 v[100:115], v[148:151], v[136:139], v[100:115]
	v_mfma_f32_32x32x16_bf16 v[52:67], v[180:183], v[132:135], v[52:67]
	v_mfma_f32_32x32x16_bf16 v[116:131], v[180:183], v[136:139], v[116:131]
	s_waitcnt lgkmcnt(0)
	v_mfma_f32_32x32x16_bf16 v[4:19], v[212:215], v[184:187], v[4:19]
	v_mfma_f32_32x32x16_bf16 v[68:83], v[212:215], v[208:211], v[68:83]
	v_mfma_f32_32x32x16_bf16 v[20:35], v[216:219], v[184:187], v[20:35]
	v_mfma_f32_32x32x16_bf16 v[84:99], v[216:219], v[208:211], v[84:99]
	v_mfma_f32_32x32x16_bf16 v[36:51], v[220:223], v[184:187], v[36:51]
	v_mfma_f32_32x32x16_bf16 v[100:115], v[220:223], v[208:211], v[100:115]
	v_mfma_f32_32x32x16_bf16 v[52:67], v[224:227], v[184:187], v[52:67]
	v_mfma_f32_32x32x16_bf16 v[116:131], v[224:227], v[208:211], v[116:131]
	s_waitcnt vmcnt(0) lgkmcnt(0)
	s_barrier
	ds_read_b128 v[132:135], v228 offset:0
	ds_read_b128 v[136:139], v228 offset:4096
	ds_read_b128 v[140:143], v232 offset:0
	ds_read_b128 v[144:147], v232 offset:4096
	ds_read_b128 v[148:151], v232 offset:16384
	ds_read_b128 v[180:183], v232 offset:20480
	s_mov_b32 m0, s45
	s_nop 0
	global_load_lds_dwordx4 v178, s[68:69]
	global_load_lds_dwordx4 v179, s[70:71] offset:1024
	global_load_lds_dwordx4 v178, s[72:73] offset:2048
	global_load_lds_dwordx4 v179, s[74:75] offset:3072
	ds_read_b128 v[184:187], v229 offset:0
	ds_read_b128 v[208:211], v229 offset:4096
	ds_read_b128 v[212:215], v233 offset:0
	ds_read_b128 v[216:219], v233 offset:4096
	ds_read_b128 v[220:223], v233 offset:16384
	ds_read_b128 v[224:227], v233 offset:20480
	s_waitcnt lgkmcnt(6)
	v_mfma_f32_32x32x16_bf16 v[4:19], v[140:143], v[132:135], v[4:19]
	v_mfma_f32_32x32x16_bf16 v[68:83], v[140:143], v[136:139], v[68:83]
	v_mfma_f32_32x32x16_bf16 v[20:35], v[144:147], v[132:135], v[20:35]
	v_mfma_f32_32x32x16_bf16 v[84:99], v[144:147], v[136:139], v[84:99]
	v_mfma_f32_32x32x16_bf16 v[36:51], v[148:151], v[132:135], v[36:51]
	v_mfma_f32_32x32x16_bf16 v[100:115], v[148:151], v[136:139], v[100:115]
	v_mfma_f32_32x32x16_bf16 v[52:67], v[180:183], v[132:135], v[52:67]
	v_mfma_f32_32x32x16_bf16 v[116:131], v[180:183], v[136:139], v[116:131]
	s_mov_b32 m0, s47
	s_nop 0
	global_load_lds_dwordx4 v178, s[76:77]
	global_load_lds_dwordx4 v179, s[78:79] offset:1024
	global_load_lds_dwordx4 v178, s[80:81] offset:2048
	global_load_lds_dwordx4 v179, s[82:83] offset:3072
	v_add_u32_e32 v178, 0x80, v178
	v_add_u32_e32 v179, 0x80, v179
	ds_read_b128 v[132:135], v230 offset:0
	ds_read_b128 v[136:139], v230 offset:4096
	ds_read_b128 v[140:143], v234 offset:0
	ds_read_b128 v[144:147], v234 offset:4096
	ds_read_b128 v[148:151], v234 offset:16384
	ds_read_b128 v[180:183], v234 offset:20480
	s_waitcnt lgkmcnt(6)
; #define MFMA32(a, b, c) __builtin_amdgcn_mfma_f32_32x32x16_bf16((a), (b), (c), 0, 0, 0)
; template <bool SWAP, class Epi>
; DI void gemm_tile(const u16* __restrict__ A, int lda, const u16* __restrict__ Bw, int ldb, int K, char* lds, Epi epi) {
;     ...
;   auto compute = [&](int st) {
;     const char* as = lds + st * GEMM_STAGE;
;     const char* bs = as + 36864;
; #pragma unroll
;     for (int ks = 0; ks < 4; ++ks) {
;       bf16x8 af[2], bfr[2];
; #pragma unroll
;       for (int mi = 0; mi < 2; ++mi) af[mi] = *(const bf16x8*)(as + ((wm * 64 + mi * 32 + r) * 72 + ks * 16 + 8 * h) * 2);
; #pragma unroll
;       for (int ni = 0; ni < 2; ++ni) bfr[ni] = *(const bf16x8*)(bs + ((wn * 64 + ni * 32 + r) * 72 + ks * 16 + 8 * h) * 2);
; #pragma unroll
;       for (int mi = 0; mi < 2; ++mi)
; #pragma unroll
;         for (int ni = 0; ni < 2; ++ni) {
;           if (SWAP) acc[mi][ni] = MFMA32(bfr[ni], af[mi], acc[mi][ni]);
;           else acc[mi][ni] = MFMA32(af[mi], bfr[ni], acc[mi][ni]);
;         }
;     }
;   };
;   gload(0, ra0, rb0);
;   lstore(0, ra0, rb0);
;   gload(1, ra1, rb1);
;   __syncthreads();
;   for (int kt = 0; kt < nk; kt += 2) {
;     if (kt + 2 < nk) gload(kt + 2, ra0, rb0);
;     compute(0);
;     lstore(1, ra1, rb1);
;     __syncthreads();
;     if (kt + 3 < nk) gload(kt + 3, ra1, rb1);
;     compute(1);
;     if (kt + 2 < nk) lstore(0, ra0, rb0);
;     __syncthreads();
	v_mfma_f32_32x32x16_bf16 v[4:19], v[212:215], v[184:187], v[4:19]
	v_mfma_f32_32x32x16_bf16 v[68:83], v[212:215], v[208:211], v[68:83]
	v_mfma_f32_32x32x16_bf16 v[20:35], v[216:219], v[184:187], v[20:35]
	v_mfma_f32_32x32x16_bf16 v[84:99], v[216:219], v[208:211], v[84:99]
	v_mfma_f32_32x32x16_bf16 v[36:51], v[220:223], v[184:187], v[36:51]
	v_mfma_f32_32x32x16_bf16 v[100:115], v[220:223], v[208:211], v[100:115]
	v_mfma_f32_32x32x16_bf16 v[52:67], v[224:227], v[184:187], v[52:67]
	v_mfma_f32_32x32x16_bf16 v[116:131], v[224:227], v[208:211], v[116:131]
	ds_read_b128 v[184:187], v231 offset:0
	ds_read_b128 v[208:211], v231 offset:4096
	ds_read_b128 v[212:215], v235 offset:0
	ds_read_b128 v[216:219], v235 offset:4096
	ds_read_b128 v[220:223], v235 offset:16384
	ds_read_b128 v[224:227], v235 offset:20480
	s_waitcnt lgkmcnt(6)
	v_mfma_f32_32x32x16_bf16 v[4:19], v[140:143], v[132:135], v[4:19]
	v_mfma_f32_32x32x16_bf16 v[68:83], v[140:143], v[136:139], v[68:83]
	v_mfma_f32_32x32x16_bf16 v[20:35], v[144:147], v[132:135], v[20:35]
	v_mfma_f32_32x32x16_bf16 v[84:99], v[144:147], v[136:139], v[84:99]
	v_mfma_f32_32x32x16_bf16 v[36:51], v[148:151], v[132:135], v[36:51]
	v_mfma_f32_32x32x16_bf16 v[100:115], v[148:151], v[136:139], v[100:115]
	v_mfma_f32_32x32x16_bf16 v[52:67], v[180:183], v[132:135], v[52:67]
	v_mfma_f32_32x32x16_bf16 v[116:131], v[180:183], v[136:139], v[116:131]
	s_waitcnt lgkmcnt(0)
	v_mfma_f32_32x32x16_bf16 v[4:19], v[212:215], v[184:187], v[4:19]
	v_mfma_f32_32x32x16_bf16 v[68:83], v[212:215], v[208:211], v[68:83]
	v_mfma_f32_32x32x16_bf16 v[20:35], v[216:219], v[184:187], v[20:35]
	v_mfma_f32_32x32x16_bf16 v[84:99], v[216:219], v[208:211], v[84:99]
	v_mfma_f32_32x32x16_bf16 v[36:51], v[220:223], v[184:187], v[36:51]
	v_mfma_f32_32x32x16_bf16 v[100:115], v[220:223], v[208:211], v[100:115]
	v_mfma_f32_32x32x16_bf16 v[52:67], v[224:227], v[184:187], v[52:67]
	v_mfma_f32_32x32x16_bf16 v[116:131], v[224:227], v[208:211], v[116:131]
	s_waitcnt vmcnt(0) lgkmcnt(0)
	s_barrier
	ds_read_b128 v[132:135], v228 offset:32768
	ds_read_b128 v[136:139], v228 offset:36864
	ds_read_b128 v[140:143], v232 offset:32768
	ds_read_b128 v[144:147], v232 offset:36864
	ds_read_b128 v[148:151], v232 offset:49152
	ds_read_b128 v[180:183], v232 offset:53248
	s_mov_b32 m0, s44
	s_nop 0
	global_load_lds_dwordx4 v178, s[68:69]
	global_load_lds_dwordx4 v179, s[70:71] offset:1024
	global_load_lds_dwordx4 v178, s[72:73] offset:2048
	global_load_lds_dwordx4 v179, s[74:75] offset:3072
	ds_read_b128 v[184:187], v229 offset:32768
	ds_read_b128 v[208:211], v229 offset:36864
	ds_read_b128 v[212:215], v233 offset:32768
	ds_read_b128 v[216:219], v233 offset:36864
	ds_read_b128 v[220:223], v233 offset:49152
	ds_read_b128 v[224:227], v233 offset:53248
	s_waitcnt lgkmcnt(6)
	v_mfma_f32_32x32x16_bf16 v[4:19], v[140:143], v[132:135], v[4:19]
	v_mfma_f32_32x32x16_bf16 v[68:83], v[140:143], v[136:139], v[68:83]
	v_mfma_f32_32x32x16_bf16 v[20:35], v[144:147], v[132:135], v[20:35]
	v_mfma_f32_32x32x16_bf16 v[84:99], v[144:147], v[136:139], v[84:99]
	v_mfma_f32_32x32x16_bf16 v[36:51], v[148:151], v[132:135], v[36:51]
	v_mfma_f32_32x32x16_bf16 v[100:115], v[148:151], v[136:139], v[100:115]
	v_mfma_f32_32x32x16_bf16 v[52:67], v[180:183], v[132:135], v[52:67]
	v_mfma_f32_32x32x16_bf16 v[116:131], v[180:183], v[136:139], v[116:131]
	s_mov_b32 m0, s46
	s_nop 0
	global_load_lds_dwordx4 v178, s[76:77]
	global_load_lds_dwordx4 v179, s[78:79] offset:1024
	global_load_lds_dwordx4 v178, s[80:81] offset:2048
	global_load_lds_dwordx4 v179, s[82:83] offset:3072
	v_add_u32_e32 v178, 0x80, v178
	v_add_u32_e32 v179, 0x80, v179
	ds_read_b128 v[132:135], v230 offset:32768
	ds_read_b128 v[136:139], v230 offset:36864
	ds_read_b128 v[140:143], v234 offset:32768
	ds_read_b128 v[144:147], v234 offset:36864
	ds_read_b128 v[148:151], v234 offset:49152
	ds_read_b128 v[180:183], v234 offset:53248
	s_waitcnt lgkmcnt(6)
	v_mfma_f32_32x32x16_bf16 v[4:19], v[212:215], v[184:187], v[4:19]
	v_mfma_f32_32x32x16_bf16 v[68:83], v[212:215], v[208:211], v[68:83]
	v_mfma_f32_32x32x16_bf16 v[20:35], v[216:219], v[184:187], v[20:35]
	v_mfma_f32_32x32x16_bf16 v[84:99], v[216:219], v[208:211], v[84:99]
	v_mfma_f32_32x32x16_bf16 v[36:51], v[220:223], v[184:187], v[36:51]
	v_mfma_f32_32x32x16_bf16 v[100:115], v[220:223], v[208:211], v[100:115]
	v_mfma_f32_32x32x16_bf16 v[52:67], v[224:227], v[184:187], v[52:67]
	v_mfma_f32_32x32x16_bf16 v[116:131], v[224:227], v[208:211], v[116:131]
	ds_read_b128 v[184:187], v231 offset:32768
	ds_read_b128 v[208:211], v231 offset:36864
	ds_read_b128 v[212:215], v235 offset:32768
	ds_read_b128 v[216:219], v235 offset:36864
	ds_read_b128 v[220:223], v235 offset:49152
	ds_read_b128 v[224:227], v235 offset:53248
	s_waitcnt lgkmcnt(6)
	v_mfma_f32_32x32x16_bf16 v[4:19], v[140:143], v[132:135], v[4:19]
	v_mfma_f32_32x32x16_bf16 v[68:83], v[140:143], v[136:139], v[68:83]
	v_mfma_f32_32x32x16_bf16 v[20:35], v[144:147], v[132:135], v[20:35]
	v_mfma_f32_32x32x16_bf16 v[84:99], v[144:147], v[136:139], v[84:99]
	v_mfma_f32_32x32x16_bf16 v[36:51], v[148:151], v[132:135], v[36:51]
	v_mfma_f32_32x32x16_bf16 v[100:115], v[148:151], v[136:139], v[100:115]
	v_mfma_f32_32x32x16_bf16 v[52:67], v[180:183], v[132:135], v[52:67]
	v_mfma_f32_32x32x16_bf16 v[116:131], v[180:183], v[136:139], v[116:131]
	s_waitcnt lgkmcnt(0)
	v_mfma_f32_32x32x16_bf16 v[4:19], v[212:215], v[184:187], v[4:19]
	v_mfma_f32_32x32x16_bf16 v[68:83], v[212:215], v[208:211], v[68:83]
	v_mfma_f32_32x32x16_bf16 v[20:35], v[216:219], v[184:187], v[20:35]
	v_mfma_f32_32x32x16_bf16 v[84:99], v[216:219], v[208:211], v[84:99]
	v_mfma_f32_32x32x16_bf16 v[36:51], v[220:223], v[184:187], v[36:51]
	v_mfma_f32_32x32x16_bf16 v[100:115], v[220:223], v[208:211], v[100:115]
	v_mfma_f32_32x32x16_bf16 v[52:67], v[224:227], v[184:187], v[52:67]
	v_mfma_f32_32x32x16_bf16 v[116:131], v[224:227], v[208:211], v[116:131]
	s_waitcnt vmcnt(0) lgkmcnt(0)
	s_barrier
; #define MFMA32(a, b, c) __builtin_amdgcn_mfma_f32_32x32x16_bf16((a), (b), (c), 0, 0, 0)
; template <bool SWAP, class Epi>
; DI void gemm_tile(const u16* __restrict__ A, int lda, const u16* __restrict__ Bw, int ldb, int K, char* lds, Epi epi) {
;     ...
;   auto compute = [&](int st) {
;     const char* as = lds + st * GEMM_STAGE;
;     const char* bs = as + 36864;
; #pragma unroll
;     for (int ks = 0; ks < 4; ++ks) {
;       bf16x8 af[2], bfr[2];
; #pragma unroll
;       for (int mi = 0; mi < 2; ++mi) af[mi] = *(const bf16x8*)(as + ((wm * 64 + mi * 32 + r) * 72 + ks * 16 + 8 * h) * 2);
; #pragma unroll
;       for (int ni = 0; ni < 2; ++ni) bfr[ni] = *(const bf16x8*)(bs + ((wn * 64 + ni * 32 + r) * 72 + ks * 16 + 8 * h) * 2);
; #pragma unroll
;       for (int mi = 0; mi < 2; ++mi)
; #pragma unroll
;         for (int ni = 0; ni < 2; ++ni) {
;           if (SWAP) acc[mi][ni] = MFMA32(bfr[ni], af[mi], acc[mi][ni]);
;           else acc[mi][ni] = MFMA32(af[mi], bfr[ni], acc[mi][ni]);
;         }
;     }
;   };
;   gload(0, ra0, rb0);
;   lstore(0, ra0, rb0);
;   gload(1, ra1, rb1);
;   __syncthreads();
;   for (int kt = 0; kt < nk; kt += 2) {
;     if (kt + 2 < nk) gload(kt + 2, ra0, rb0);
;     compute(0);
;     lstore(1, ra1, rb1);
;     __syncthreads();
;     if (kt + 3 < nk) gload(kt + 3, ra1, rb1);
;     compute(1);
;     if (kt + 2 < nk) lstore(0, ra0, rb0);
;     __syncthreads();
	ds_read_b128 v[132:135], v228 offset:0
	ds_read_b128 v[136:139], v228 offset:4096
	ds_read_b128 v[140:143], v232 offset:0
	ds_read_b128 v[144:147], v232 offset:4096
	ds_read_b128 v[148:151], v232 offset:16384
	ds_read_b128 v[180:183], v232 offset:20480
	s_mov_b32 m0, s45
	s_nop 0
	global_load_lds_dwordx4 v178, s[68:69]
	global_load_lds_dwordx4 v179, s[70:71] offset:1024
	global_load_lds_dwordx4 v178, s[72:73] offset:2048
	global_load_lds_dwordx4 v179, s[74:75] offset:3072
	ds_read_b128 v[184:187], v229 offset:0
	ds_read_b128 v[208:211], v229 offset:4096
	ds_read_b128 v[212:215], v233 offset:0
	ds_read_b128 v[216:219], v233 offset:4096
	ds_read_b128 v[220:223], v233 offset:16384
	ds_read_b128 v[224:227], v233 offset:20480
	s_waitcnt lgkmcnt(6)
	v_mfma_f32_32x32x16_bf16 v[4:19], v[140:143], v[132:135], v[4:19]
	v_mfma_f32_32x32x16_bf16 v[68:83], v[140:143], v[136:139], v[68:83]
	v_mfma_f32_32x32x16_bf16 v[20:35], v[144:147], v[132:135], v[20:35]
	v_mfma_f32_32x32x16_bf16 v[84:99], v[144:147], v[136:139], v[84:99]
	v_mfma_f32_32x32x16_bf16 v[36:51], v[148:151], v[132:135], v[36:51]
	v_mfma_f32_32x32x16_bf16 v[100:115], v[148:151], v[136:139], v[100:115]
	v_mfma_f32_32x32x16_bf16 v[52:67], v[180:183], v[132:135], v[52:67]
	v_mfma_f32_32x32x16_bf16 v[116:131], v[180:183], v[136:139], v[116:131]
	s_mov_b32 m0, s47
	s_nop 0
	global_load_lds_dwordx4 v178, s[76:77]
	global_load_lds_dwordx4 v179, s[78:79] offset:1024
	global_load_lds_dwordx4 v178, s[80:81] offset:2048
	global_load_lds_dwordx4 v179, s[82:83] offset:3072
	v_add_u32_e32 v178, 0x80, v178
	v_add_u32_e32 v179, 0x80, v179
	ds_read_b128 v[132:135], v230 offset:0
	ds_read_b128 v[136:139], v230 offset:4096
	ds_read_b128 v[140:143], v234 offset:0
	ds_read_b128 v[144:147], v234 offset:4096
	ds_read_b128 v[148:151], v234 offset:16384
	ds_read_b128 v[180:183], v234 offset:20480
	s_waitcnt lgkmcnt(6)
	v_mfma_f32_32x32x16_bf16 v[4:19], v[212:215], v[184:187], v[4:19]
	v_mfma_f32_32x32x16_bf16 v[68:83], v[212:215], v[208:211], v[68:83]
	v_mfma_f32_32x32x16_bf16 v[20:35], v[216:219], v[184:187], v[20:35]
	v_mfma_f32_32x32x16_bf16 v[84:99], v[216:219], v[208:211], v[84:99]
	v_mfma_f32_32x32x16_bf16 v[36:51], v[220:223], v[184:187], v[36:51]
	v_mfma_f32_32x32x16_bf16 v[100:115], v[220:223], v[208:211], v[100:115]
	v_mfma_f32_32x32x16_bf16 v[52:67], v[224:227], v[184:187], v[52:67]
	v_mfma_f32_32x32x16_bf16 v[116:131], v[224:227], v[208:211], v[116:131]
	ds_read_b128 v[184:187], v231 offset:0
	ds_read_b128 v[208:211], v231 offset:4096
	ds_read_b128 v[212:215], v235 offset:0
	ds_read_b128 v[216:219], v235 offset:4096
	ds_read_b128 v[220:223], v235 offset:16384
	ds_read_b128 v[224:227], v235 offset:20480
	s_waitcnt lgkmcnt(6)
	v_mfma_f32_32x32x16_bf16 v[4:19], v[140:143], v[132:135], v[4:19]
	v_mfma_f32_32x32x16_bf16 v[68:83], v[140:143], v[136:139], v[68:83]
	v_mfma_f32_32x32x16_bf16 v[20:35], v[144:147], v[132:135], v[20:35]
	v_mfma_f32_32x32x16_bf16 v[84:99], v[144:147], v[136:139], v[84:99]
	v_mfma_f32_32x32x16_bf16 v[36:51], v[148:151], v[132:135], v[36:51]
	v_mfma_f32_32x32x16_bf16 v[100:115], v[148:151], v[136:139], v[100:115]
	v_mfma_f32_32x32x16_bf16 v[52:67], v[180:183], v[132:135], v[52:67]
	v_mfma_f32_32x32x16_bf16 v[116:131], v[180:183], v[136:139], v[116:131]
	s_waitcnt lgkmcnt(0)
	v_mfma_f32_32x32x16_bf16 v[4:19], v[212:215], v[184:187], v[4:19]
	v_mfma_f32_32x32x16_bf16 v[68:83], v[212:215], v[208:211], v[68:83]
	v_mfma_f32_32x32x16_bf16 v[20:35], v[216:219], v[184:187], v[20:35]
	v_mfma_f32_32x32x16_bf16 v[84:99], v[216:219], v[208:211], v[84:99]
	v_mfma_f32_32x32x16_bf16 v[36:51], v[220:223], v[184:187], v[36:51]
	v_mfma_f32_32x32x16_bf16 v[100:115], v[220:223], v[208:211], v[100:115]
	v_mfma_f32_32x32x16_bf16 v[52:67], v[224:227], v[184:187], v[52:67]
	v_mfma_f32_32x32x16_bf16 v[116:131], v[224:227], v[208:211], v[116:131]
	s_waitcnt vmcnt(0) lgkmcnt(0)
	s_barrier
	ds_read_b128 v[132:135], v228 offset:32768
	ds_read_b128 v[136:139], v228 offset:36864
	ds_read_b128 v[140:143], v232 offset:32768
	ds_read_b128 v[144:147], v232 offset:36864
	ds_read_b128 v[148:151], v232 offset:49152
	ds_read_b128 v[180:183], v232 offset:53248
	s_mov_b32 m0, s44
	s_nop 0
	global_load_lds_dwordx4 v178, s[68:69]
	global_load_lds_dwordx4 v179, s[70:71] offset:1024
	global_load_lds_dwordx4 v178, s[72:73] offset:2048
	global_load_lds_dwordx4 v179, s[74:75] offset:3072
	ds_read_b128 v[184:187], v229 offset:32768
	ds_read_b128 v[208:211], v229 offset:36864
	ds_read_b128 v[212:215], v233 offset:32768
	ds_read_b128 v[216:219], v233 offset:36864
	ds_read_b128 v[220:223], v233 offset:49152
	ds_read_b128 v[224:227], v233 offset:53248
	s_waitcnt lgkmcnt(6)
	v_mfma_f32_32x32x16_bf16 v[4:19], v[140:143], v[132:135], v[4:19]
	v_mfma_f32_32x32x16_bf16 v[68:83], v[140:143], v[136:139], v[68:83]
	v_mfma_f32_32x32x16_bf16 v[20:35], v[144:147], v[132:135], v[20:35]
	v_mfma_f32_32x32x16_bf16 v[84:99], v[144:147], v[136:139], v[84:99]
	v_mfma_f32_32x32x16_bf16 v[36:51], v[148:151], v[132:135], v[36:51]
	v_mfma_f32_32x32x16_bf16 v[100:115], v[148:151], v[136:139], v[100:115]
	v_mfma_f32_32x32x16_bf16 v[52:67], v[180:183], v[132:135], v[52:67]
	v_mfma_f32_32x32x16_bf16 v[116:131], v[180:183], v[136:139], v[116:131]
	s_mov_b32 m0, s46
	s_nop 0
	global_load_lds_dwordx4 v178, s[76:77]
	global_load_lds_dwordx4 v179, s[78:79] offset:1024
	global_load_lds_dwordx4 v178, s[80:81] offset:2048
	global_load_lds_dwordx4 v179, s[82:83] offset:3072
	v_add_u32_e32 v178, 0x80, v178
	v_add_u32_e32 v179, 0x80, v179
	ds_read_b128 v[132:135], v230 offset:32768
	ds_read_b128 v[136:139], v230 offset:36864
	ds_read_b128 v[140:143], v234 offset:32768
	ds_read_b128 v[144:147], v234 offset:36864
	ds_read_b128 v[148:151], v234 offset:49152
	ds_read_b128 v[180:183], v234 offset:53248
	s_waitcnt lgkmcnt(6)
; #define MFMA32(a, b, c) __builtin_amdgcn_mfma_f32_32x32x16_bf16((a), (b), (c), 0, 0, 0)
; template <bool SWAP, class Epi>
; DI void gemm_tile(const u16* __restrict__ A, int lda, const u16* __restrict__ Bw, int ldb, int K, char* lds, Epi epi) {
;     ...
;   auto compute = [&](int st) {
;     const char* as = lds + st * GEMM_STAGE;
;     const char* bs = as + 36864;
; #pragma unroll
;     for (int ks = 0; ks < 4; ++ks) {
;       bf16x8 af[2], bfr[2];
; #pragma unroll
;       for (int mi = 0; mi < 2; ++mi) af[mi] = *(const bf16x8*)(as + ((wm * 64 + mi * 32 + r) * 72 + ks * 16 + 8 * h) * 2);
; #pragma unroll
;       for (int ni = 0; ni < 2; ++ni) bfr[ni] = *(const bf16x8*)(bs + ((wn * 64 + ni * 32 + r) * 72 + ks * 16 + 8 * h) * 2);
; #pragma unroll
;       for (int mi = 0; mi < 2; ++mi)
; #pragma unroll
;         for (int ni = 0; ni < 2; ++ni) {
;           if (SWAP) acc[mi][ni] = MFMA32(bfr[ni], af[mi], acc[mi][ni]);
;           else acc[mi][ni] = MFMA32(af[mi], bfr[ni], acc[mi][ni]);
;         }
;     }
;   };
;   gload(0, ra0, rb0);
;   lstore(0, ra0, rb0);
;   gload(1, ra1, rb1);
;   __syncthreads();
;   for (int kt = 0; kt < nk; kt += 2) {
;     if (kt + 2 < nk) gload(kt + 2, ra0, rb0);
;     compute(0);
;     lstore(1, ra1, rb1);
;     __syncthreads();
;     if (kt + 3 < nk) gload(kt + 3, ra1, rb1);
;     compute(1);
;     if (kt + 2 < nk) lstore(0, ra0, rb0);
;     __syncthreads();
	v_mfma_f32_32x32x16_bf16 v[4:19], v[212:215], v[184:187], v[4:19]
	v_mfma_f32_32x32x16_bf16 v[68:83], v[212:215], v[208:211], v[68:83]
	v_mfma_f32_32x32x16_bf16 v[20:35], v[216:219], v[184:187], v[20:35]
	v_mfma_f32_32x32x16_bf16 v[84:99], v[216:219], v[208:211], v[84:99]
	v_mfma_f32_32x32x16_bf16 v[36:51], v[220:223], v[184:187], v[36:51]
	v_mfma_f32_32x32x16_bf16 v[100:115], v[220:223], v[208:211], v[100:115]
	v_mfma_f32_32x32x16_bf16 v[52:67], v[224:227], v[184:187], v[52:67]
	v_mfma_f32_32x32x16_bf16 v[116:131], v[224:227], v[208:211], v[116:131]
	ds_read_b128 v[184:187], v231 offset:32768
	ds_read_b128 v[208:211], v231 offset:36864
	ds_read_b128 v[212:215], v235 offset:32768
	ds_read_b128 v[216:219], v235 offset:36864
	ds_read_b128 v[220:223], v235 offset:49152
	ds_read_b128 v[224:227], v235 offset:53248
	s_waitcnt lgkmcnt(6)
	v_mfma_f32_32x32x16_bf16 v[4:19], v[140:143], v[132:135], v[4:19]
	v_mfma_f32_32x32x16_bf16 v[68:83], v[140:143], v[136:139], v[68:83]
	v_mfma_f32_32x32x16_bf16 v[20:35], v[144:147], v[132:135], v[20:35]
	v_mfma_f32_32x32x16_bf16 v[84:99], v[144:147], v[136:139], v[84:99]
	v_mfma_f32_32x32x16_bf16 v[36:51], v[148:151], v[132:135], v[36:51]
	v_mfma_f32_32x32x16_bf16 v[100:115], v[148:151], v[136:139], v[100:115]
	v_mfma_f32_32x32x16_bf16 v[52:67], v[180:183], v[132:135], v[52:67]
	v_mfma_f32_32x32x16_bf16 v[116:131], v[180:183], v[136:139], v[116:131]
	s_waitcnt lgkmcnt(0)
	v_mfma_f32_32x32x16_bf16 v[4:19], v[212:215], v[184:187], v[4:19]
	v_mfma_f32_32x32x16_bf16 v[68:83], v[212:215], v[208:211], v[68:83]
	v_mfma_f32_32x32x16_bf16 v[20:35], v[216:219], v[184:187], v[20:35]
	v_mfma_f32_32x32x16_bf16 v[84:99], v[216:219], v[208:211], v[84:99]
	v_mfma_f32_32x32x16_bf16 v[36:51], v[220:223], v[184:187], v[36:51]
	v_mfma_f32_32x32x16_bf16 v[100:115], v[220:223], v[208:211], v[100:115]
	v_mfma_f32_32x32x16_bf16 v[52:67], v[224:227], v[184:187], v[52:67]
	v_mfma_f32_32x32x16_bf16 v[116:131], v[224:227], v[208:211], v[116:131]
	s_waitcnt vmcnt(0) lgkmcnt(0)
	s_barrier
	ds_read_b128 v[132:135], v228 offset:0
	ds_read_b128 v[136:139], v228 offset:4096
	ds_read_b128 v[140:143], v232 offset:0
	ds_read_b128 v[144:147], v232 offset:4096
	ds_read_b128 v[148:151], v232 offset:16384
	ds_read_b128 v[180:183], v232 offset:20480
	s_mov_b32 m0, s45
	s_nop 0
	global_load_lds_dwordx4 v178, s[68:69]
	global_load_lds_dwordx4 v179, s[70:71] offset:1024
	global_load_lds_dwordx4 v178, s[72:73] offset:2048
	global_load_lds_dwordx4 v179, s[74:75] offset:3072
	ds_read_b128 v[184:187], v229 offset:0
	ds_read_b128 v[208:211], v229 offset:4096
	ds_read_b128 v[212:215], v233 offset:0
	ds_read_b128 v[216:219], v233 offset:4096
	ds_read_b128 v[220:223], v233 offset:16384
	ds_read_b128 v[224:227], v233 offset:20480
	s_waitcnt lgkmcnt(6)
	v_mfma_f32_32x32x16_bf16 v[4:19], v[140:143], v[132:135], v[4:19]
	v_mfma_f32_32x32x16_bf16 v[68:83], v[140:143], v[136:139], v[68:83]
	v_mfma_f32_32x32x16_bf16 v[20:35], v[144:147], v[132:135], v[20:35]
	v_mfma_f32_32x32x16_bf16 v[84:99], v[144:147], v[136:139], v[84:99]
	v_mfma_f32_32x32x16_bf16 v[36:51], v[148:151], v[132:135], v[36:51]
	v_mfma_f32_32x32x16_bf16 v[100:115], v[148:151], v[136:139], v[100:115]
	v_mfma_f32_32x32x16_bf16 v[52:67], v[180:183], v[132:135], v[52:67]
	v_mfma_f32_32x32x16_bf16 v[116:131], v[180:183], v[136:139], v[116:131]
	s_mov_b32 m0, s47
	s_nop 0
	global_load_lds_dwordx4 v178, s[76:77]
	global_load_lds_dwordx4 v179, s[78:79] offset:1024
	global_load_lds_dwordx4 v178, s[80:81] offset:2048
	global_load_lds_dwordx4 v179, s[82:83] offset:3072
	v_add_u32_e32 v178, 0x80, v178
	v_add_u32_e32 v179, 0x80, v179
	ds_read_b128 v[132:135], v230 offset:0
	ds_read_b128 v[136:139], v230 offset:4096
	ds_read_b128 v[140:143], v234 offset:0
	ds_read_b128 v[144:147], v234 offset:4096
	ds_read_b128 v[148:151], v234 offset:16384
	ds_read_b128 v[180:183], v234 offset:20480
	s_waitcnt lgkmcnt(6)
	v_mfma_f32_32x32x16_bf16 v[4:19], v[212:215], v[184:187], v[4:19]
	v_mfma_f32_32x32x16_bf16 v[68:83], v[212:215], v[208:211], v[68:83]
	v_mfma_f32_32x32x16_bf16 v[20:35], v[216:219], v[184:187], v[20:35]
	v_mfma_f32_32x32x16_bf16 v[84:99], v[216:219], v[208:211], v[84:99]
	v_mfma_f32_32x32x16_bf16 v[36:51], v[220:223], v[184:187], v[36:51]
	v_mfma_f32_32x32x16_bf16 v[100:115], v[220:223], v[208:211], v[100:115]
	v_mfma_f32_32x32x16_bf16 v[52:67], v[224:227], v[184:187], v[52:67]
	v_mfma_f32_32x32x16_bf16 v[116:131], v[224:227], v[208:211], v[116:131]
	ds_read_b128 v[184:187], v231 offset:0
	ds_read_b128 v[208:211], v231 offset:4096
	ds_read_b128 v[212:215], v235 offset:0
	ds_read_b128 v[216:219], v235 offset:4096
	ds_read_b128 v[220:223], v235 offset:16384
	ds_read_b128 v[224:227], v235 offset:20480
	s_waitcnt lgkmcnt(6)
	v_mfma_f32_32x32x16_bf16 v[4:19], v[140:143], v[132:135], v[4:19]
	v_mfma_f32_32x32x16_bf16 v[68:83], v[140:143], v[136:139], v[68:83]
	v_mfma_f32_32x32x16_bf16 v[20:35], v[144:147], v[132:135], v[20:35]
	v_mfma_f32_32x32x16_bf16 v[84:99], v[144:147], v[136:139], v[84:99]
	v_mfma_f32_32x32x16_bf16 v[36:51], v[148:151], v[132:135], v[36:51]
	v_mfma_f32_32x32x16_bf16 v[100:115], v[148:151], v[136:139], v[100:115]
	v_mfma_f32_32x32x16_bf16 v[52:67], v[180:183], v[132:135], v[52:67]
	v_mfma_f32_32x32x16_bf16 v[116:131], v[180:183], v[136:139], v[116:131]
	s_waitcnt lgkmcnt(0)
	v_mfma_f32_32x32x16_bf16 v[4:19], v[212:215], v[184:187], v[4:19]
	v_mfma_f32_32x32x16_bf16 v[68:83], v[212:215], v[208:211], v[68:83]
	v_mfma_f32_32x32x16_bf16 v[20:35], v[216:219], v[184:187], v[20:35]
	v_mfma_f32_32x32x16_bf16 v[84:99], v[216:219], v[208:211], v[84:99]
	v_mfma_f32_32x32x16_bf16 v[36:51], v[220:223], v[184:187], v[36:51]
	v_mfma_f32_32x32x16_bf16 v[100:115], v[220:223], v[208:211], v[100:115]
	v_mfma_f32_32x32x16_bf16 v[52:67], v[224:227], v[184:187], v[52:67]
	v_mfma_f32_32x32x16_bf16 v[116:131], v[224:227], v[208:211], v[116:131]
	s_waitcnt vmcnt(0) lgkmcnt(0)
	s_barrier
; #define MFMA32(a, b, c) __builtin_amdgcn_mfma_f32_32x32x16_bf16((a), (b), (c), 0, 0, 0)
; template <bool SWAP, class Epi>
; DI void gemm_tile(const u16* __restrict__ A, int lda, const u16* __restrict__ Bw, int ldb, int K, char* lds, Epi epi) {
;     ...
;   auto compute = [&](int st) {
;     const char* as = lds + st * GEMM_STAGE;
;     const char* bs = as + 36864;
; #pragma unroll
;     for (int ks = 0; ks < 4; ++ks) {
;       bf16x8 af[2], bfr[2];
; #pragma unroll
;       for (int mi = 0; mi < 2; ++mi) af[mi] = *(const bf16x8*)(as + ((wm * 64 + mi * 32 + r) * 72 + ks * 16 + 8 * h) * 2);
; #pragma unroll
;       for (int ni = 0; ni < 2; ++ni) bfr[ni] = *(const bf16x8*)(bs + ((wn * 64 + ni * 32 + r) * 72 + ks * 16 + 8 * h) * 2);
; #pragma unroll
;       for (int mi = 0; mi < 2; ++mi)
; #pragma unroll
;         for (int ni = 0; ni < 2; ++ni) {
;           if (SWAP) acc[mi][ni] = MFMA32(bfr[ni], af[mi], acc[mi][ni]);
;           else acc[mi][ni] = MFMA32(af[mi], bfr[ni], acc[mi][ni]);
;         }
;     }
;   };
;   gload(0, ra0, rb0);
;   lstore(0, ra0, rb0);
;   gload(1, ra1, rb1);
;   __syncthreads();
;   for (int kt = 0; kt < nk; kt += 2) {
;     if (kt + 2 < nk) gload(kt + 2, ra0, rb0);
;     compute(0);
;     lstore(1, ra1, rb1);
;     __syncthreads();
;     if (kt + 3 < nk) gload(kt + 3, ra1, rb1);
;     compute(1);
;     if (kt + 2 < nk) lstore(0, ra0, rb0);
;     __syncthreads();
	ds_read_b128 v[132:135], v228 offset:32768
	ds_read_b128 v[136:139], v228 offset:36864
	ds_read_b128 v[140:143], v232 offset:32768
	ds_read_b128 v[144:147], v232 offset:36864
	ds_read_b128 v[148:151], v232 offset:49152
	ds_read_b128 v[180:183], v232 offset:53248
	s_mov_b32 m0, s44
	s_nop 0
	global_load_lds_dwordx4 v178, s[68:69]
	global_load_lds_dwordx4 v179, s[70:71] offset:1024
	global_load_lds_dwordx4 v178, s[72:73] offset:2048
	global_load_lds_dwordx4 v179, s[74:75] offset:3072
	ds_read_b128 v[184:187], v229 offset:32768
	ds_read_b128 v[208:211], v229 offset:36864
	ds_read_b128 v[212:215], v233 offset:32768
	ds_read_b128 v[216:219], v233 offset:36864
	ds_read_b128 v[220:223], v233 offset:49152
	ds_read_b128 v[224:227], v233 offset:53248
	s_waitcnt lgkmcnt(6)
	v_mfma_f32_32x32x16_bf16 v[4:19], v[140:143], v[132:135], v[4:19]
	v_mfma_f32_32x32x16_bf16 v[68:83], v[140:143], v[136:139], v[68:83]
	v_mfma_f32_32x32x16_bf16 v[20:35], v[144:147], v[132:135], v[20:35]
	v_mfma_f32_32x32x16_bf16 v[84:99], v[144:147], v[136:139], v[84:99]
	v_mfma_f32_32x32x16_bf16 v[36:51], v[148:151], v[132:135], v[36:51]
	v_mfma_f32_32x32x16_bf16 v[100:115], v[148:151], v[136:139], v[100:115]
	v_mfma_f32_32x32x16_bf16 v[52:67], v[180:183], v[132:135], v[52:67]
	v_mfma_f32_32x32x16_bf16 v[116:131], v[180:183], v[136:139], v[116:131]
	s_mov_b32 m0, s46
	s_nop 0
	global_load_lds_dwordx4 v178, s[76:77]
	global_load_lds_dwordx4 v179, s[78:79] offset:1024
	global_load_lds_dwordx4 v178, s[80:81] offset:2048
	global_load_lds_dwordx4 v179, s[82:83] offset:3072
	v_add_u32_e32 v178, 0x80, v178
	v_add_u32_e32 v179, 0x80, v179
	ds_read_b128 v[132:135], v230 offset:32768
	ds_read_b128 v[136:139], v230 offset:36864
	ds_read_b128 v[140:143], v234 offset:32768
	ds_read_b128 v[144:147], v234 offset:36864
	ds_read_b128 v[148:151], v234 offset:49152
	ds_read_b128 v[180:183], v234 offset:53248
	s_waitcnt lgkmcnt(6)
	v_mfma_f32_32x32x16_bf16 v[4:19], v[212:215], v[184:187], v[4:19]
	v_mfma_f32_32x32x16_bf16 v[68:83], v[212:215], v[208:211], v[68:83]
	v_mfma_f32_32x32x16_bf16 v[20:35], v[216:219], v[184:187], v[20:35]
	v_mfma_f32_32x32x16_bf16 v[84:99], v[216:219], v[208:211], v[84:99]
	v_mfma_f32_32x32x16_bf16 v[36:51], v[220:223], v[184:187], v[36:51]
	v_mfma_f32_32x32x16_bf16 v[100:115], v[220:223], v[208:211], v[100:115]
	v_mfma_f32_32x32x16_bf16 v[52:67], v[224:227], v[184:187], v[52:67]
	v_mfma_f32_32x32x16_bf16 v[116:131], v[224:227], v[208:211], v[116:131]
	ds_read_b128 v[184:187], v231 offset:32768
	ds_read_b128 v[208:211], v231 offset:36864
	ds_read_b128 v[212:215], v235 offset:32768
	ds_read_b128 v[216:219], v235 offset:36864
	ds_read_b128 v[220:223], v235 offset:49152
	ds_read_b128 v[224:227], v235 offset:53248
	s_waitcnt lgkmcnt(6)
	v_mfma_f32_32x32x16_bf16 v[4:19], v[140:143], v[132:135], v[4:19]
	v_mfma_f32_32x32x16_bf16 v[68:83], v[140:143], v[136:139], v[68:83]
	v_mfma_f32_32x32x16_bf16 v[20:35], v[144:147], v[132:135], v[20:35]
	v_mfma_f32_32x32x16_bf16 v[84:99], v[144:147], v[136:139], v[84:99]
	v_mfma_f32_32x32x16_bf16 v[36:51], v[148:151], v[132:135], v[36:51]
	v_mfma_f32_32x32x16_bf16 v[100:115], v[148:151], v[136:139], v[100:115]
	v_mfma_f32_32x32x16_bf16 v[52:67], v[180:183], v[132:135], v[52:67]
	v_mfma_f32_32x32x16_bf16 v[116:131], v[180:183], v[136:139], v[116:131]
	s_waitcnt lgkmcnt(0)
	v_mfma_f32_32x32x16_bf16 v[4:19], v[212:215], v[184:187], v[4:19]
	v_mfma_f32_32x32x16_bf16 v[68:83], v[212:215], v[208:211], v[68:83]
	v_mfma_f32_32x32x16_bf16 v[20:35], v[216:219], v[184:187], v[20:35]
	v_mfma_f32_32x32x16_bf16 v[84:99], v[216:219], v[208:211], v[84:99]
	v_mfma_f32_32x32x16_bf16 v[36:51], v[220:223], v[184:187], v[36:51]
	v_mfma_f32_32x32x16_bf16 v[100:115], v[220:223], v[208:211], v[100:115]
	v_mfma_f32_32x32x16_bf16 v[52:67], v[224:227], v[184:187], v[52:67]
	v_mfma_f32_32x32x16_bf16 v[116:131], v[224:227], v[208:211], v[116:131]
	s_waitcnt vmcnt(0) lgkmcnt(0)
	s_barrier
	ds_read_b128 v[132:135], v228 offset:0
	ds_read_b128 v[136:139], v228 offset:4096
	ds_read_b128 v[140:143], v232 offset:0
	ds_read_b128 v[144:147], v232 offset:4096
	ds_read_b128 v[148:151], v232 offset:16384
	ds_read_b128 v[180:183], v232 offset:20480
	s_mov_b32 m0, s45
	s_nop 0
	global_load_lds_dwordx4 v178, s[68:69]
	global_load_lds_dwordx4 v179, s[70:71] offset:1024
	global_load_lds_dwordx4 v178, s[72:73] offset:2048
	global_load_lds_dwordx4 v179, s[74:75] offset:3072
	ds_read_b128 v[184:187], v229 offset:0
	ds_read_b128 v[208:211], v229 offset:4096
	ds_read_b128 v[212:215], v233 offset:0
	ds_read_b128 v[216:219], v233 offset:4096
	ds_read_b128 v[220:223], v233 offset:16384
	ds_read_b128 v[224:227], v233 offset:20480
	s_waitcnt lgkmcnt(6)
	v_mfma_f32_32x32x16_bf16 v[4:19], v[140:143], v[132:135], v[4:19]
	v_mfma_f32_32x32x16_bf16 v[68:83], v[140:143], v[136:139], v[68:83]
	v_mfma_f32_32x32x16_bf16 v[20:35], v[144:147], v[132:135], v[20:35]
	v_mfma_f32_32x32x16_bf16 v[84:99], v[144:147], v[136:139], v[84:99]
	v_mfma_f32_32x32x16_bf16 v[36:51], v[148:151], v[132:135], v[36:51]
	v_mfma_f32_32x32x16_bf16 v[100:115], v[148:151], v[136:139], v[100:115]
	v_mfma_f32_32x32x16_bf16 v[52:67], v[180:183], v[132:135], v[52:67]
	v_mfma_f32_32x32x16_bf16 v[116:131], v[180:183], v[136:139], v[116:131]
	s_mov_b32 m0, s47
	s_nop 0
	global_load_lds_dwordx4 v178, s[76:77]
	global_load_lds_dwordx4 v179, s[78:79] offset:1024
	global_load_lds_dwordx4 v178, s[80:81] offset:2048
	global_load_lds_dwordx4 v179, s[82:83] offset:3072
	v_add_u32_e32 v178, 0x80, v178
	v_add_u32_e32 v179, 0x80, v179
	ds_read_b128 v[132:135], v230 offset:0
	ds_read_b128 v[136:139], v230 offset:4096
	ds_read_b128 v[140:143], v234 offset:0
	ds_read_b128 v[144:147], v234 offset:4096
	ds_read_b128 v[148:151], v234 offset:16384
	ds_read_b128 v[180:183], v234 offset:20480
	s_waitcnt lgkmcnt(6)
; #define MFMA32(a, b, c) __builtin_amdgcn_mfma_f32_32x32x16_bf16((a), (b), (c), 0, 0, 0)
; template <bool SWAP, class Epi>
; DI void gemm_tile(const u16* __restrict__ A, int lda, const u16* __restrict__ Bw, int ldb, int K, char* lds, Epi epi) {
;     ...
;   auto compute = [&](int st) {
;     const char* as = lds + st * GEMM_STAGE;
;     const char* bs = as + 36864;
; #pragma unroll
;     for (int ks = 0; ks < 4; ++ks) {
;       bf16x8 af[2], bfr[2];
; #pragma unroll
;       for (int mi = 0; mi < 2; ++mi) af[mi] = *(const bf16x8*)(as + ((wm * 64 + mi * 32 + r) * 72 + ks * 16 + 8 * h) * 2);
; #pragma unroll
;       for (int ni = 0; ni < 2; ++ni) bfr[ni] = *(const bf16x8*)(bs + ((wn * 64 + ni * 32 + r) * 72 + ks * 16 + 8 * h) * 2);
; #pragma unroll
;       for (int mi = 0; mi < 2; ++mi)
; #pragma unroll
;         for (int ni = 0; ni < 2; ++ni) {
;           if (SWAP) acc[mi][ni] = MFMA32(bfr[ni], af[mi], acc[mi][ni]);
;           else acc[mi][ni] = MFMA32(af[mi], bfr[ni], acc[mi][ni]);
;         }
;     }
;   };
;   gload(0, ra0, rb0);
;   lstore(0, ra0, rb0);
;   gload(1, ra1, rb1);
;   __syncthreads();
;   for (int kt = 0; kt < nk; kt += 2) {
;     if (kt + 2 < nk) gload(kt + 2, ra0, rb0);
;     compute(0);
;     lstore(1, ra1, rb1);
;     __syncthreads();
;     if (kt + 3 < nk) gload(kt + 3, ra1, rb1);
;     compute(1);
;     if (kt + 2 < nk) lstore(0, ra0, rb0);
;     __syncthreads();
	v_mfma_f32_32x32x16_bf16 v[4:19], v[212:215], v[184:187], v[4:19]
	v_mfma_f32_32x32x16_bf16 v[68:83], v[212:215], v[208:211], v[68:83]
	v_mfma_f32_32x32x16_bf16 v[20:35], v[216:219], v[184:187], v[20:35]
	v_mfma_f32_32x32x16_bf16 v[84:99], v[216:219], v[208:211], v[84:99]
	v_mfma_f32_32x32x16_bf16 v[36:51], v[220:223], v[184:187], v[36:51]
	v_mfma_f32_32x32x16_bf16 v[100:115], v[220:223], v[208:211], v[100:115]
	v_mfma_f32_32x32x16_bf16 v[52:67], v[224:227], v[184:187], v[52:67]
	v_mfma_f32_32x32x16_bf16 v[116:131], v[224:227], v[208:211], v[116:131]
	ds_read_b128 v[184:187], v231 offset:0
	ds_read_b128 v[208:211], v231 offset:4096
	ds_read_b128 v[212:215], v235 offset:0
	ds_read_b128 v[216:219], v235 offset:4096
	ds_read_b128 v[220:223], v235 offset:16384
	ds_read_b128 v[224:227], v235 offset:20480
	s_waitcnt lgkmcnt(6)
	v_mfma_f32_32x32x16_bf16 v[4:19], v[140:143], v[132:135], v[4:19]
	v_mfma_f32_32x32x16_bf16 v[68:83], v[140:143], v[136:139], v[68:83]
	v_mfma_f32_32x32x16_bf16 v[20:35], v[144:147], v[132:135], v[20:35]
	v_mfma_f32_32x32x16_bf16 v[84:99], v[144:147], v[136:139], v[84:99]
	v_mfma_f32_32x32x16_bf16 v[36:51], v[148:151], v[132:135], v[36:51]
	v_mfma_f32_32x32x16_bf16 v[100:115], v[148:151], v[136:139], v[100:115]
	v_mfma_f32_32x32x16_bf16 v[52:67], v[180:183], v[132:135], v[52:67]
	v_mfma_f32_32x32x16_bf16 v[116:131], v[180:183], v[136:139], v[116:131]
	s_waitcnt lgkmcnt(0)
	v_mfma_f32_32x32x16_bf16 v[4:19], v[212:215], v[184:187], v[4:19]
	v_mfma_f32_32x32x16_bf16 v[68:83], v[212:215], v[208:211], v[68:83]
	v_mfma_f32_32x32x16_bf16 v[20:35], v[216:219], v[184:187], v[20:35]
	v_mfma_f32_32x32x16_bf16 v[84:99], v[216:219], v[208:211], v[84:99]
	v_mfma_f32_32x32x16_bf16 v[36:51], v[220:223], v[184:187], v[36:51]
	v_mfma_f32_32x32x16_bf16 v[100:115], v[220:223], v[208:211], v[100:115]
	v_mfma_f32_32x32x16_bf16 v[52:67], v[224:227], v[184:187], v[52:67]
	v_mfma_f32_32x32x16_bf16 v[116:131], v[224:227], v[208:211], v[116:131]
	s_waitcnt vmcnt(0) lgkmcnt(0)
	s_barrier
	ds_read_b128 v[132:135], v228 offset:32768
	ds_read_b128 v[136:139], v228 offset:36864
	ds_read_b128 v[140:143], v232 offset:32768
	ds_read_b128 v[144:147], v232 offset:36864
	ds_read_b128 v[148:151], v232 offset:49152
	ds_read_b128 v[180:183], v232 offset:53248
	s_mov_b32 m0, s44
	s_nop 0
	global_load_lds_dwordx4 v178, s[68:69]
	global_load_lds_dwordx4 v179, s[70:71] offset:1024
	global_load_lds_dwordx4 v178, s[72:73] offset:2048
	global_load_lds_dwordx4 v179, s[74:75] offset:3072
	ds_read_b128 v[184:187], v229 offset:32768
	ds_read_b128 v[208:211], v229 offset:36864
	ds_read_b128 v[212:215], v233 offset:32768
	ds_read_b128 v[216:219], v233 offset:36864
	ds_read_b128 v[220:223], v233 offset:49152
	ds_read_b128 v[224:227], v233 offset:53248
	s_waitcnt lgkmcnt(6)
	v_mfma_f32_32x32x16_bf16 v[4:19], v[140:143], v[132:135], v[4:19]
	v_mfma_f32_32x32x16_bf16 v[68:83], v[140:143], v[136:139], v[68:83]
	v_mfma_f32_32x32x16_bf16 v[20:35], v[144:147], v[132:135], v[20:35]
	v_mfma_f32_32x32x16_bf16 v[84:99], v[144:147], v[136:139], v[84:99]
	v_mfma_f32_32x32x16_bf16 v[36:51], v[148:151], v[132:135], v[36:51]
	v_mfma_f32_32x32x16_bf16 v[100:115], v[148:151], v[136:139], v[100:115]
	v_mfma_f32_32x32x16_bf16 v[52:67], v[180:183], v[132:135], v[52:67]
	v_mfma_f32_32x32x16_bf16 v[116:131], v[180:183], v[136:139], v[116:131]
	s_mov_b32 m0, s46
	s_nop 0
	global_load_lds_dwordx4 v178, s[76:77]
	global_load_lds_dwordx4 v179, s[78:79] offset:1024
	global_load_lds_dwordx4 v178, s[80:81] offset:2048
	global_load_lds_dwordx4 v179, s[82:83] offset:3072
	v_add_u32_e32 v178, 0x80, v178
	v_add_u32_e32 v179, 0x80, v179
	ds_read_b128 v[132:135], v230 offset:32768
	ds_read_b128 v[136:139], v230 offset:36864
	ds_read_b128 v[140:143], v234 offset:32768
	ds_read_b128 v[144:147], v234 offset:36864
	ds_read_b128 v[148:151], v234 offset:49152
	ds_read_b128 v[180:183], v234 offset:53248
	s_waitcnt lgkmcnt(6)
	v_mfma_f32_32x32x16_bf16 v[4:19], v[212:215], v[184:187], v[4:19]
	v_mfma_f32_32x32x16_bf16 v[68:83], v[212:215], v[208:211], v[68:83]
	v_mfma_f32_32x32x16_bf16 v[20:35], v[216:219], v[184:187], v[20:35]
	v_mfma_f32_32x32x16_bf16 v[84:99], v[216:219], v[208:211], v[84:99]
	v_mfma_f32_32x32x16_bf16 v[36:51], v[220:223], v[184:187], v[36:51]
	v_mfma_f32_32x32x16_bf16 v[100:115], v[220:223], v[208:211], v[100:115]
	v_mfma_f32_32x32x16_bf16 v[52:67], v[224:227], v[184:187], v[52:67]
	v_mfma_f32_32x32x16_bf16 v[116:131], v[224:227], v[208:211], v[116:131]
	ds_read_b128 v[184:187], v231 offset:32768
	ds_read_b128 v[208:211], v231 offset:36864
	ds_read_b128 v[212:215], v235 offset:32768
	ds_read_b128 v[216:219], v235 offset:36864
	ds_read_b128 v[220:223], v235 offset:49152
	ds_read_b128 v[224:227], v235 offset:53248
	s_waitcnt lgkmcnt(6)
	v_mfma_f32_32x32x16_bf16 v[4:19], v[140:143], v[132:135], v[4:19]
	v_mfma_f32_32x32x16_bf16 v[68:83], v[140:143], v[136:139], v[68:83]
	v_mfma_f32_32x32x16_bf16 v[20:35], v[144:147], v[132:135], v[20:35]
	v_mfma_f32_32x32x16_bf16 v[84:99], v[144:147], v[136:139], v[84:99]
	v_mfma_f32_32x32x16_bf16 v[36:51], v[148:151], v[132:135], v[36:51]
	v_mfma_f32_32x32x16_bf16 v[100:115], v[148:151], v[136:139], v[100:115]
	v_mfma_f32_32x32x16_bf16 v[52:67], v[180:183], v[132:135], v[52:67]
	v_mfma_f32_32x32x16_bf16 v[116:131], v[180:183], v[136:139], v[116:131]
	s_waitcnt lgkmcnt(0)
	v_mfma_f32_32x32x16_bf16 v[4:19], v[212:215], v[184:187], v[4:19]
	v_mfma_f32_32x32x16_bf16 v[68:83], v[212:215], v[208:211], v[68:83]
	v_mfma_f32_32x32x16_bf16 v[20:35], v[216:219], v[184:187], v[20:35]
	v_mfma_f32_32x32x16_bf16 v[84:99], v[216:219], v[208:211], v[84:99]
	v_mfma_f32_32x32x16_bf16 v[36:51], v[220:223], v[184:187], v[36:51]
	v_mfma_f32_32x32x16_bf16 v[100:115], v[220:223], v[208:211], v[100:115]
	v_mfma_f32_32x32x16_bf16 v[52:67], v[224:227], v[184:187], v[52:67]
	v_mfma_f32_32x32x16_bf16 v[116:131], v[224:227], v[208:211], v[116:131]
	s_waitcnt vmcnt(0) lgkmcnt(0)
	s_barrier
; #define MFMA32(a, b, c) __builtin_amdgcn_mfma_f32_32x32x16_bf16((a), (b), (c), 0, 0, 0)
; template <bool SWAP, class Epi>
; DI void gemm_tile(const u16* __restrict__ A, int lda, const u16* __restrict__ Bw, int ldb, int K, char* lds, Epi epi) {
;     ...
;   auto compute = [&](int st) {
;     const char* as = lds + st * GEMM_STAGE;
;     const char* bs = as + 36864;
; #pragma unroll
;     for (int ks = 0; ks < 4; ++ks) {
;       bf16x8 af[2], bfr[2];
; #pragma unroll
;       for (int mi = 0; mi < 2; ++mi) af[mi] = *(const bf16x8*)(as + ((wm * 64 + mi * 32 + r) * 72 + ks * 16 + 8 * h) * 2);
; #pragma unroll
;       for (int ni = 0; ni < 2; ++ni) bfr[ni] = *(const bf16x8*)(bs + ((wn * 64 + ni * 32 + r) * 72 + ks * 16 + 8 * h) * 2);
; #pragma unroll
;       for (int mi = 0; mi < 2; ++mi)
; #pragma unroll
;         for (int ni = 0; ni < 2; ++ni) {
;           if (SWAP) acc[mi][ni] = MFMA32(bfr[ni], af[mi], acc[mi][ni]);
;           else acc[mi][ni] = MFMA32(af[mi], bfr[ni], acc[mi][ni]);
;         }
;     }
;   };
;   gload(0, ra0, rb0);
;   lstore(0, ra0, rb0);
;   gload(1, ra1, rb1);
;   __syncthreads();
;   for (int kt = 0; kt < nk; kt += 2) {
;     if (kt + 2 < nk) gload(kt + 2, ra0, rb0);
;     compute(0);
;     lstore(1, ra1, rb1);
;     __syncthreads();
;     if (kt + 3 < nk) gload(kt + 3, ra1, rb1);
;     compute(1);
;     if (kt + 2 < nk) lstore(0, ra0, rb0);
;     __syncthreads();
	ds_read_b128 v[132:135], v228 offset:0
	ds_read_b128 v[136:139], v228 offset:4096
	ds_read_b128 v[140:143], v232 offset:0
	ds_read_b128 v[144:147], v232 offset:4096
	ds_read_b128 v[148:151], v232 offset:16384
	ds_read_b128 v[180:183], v232 offset:20480
	s_mov_b32 m0, s45
	s_nop 0
	global_load_lds_dwordx4 v178, s[68:69]
	global_load_lds_dwordx4 v179, s[70:71] offset:1024
	global_load_lds_dwordx4 v178, s[72:73] offset:2048
	global_load_lds_dwordx4 v179, s[74:75] offset:3072
	ds_read_b128 v[184:187], v229 offset:0
	ds_read_b128 v[208:211], v229 offset:4096
	ds_read_b128 v[212:215], v233 offset:0
	ds_read_b128 v[216:219], v233 offset:4096
	ds_read_b128 v[220:223], v233 offset:16384
	ds_read_b128 v[224:227], v233 offset:20480
	s_waitcnt lgkmcnt(6)
	v_mfma_f32_32x32x16_bf16 v[4:19], v[140:143], v[132:135], v[4:19]
	v_mfma_f32_32x32x16_bf16 v[68:83], v[140:143], v[136:139], v[68:83]
	v_mfma_f32_32x32x16_bf16 v[20:35], v[144:147], v[132:135], v[20:35]
	v_mfma_f32_32x32x16_bf16 v[84:99], v[144:147], v[136:139], v[84:99]
	v_mfma_f32_32x32x16_bf16 v[36:51], v[148:151], v[132:135], v[36:51]
	v_mfma_f32_32x32x16_bf16 v[100:115], v[148:151], v[136:139], v[100:115]
	v_mfma_f32_32x32x16_bf16 v[52:67], v[180:183], v[132:135], v[52:67]
	v_mfma_f32_32x32x16_bf16 v[116:131], v[180:183], v[136:139], v[116:131]
	s_mov_b32 m0, s47
	s_nop 0
	global_load_lds_dwordx4 v178, s[76:77]
	global_load_lds_dwordx4 v179, s[78:79] offset:1024
	global_load_lds_dwordx4 v178, s[80:81] offset:2048
	global_load_lds_dwordx4 v179, s[82:83] offset:3072
	v_add_u32_e32 v178, 0x80, v178
	v_add_u32_e32 v179, 0x80, v179
	ds_read_b128 v[132:135], v230 offset:0
	ds_read_b128 v[136:139], v230 offset:4096
	ds_read_b128 v[140:143], v234 offset:0
	ds_read_b128 v[144:147], v234 offset:4096
	ds_read_b128 v[148:151], v234 offset:16384
	ds_read_b128 v[180:183], v234 offset:20480
	s_waitcnt lgkmcnt(6)
	v_mfma_f32_32x32x16_bf16 v[4:19], v[212:215], v[184:187], v[4:19]
	v_mfma_f32_32x32x16_bf16 v[68:83], v[212:215], v[208:211], v[68:83]
	v_mfma_f32_32x32x16_bf16 v[20:35], v[216:219], v[184:187], v[20:35]
	v_mfma_f32_32x32x16_bf16 v[84:99], v[216:219], v[208:211], v[84:99]
	v_mfma_f32_32x32x16_bf16 v[36:51], v[220:223], v[184:187], v[36:51]
	v_mfma_f32_32x32x16_bf16 v[100:115], v[220:223], v[208:211], v[100:115]
	v_mfma_f32_32x32x16_bf16 v[52:67], v[224:227], v[184:187], v[52:67]
	v_mfma_f32_32x32x16_bf16 v[116:131], v[224:227], v[208:211], v[116:131]
	ds_read_b128 v[184:187], v231 offset:0
	ds_read_b128 v[208:211], v231 offset:4096
	ds_read_b128 v[212:215], v235 offset:0
	ds_read_b128 v[216:219], v235 offset:4096
	ds_read_b128 v[220:223], v235 offset:16384
	ds_read_b128 v[224:227], v235 offset:20480
	s_waitcnt lgkmcnt(6)
	v_mfma_f32_32x32x16_bf16 v[4:19], v[140:143], v[132:135], v[4:19]
	v_mfma_f32_32x32x16_bf16 v[68:83], v[140:143], v[136:139], v[68:83]
	v_mfma_f32_32x32x16_bf16 v[20:35], v[144:147], v[132:135], v[20:35]
	v_mfma_f32_32x32x16_bf16 v[84:99], v[144:147], v[136:139], v[84:99]
	v_mfma_f32_32x32x16_bf16 v[36:51], v[148:151], v[132:135], v[36:51]
	v_mfma_f32_32x32x16_bf16 v[100:115], v[148:151], v[136:139], v[100:115]
	v_mfma_f32_32x32x16_bf16 v[52:67], v[180:183], v[132:135], v[52:67]
	v_mfma_f32_32x32x16_bf16 v[116:131], v[180:183], v[136:139], v[116:131]
	s_waitcnt lgkmcnt(0)
	v_mfma_f32_32x32x16_bf16 v[4:19], v[212:215], v[184:187], v[4:19]
	v_mfma_f32_32x32x16_bf16 v[68:83], v[212:215], v[208:211], v[68:83]
	v_mfma_f32_32x32x16_bf16 v[20:35], v[216:219], v[184:187], v[20:35]
	v_mfma_f32_32x32x16_bf16 v[84:99], v[216:219], v[208:211], v[84:99]
	v_mfma_f32_32x32x16_bf16 v[36:51], v[220:223], v[184:187], v[36:51]
	v_mfma_f32_32x32x16_bf16 v[100:115], v[220:223], v[208:211], v[100:115]
	v_mfma_f32_32x32x16_bf16 v[52:67], v[224:227], v[184:187], v[52:67]
	v_mfma_f32_32x32x16_bf16 v[116:131], v[224:227], v[208:211], v[116:131]
	s_waitcnt vmcnt(0) lgkmcnt(0)
	s_barrier
	ds_read_b128 v[132:135], v228 offset:32768
	ds_read_b128 v[136:139], v228 offset:36864
	ds_read_b128 v[140:143], v232 offset:32768
	ds_read_b128 v[144:147], v232 offset:36864
	ds_read_b128 v[148:151], v232 offset:49152
	ds_read_b128 v[180:183], v232 offset:53248
	s_mov_b32 m0, s44
	s_nop 0
	global_load_lds_dwordx4 v178, s[68:69]
	global_load_lds_dwordx4 v179, s[70:71] offset:1024
	global_load_lds_dwordx4 v178, s[72:73] offset:2048
	global_load_lds_dwordx4 v179, s[74:75] offset:3072
	ds_read_b128 v[184:187], v229 offset:32768
	ds_read_b128 v[208:211], v229 offset:36864
	ds_read_b128 v[212:215], v233 offset:32768
	ds_read_b128 v[216:219], v233 offset:36864
	ds_read_b128 v[220:223], v233 offset:49152
	ds_read_b128 v[224:227], v233 offset:53248
	s_waitcnt lgkmcnt(6)
	v_mfma_f32_32x32x16_bf16 v[4:19], v[140:143], v[132:135], v[4:19]
	v_mfma_f32_32x32x16_bf16 v[68:83], v[140:143], v[136:139], v[68:83]
	v_mfma_f32_32x32x16_bf16 v[20:35], v[144:147], v[132:135], v[20:35]
	v_mfma_f32_32x32x16_bf16 v[84:99], v[144:147], v[136:139], v[84:99]
	v_mfma_f32_32x32x16_bf16 v[36:51], v[148:151], v[132:135], v[36:51]
	v_mfma_f32_32x32x16_bf16 v[100:115], v[148:151], v[136:139], v[100:115]
	v_mfma_f32_32x32x16_bf16 v[52:67], v[180:183], v[132:135], v[52:67]
	v_mfma_f32_32x32x16_bf16 v[116:131], v[180:183], v[136:139], v[116:131]
	s_mov_b32 m0, s46
	s_nop 0
	global_load_lds_dwordx4 v178, s[76:77]
	global_load_lds_dwordx4 v179, s[78:79] offset:1024
	global_load_lds_dwordx4 v178, s[80:81] offset:2048
	global_load_lds_dwordx4 v179, s[82:83] offset:3072
	v_add_u32_e32 v178, 0x80, v178
	v_add_u32_e32 v179, 0x80, v179
	ds_read_b128 v[132:135], v230 offset:32768
	ds_read_b128 v[136:139], v230 offset:36864
	ds_read_b128 v[140:143], v234 offset:32768
	ds_read_b128 v[144:147], v234 offset:36864
	ds_read_b128 v[148:151], v234 offset:49152
	ds_read_b128 v[180:183], v234 offset:53248
	s_waitcnt lgkmcnt(6)
; #define MFMA32(a, b, c) __builtin_amdgcn_mfma_f32_32x32x16_bf16((a), (b), (c), 0, 0, 0)
; template <bool SWAP, class Epi>
; DI void gemm_tile(const u16* __restrict__ A, int lda, const u16* __restrict__ Bw, int ldb, int K, char* lds, Epi epi) {
;     ...
;   auto compute = [&](int st) {
;     const char* as = lds + st * GEMM_STAGE;
;     const char* bs = as + 36864;
; #pragma unroll
;     for (int ks = 0; ks < 4; ++ks) {
;       bf16x8 af[2], bfr[2];
; #pragma unroll
;       for (int mi = 0; mi < 2; ++mi) af[mi] = *(const bf16x8*)(as + ((wm * 64 + mi * 32 + r) * 72 + ks * 16 + 8 * h) * 2);
; #pragma unroll
;       for (int ni = 0; ni < 2; ++ni) bfr[ni] = *(const bf16x8*)(bs + ((wn * 64 + ni * 32 + r) * 72 + ks * 16 + 8 * h) * 2);
; #pragma unroll
;       for (int mi = 0; mi < 2; ++mi)
; #pragma unroll
;         for (int ni = 0; ni < 2; ++ni) {
;           if (SWAP) acc[mi][ni] = MFMA32(bfr[ni], af[mi], acc[mi][ni]);
;           else acc[mi][ni] = MFMA32(af[mi], bfr[ni], acc[mi][ni]);
;         }
;     }
;   };
;   gload(0, ra0, rb0);
;   lstore(0, ra0, rb0);
;   gload(1, ra1, rb1);
;   __syncthreads();
;   for (int kt = 0; kt < nk; kt += 2) {
;     if (kt + 2 < nk) gload(kt + 2, ra0, rb0);
;     compute(0);
;     lstore(1, ra1, rb1);
;     __syncthreads();
;     if (kt + 3 < nk) gload(kt + 3, ra1, rb1);
;     compute(1);
;     if (kt + 2 < nk) lstore(0, ra0, rb0);
;     __syncthreads();
	v_mfma_f32_32x32x16_bf16 v[4:19], v[212:215], v[184:187], v[4:19]
	v_mfma_f32_32x32x16_bf16 v[68:83], v[212:215], v[208:211], v[68:83]
	v_mfma_f32_32x32x16_bf16 v[20:35], v[216:219], v[184:187], v[20:35]
	v_mfma_f32_32x32x16_bf16 v[84:99], v[216:219], v[208:211], v[84:99]
	v_mfma_f32_32x32x16_bf16 v[36:51], v[220:223], v[184:187], v[36:51]
	v_mfma_f32_32x32x16_bf16 v[100:115], v[220:223], v[208:211], v[100:115]
	v_mfma_f32_32x32x16_bf16 v[52:67], v[224:227], v[184:187], v[52:67]
	v_mfma_f32_32x32x16_bf16 v[116:131], v[224:227], v[208:211], v[116:131]
	ds_read_b128 v[184:187], v231 offset:32768
	ds_read_b128 v[208:211], v231 offset:36864
	ds_read_b128 v[212:215], v235 offset:32768
	ds_read_b128 v[216:219], v235 offset:36864
	ds_read_b128 v[220:223], v235 offset:49152
	ds_read_b128 v[224:227], v235 offset:53248
	s_waitcnt lgkmcnt(6)
	v_mfma_f32_32x32x16_bf16 v[4:19], v[140:143], v[132:135], v[4:19]
	v_mfma_f32_32x32x16_bf16 v[68:83], v[140:143], v[136:139], v[68:83]
	v_mfma_f32_32x32x16_bf16 v[20:35], v[144:147], v[132:135], v[20:35]
	v_mfma_f32_32x32x16_bf16 v[84:99], v[144:147], v[136:139], v[84:99]
	v_mfma_f32_32x32x16_bf16 v[36:51], v[148:151], v[132:135], v[36:51]
	v_mfma_f32_32x32x16_bf16 v[100:115], v[148:151], v[136:139], v[100:115]
	v_mfma_f32_32x32x16_bf16 v[52:67], v[180:183], v[132:135], v[52:67]
	v_mfma_f32_32x32x16_bf16 v[116:131], v[180:183], v[136:139], v[116:131]
	s_waitcnt lgkmcnt(0)
	v_mfma_f32_32x32x16_bf16 v[4:19], v[212:215], v[184:187], v[4:19]
	v_mfma_f32_32x32x16_bf16 v[68:83], v[212:215], v[208:211], v[68:83]
	v_mfma_f32_32x32x16_bf16 v[20:35], v[216:219], v[184:187], v[20:35]
	v_mfma_f32_32x32x16_bf16 v[84:99], v[216:219], v[208:211], v[84:99]
	v_mfma_f32_32x32x16_bf16 v[36:51], v[220:223], v[184:187], v[36:51]
	v_mfma_f32_32x32x16_bf16 v[100:115], v[220:223], v[208:211], v[100:115]
	v_mfma_f32_32x32x16_bf16 v[52:67], v[224:227], v[184:187], v[52:67]
	v_mfma_f32_32x32x16_bf16 v[116:131], v[224:227], v[208:211], v[116:131]
	s_waitcnt vmcnt(0) lgkmcnt(0)
	s_barrier
	ds_read_b128 v[132:135], v228 offset:0
	ds_read_b128 v[136:139], v228 offset:4096
	ds_read_b128 v[140:143], v232 offset:0
	ds_read_b128 v[144:147], v232 offset:4096
	ds_read_b128 v[148:151], v232 offset:16384
	ds_read_b128 v[180:183], v232 offset:20480
	s_mov_b32 m0, s45
	s_nop 0
	global_load_lds_dwordx4 v178, s[68:69]
	global_load_lds_dwordx4 v179, s[70:71] offset:1024
	global_load_lds_dwordx4 v178, s[72:73] offset:2048
	global_load_lds_dwordx4 v179, s[74:75] offset:3072
	ds_read_b128 v[184:187], v229 offset:0
	ds_read_b128 v[208:211], v229 offset:4096
	ds_read_b128 v[212:215], v233 offset:0
	ds_read_b128 v[216:219], v233 offset:4096
	ds_read_b128 v[220:223], v233 offset:16384
	ds_read_b128 v[224:227], v233 offset:20480
	s_waitcnt lgkmcnt(6)
	v_mfma_f32_32x32x16_bf16 v[4:19], v[140:143], v[132:135], v[4:19]
	v_mfma_f32_32x32x16_bf16 v[68:83], v[140:143], v[136:139], v[68:83]
	v_mfma_f32_32x32x16_bf16 v[20:35], v[144:147], v[132:135], v[20:35]
	v_mfma_f32_32x32x16_bf16 v[84:99], v[144:147], v[136:139], v[84:99]
	v_mfma_f32_32x32x16_bf16 v[36:51], v[148:151], v[132:135], v[36:51]
	v_mfma_f32_32x32x16_bf16 v[100:115], v[148:151], v[136:139], v[100:115]
	v_mfma_f32_32x32x16_bf16 v[52:67], v[180:183], v[132:135], v[52:67]
	v_mfma_f32_32x32x16_bf16 v[116:131], v[180:183], v[136:139], v[116:131]
	s_mov_b32 m0, s47
	s_nop 0
	global_load_lds_dwordx4 v178, s[76:77]
	global_load_lds_dwordx4 v179, s[78:79] offset:1024
	global_load_lds_dwordx4 v178, s[80:81] offset:2048
	global_load_lds_dwordx4 v179, s[82:83] offset:3072
	v_add_u32_e32 v178, 0x80, v178
	v_add_u32_e32 v179, 0x80, v179
	ds_read_b128 v[132:135], v230 offset:0
	ds_read_b128 v[136:139], v230 offset:4096
	ds_read_b128 v[140:143], v234 offset:0
	ds_read_b128 v[144:147], v234 offset:4096
	ds_read_b128 v[148:151], v234 offset:16384
	ds_read_b128 v[180:183], v234 offset:20480
	s_waitcnt lgkmcnt(6)
	v_mfma_f32_32x32x16_bf16 v[4:19], v[212:215], v[184:187], v[4:19]
	v_mfma_f32_32x32x16_bf16 v[68:83], v[212:215], v[208:211], v[68:83]
	v_mfma_f32_32x32x16_bf16 v[20:35], v[216:219], v[184:187], v[20:35]
	v_mfma_f32_32x32x16_bf16 v[84:99], v[216:219], v[208:211], v[84:99]
	v_mfma_f32_32x32x16_bf16 v[36:51], v[220:223], v[184:187], v[36:51]
	v_mfma_f32_32x32x16_bf16 v[100:115], v[220:223], v[208:211], v[100:115]
	v_mfma_f32_32x32x16_bf16 v[52:67], v[224:227], v[184:187], v[52:67]
	v_mfma_f32_32x32x16_bf16 v[116:131], v[224:227], v[208:211], v[116:131]
	ds_read_b128 v[184:187], v231 offset:0
	ds_read_b128 v[208:211], v231 offset:4096
	ds_read_b128 v[212:215], v235 offset:0
	ds_read_b128 v[216:219], v235 offset:4096
	ds_read_b128 v[220:223], v235 offset:16384
	ds_read_b128 v[224:227], v235 offset:20480
	s_waitcnt lgkmcnt(6)
	v_mfma_f32_32x32x16_bf16 v[4:19], v[140:143], v[132:135], v[4:19]
	v_mfma_f32_32x32x16_bf16 v[68:83], v[140:143], v[136:139], v[68:83]
	v_mfma_f32_32x32x16_bf16 v[20:35], v[144:147], v[132:135], v[20:35]
	v_mfma_f32_32x32x16_bf16 v[84:99], v[144:147], v[136:139], v[84:99]
	v_mfma_f32_32x32x16_bf16 v[36:51], v[148:151], v[132:135], v[36:51]
	v_mfma_f32_32x32x16_bf16 v[100:115], v[148:151], v[136:139], v[100:115]
	v_mfma_f32_32x32x16_bf16 v[52:67], v[180:183], v[132:135], v[52:67]
	v_mfma_f32_32x32x16_bf16 v[116:131], v[180:183], v[136:139], v[116:131]
	s_waitcnt lgkmcnt(0)
	v_mfma_f32_32x32x16_bf16 v[4:19], v[212:215], v[184:187], v[4:19]
	v_mfma_f32_32x32x16_bf16 v[68:83], v[212:215], v[208:211], v[68:83]
	v_mfma_f32_32x32x16_bf16 v[20:35], v[216:219], v[184:187], v[20:35]
	v_mfma_f32_32x32x16_bf16 v[84:99], v[216:219], v[208:211], v[84:99]
	v_mfma_f32_32x32x16_bf16 v[36:51], v[220:223], v[184:187], v[36:51]
	v_mfma_f32_32x32x16_bf16 v[100:115], v[220:223], v[208:211], v[100:115]
	v_mfma_f32_32x32x16_bf16 v[52:67], v[224:227], v[184:187], v[52:67]
	v_mfma_f32_32x32x16_bf16 v[116:131], v[224:227], v[208:211], v[116:131]
	s_waitcnt vmcnt(0) lgkmcnt(0)
	s_barrier
; #define MFMA32(a, b, c) __builtin_amdgcn_mfma_f32_32x32x16_bf16((a), (b), (c), 0, 0, 0)
; template <bool SWAP, class Epi>
; DI void gemm_tile(const u16* __restrict__ A, int lda, const u16* __restrict__ Bw, int ldb, int K, char* lds, Epi epi) {
;     ...
;   auto compute = [&](int st) {
;     const char* as = lds + st * GEMM_STAGE;
;     const char* bs = as + 36864;
; #pragma unroll
;     for (int ks = 0; ks < 4; ++ks) {
;       bf16x8 af[2], bfr[2];
; #pragma unroll
;       for (int mi = 0; mi < 2; ++mi) af[mi] = *(const bf16x8*)(as + ((wm * 64 + mi * 32 + r) * 72 + ks * 16 + 8 * h) * 2);
; #pragma unroll
;       for (int ni = 0; ni < 2; ++ni) bfr[ni] = *(const bf16x8*)(bs + ((wn * 64 + ni * 32 + r) * 72 + ks * 16 + 8 * h) * 2);
; #pragma unroll
;       for (int mi = 0; mi < 2; ++mi)
; #pragma unroll
;         for (int ni = 0; ni < 2; ++ni) {
;           if (SWAP) acc[mi][ni] = MFMA32(bfr[ni], af[mi], acc[mi][ni]);
;           else acc[mi][ni] = MFMA32(af[mi], bfr[ni], acc[mi][ni]);
;         }
;     }
;   };
;   gload(0, ra0, rb0);
;   lstore(0, ra0, rb0);
;   gload(1, ra1, rb1);
;   __syncthreads();
;   for (int kt = 0; kt < nk; kt += 2) {
;     if (kt + 2 < nk) gload(kt + 2, ra0, rb0);
;     compute(0);
;     lstore(1, ra1, rb1);
;     __syncthreads();
;     if (kt + 3 < nk) gload(kt + 3, ra1, rb1);
;     compute(1);
;     if (kt + 2 < nk) lstore(0, ra0, rb0);
;     __syncthreads();
	ds_read_b128 v[132:135], v228 offset:32768
	ds_read_b128 v[136:139], v228 offset:36864
	ds_read_b128 v[140:143], v232 offset:32768
	ds_read_b128 v[144:147], v232 offset:36864
	ds_read_b128 v[148:151], v232 offset:49152
	ds_read_b128 v[180:183], v232 offset:53248
	s_mov_b32 m0, s44
	s_nop 0
	global_load_lds_dwordx4 v178, s[68:69]
	global_load_lds_dwordx4 v179, s[70:71] offset:1024
	global_load_lds_dwordx4 v178, s[72:73] offset:2048
	global_load_lds_dwordx4 v179, s[74:75] offset:3072
	ds_read_b128 v[184:187], v229 offset:32768
	ds_read_b128 v[208:211], v229 offset:36864
	ds_read_b128 v[212:215], v233 offset:32768
	ds_read_b128 v[216:219], v233 offset:36864
	ds_read_b128 v[220:223], v233 offset:49152
	ds_read_b128 v[224:227], v233 offset:53248
	s_waitcnt lgkmcnt(6)
	v_mfma_f32_32x32x16_bf16 v[4:19], v[140:143], v[132:135], v[4:19]
	v_mfma_f32_32x32x16_bf16 v[68:83], v[140:143], v[136:139], v[68:83]
	v_mfma_f32_32x32x16_bf16 v[20:35], v[144:147], v[132:135], v[20:35]
	v_mfma_f32_32x32x16_bf16 v[84:99], v[144:147], v[136:139], v[84:99]
	v_mfma_f32_32x32x16_bf16 v[36:51], v[148:151], v[132:135], v[36:51]
	v_mfma_f32_32x32x16_bf16 v[100:115], v[148:151], v[136:139], v[100:115]
	v_mfma_f32_32x32x16_bf16 v[52:67], v[180:183], v[132:135], v[52:67]
	v_mfma_f32_32x32x16_bf16 v[116:131], v[180:183], v[136:139], v[116:131]
	s_mov_b32 m0, s46
	s_nop 0
	global_load_lds_dwordx4 v178, s[76:77]
	global_load_lds_dwordx4 v179, s[78:79] offset:1024
	global_load_lds_dwordx4 v178, s[80:81] offset:2048
	global_load_lds_dwordx4 v179, s[82:83] offset:3072
	v_add_u32_e32 v178, 0x80, v178
	v_add_u32_e32 v179, 0x80, v179
	ds_read_b128 v[132:135], v230 offset:32768
	ds_read_b128 v[136:139], v230 offset:36864
	ds_read_b128 v[140:143], v234 offset:32768
	ds_read_b128 v[144:147], v234 offset:36864
	ds_read_b128 v[148:151], v234 offset:49152
	ds_read_b128 v[180:183], v234 offset:53248
	s_waitcnt lgkmcnt(6)
	v_mfma_f32_32x32x16_bf16 v[4:19], v[212:215], v[184:187], v[4:19]
	v_mfma_f32_32x32x16_bf16 v[68:83], v[212:215], v[208:211], v[68:83]
	v_mfma_f32_32x32x16_bf16 v[20:35], v[216:219], v[184:187], v[20:35]
	v_mfma_f32_32x32x16_bf16 v[84:99], v[216:219], v[208:211], v[84:99]
	v_mfma_f32_32x32x16_bf16 v[36:51], v[220:223], v[184:187], v[36:51]
	v_mfma_f32_32x32x16_bf16 v[100:115], v[220:223], v[208:211], v[100:115]
	v_mfma_f32_32x32x16_bf16 v[52:67], v[224:227], v[184:187], v[52:67]
	v_mfma_f32_32x32x16_bf16 v[116:131], v[224:227], v[208:211], v[116:131]
	ds_read_b128 v[184:187], v231 offset:32768
	ds_read_b128 v[208:211], v231 offset:36864
	ds_read_b128 v[212:215], v235 offset:32768
	ds_read_b128 v[216:219], v235 offset:36864
	ds_read_b128 v[220:223], v235 offset:49152
	ds_read_b128 v[224:227], v235 offset:53248
	s_waitcnt lgkmcnt(6)
	v_mfma_f32_32x32x16_bf16 v[4:19], v[140:143], v[132:135], v[4:19]
	v_mfma_f32_32x32x16_bf16 v[68:83], v[140:143], v[136:139], v[68:83]
	v_mfma_f32_32x32x16_bf16 v[20:35], v[144:147], v[132:135], v[20:35]
	v_mfma_f32_32x32x16_bf16 v[84:99], v[144:147], v[136:139], v[84:99]
	v_mfma_f32_32x32x16_bf16 v[36:51], v[148:151], v[132:135], v[36:51]
	v_mfma_f32_32x32x16_bf16 v[100:115], v[148:151], v[136:139], v[100:115]
	v_mfma_f32_32x32x16_bf16 v[52:67], v[180:183], v[132:135], v[52:67]
	v_mfma_f32_32x32x16_bf16 v[116:131], v[180:183], v[136:139], v[116:131]
	s_waitcnt lgkmcnt(0)
	v_mfma_f32_32x32x16_bf16 v[4:19], v[212:215], v[184:187], v[4:19]
	v_mfma_f32_32x32x16_bf16 v[68:83], v[212:215], v[208:211], v[68:83]
	v_mfma_f32_32x32x16_bf16 v[20:35], v[216:219], v[184:187], v[20:35]
	v_mfma_f32_32x32x16_bf16 v[84:99], v[216:219], v[208:211], v[84:99]
	v_mfma_f32_32x32x16_bf16 v[36:51], v[220:223], v[184:187], v[36:51]
	v_mfma_f32_32x32x16_bf16 v[100:115], v[220:223], v[208:211], v[100:115]
	v_mfma_f32_32x32x16_bf16 v[52:67], v[224:227], v[184:187], v[52:67]
	v_mfma_f32_32x32x16_bf16 v[116:131], v[224:227], v[208:211], v[116:131]
	s_waitcnt vmcnt(0) lgkmcnt(0)
	s_barrier
	ds_read_b128 v[132:135], v228 offset:0
	ds_read_b128 v[136:139], v228 offset:4096
	ds_read_b128 v[140:143], v232 offset:0
	ds_read_b128 v[144:147], v232 offset:4096
	ds_read_b128 v[148:151], v232 offset:16384
	ds_read_b128 v[180:183], v232 offset:20480
	s_mov_b32 m0, s45
	s_nop 0
	global_load_lds_dwordx4 v178, s[68:69]
	global_load_lds_dwordx4 v179, s[70:71] offset:1024
	global_load_lds_dwordx4 v178, s[72:73] offset:2048
	global_load_lds_dwordx4 v179, s[74:75] offset:3072
	ds_read_b128 v[184:187], v229 offset:0
	ds_read_b128 v[208:211], v229 offset:4096
	ds_read_b128 v[212:215], v233 offset:0
	ds_read_b128 v[216:219], v233 offset:4096
	ds_read_b128 v[220:223], v233 offset:16384
	ds_read_b128 v[224:227], v233 offset:20480
	s_waitcnt lgkmcnt(6)
	v_mfma_f32_32x32x16_bf16 v[4:19], v[140:143], v[132:135], v[4:19]
	v_mfma_f32_32x32x16_bf16 v[68:83], v[140:143], v[136:139], v[68:83]
	v_mfma_f32_32x32x16_bf16 v[20:35], v[144:147], v[132:135], v[20:35]
	v_mfma_f32_32x32x16_bf16 v[84:99], v[144:147], v[136:139], v[84:99]
	v_mfma_f32_32x32x16_bf16 v[36:51], v[148:151], v[132:135], v[36:51]
	v_mfma_f32_32x32x16_bf16 v[100:115], v[148:151], v[136:139], v[100:115]
	v_mfma_f32_32x32x16_bf16 v[52:67], v[180:183], v[132:135], v[52:67]
	v_mfma_f32_32x32x16_bf16 v[116:131], v[180:183], v[136:139], v[116:131]
	s_mov_b32 m0, s47
	s_nop 0
	global_load_lds_dwordx4 v178, s[76:77]
	global_load_lds_dwordx4 v179, s[78:79] offset:1024
	global_load_lds_dwordx4 v178, s[80:81] offset:2048
	global_load_lds_dwordx4 v179, s[82:83] offset:3072
	v_add_u32_e32 v178, 0x80, v178
	v_add_u32_e32 v179, 0x80, v179
	ds_read_b128 v[132:135], v230 offset:0
	ds_read_b128 v[136:139], v230 offset:4096
	ds_read_b128 v[140:143], v234 offset:0
	ds_read_b128 v[144:147], v234 offset:4096
	ds_read_b128 v[148:151], v234 offset:16384
	ds_read_b128 v[180:183], v234 offset:20480
	s_waitcnt lgkmcnt(6)
; #define MFMA32(a, b, c) __builtin_amdgcn_mfma_f32_32x32x16_bf16((a), (b), (c), 0, 0, 0)
; template <bool SWAP, class Epi>
; DI void gemm_tile(const u16* __restrict__ A, int lda, const u16* __restrict__ Bw, int ldb, int K, char* lds, Epi epi) {
;     ...
;   auto compute = [&](int st) {
;     const char* as = lds + st * GEMM_STAGE;
;     const char* bs = as + 36864;
; #pragma unroll
;     for (int ks = 0; ks < 4; ++ks) {
;       bf16x8 af[2], bfr[2];
; #pragma unroll
;       for (int mi = 0; mi < 2; ++mi) af[mi] = *(const bf16x8*)(as + ((wm * 64 + mi * 32 + r) * 72 + ks * 16 + 8 * h) * 2);
; #pragma unroll
;       for (int ni = 0; ni < 2; ++ni) bfr[ni] = *(const bf16x8*)(bs + ((wn * 64 + ni * 32 + r) * 72 + ks * 16 + 8 * h) * 2);
; #pragma unroll
;       for (int mi = 0; mi < 2; ++mi)
; #pragma unroll
;         for (int ni = 0; ni < 2; ++ni) {
;           if (SWAP) acc[mi][ni] = MFMA32(bfr[ni], af[mi], acc[mi][ni]);
;           else acc[mi][ni] = MFMA32(af[mi], bfr[ni], acc[mi][ni]);
;         }
;     }
;   };
;   gload(0, ra0, rb0);
;   lstore(0, ra0, rb0);
;   gload(1, ra1, rb1);
;   __syncthreads();
;   for (int kt = 0; kt < nk; kt += 2) {
;     if (kt + 2 < nk) gload(kt + 2, ra0, rb0);
;     compute(0);
;     lstore(1, ra1, rb1);
;     __syncthreads();
;     if (kt + 3 < nk) gload(kt + 3, ra1, rb1);
;     compute(1);
;     if (kt + 2 < nk) lstore(0, ra0, rb0);
;     __syncthreads();
	v_mfma_f32_32x32x16_bf16 v[4:19], v[212:215], v[184:187], v[4:19]
	v_mfma_f32_32x32x16_bf16 v[68:83], v[212:215], v[208:211], v[68:83]
	v_mfma_f32_32x32x16_bf16 v[20:35], v[216:219], v[184:187], v[20:35]
	v_mfma_f32_32x32x16_bf16 v[84:99], v[216:219], v[208:211], v[84:99]
	v_mfma_f32_32x32x16_bf16 v[36:51], v[220:223], v[184:187], v[36:51]
	v_mfma_f32_32x32x16_bf16 v[100:115], v[220:223], v[208:211], v[100:115]
	v_mfma_f32_32x32x16_bf16 v[52:67], v[224:227], v[184:187], v[52:67]
	v_mfma_f32_32x32x16_bf16 v[116:131], v[224:227], v[208:211], v[116:131]
	ds_read_b128 v[184:187], v231 offset:0
	ds_read_b128 v[208:211], v231 offset:4096
	ds_read_b128 v[212:215], v235 offset:0
	ds_read_b128 v[216:219], v235 offset:4096
	ds_read_b128 v[220:223], v235 offset:16384
	ds_read_b128 v[224:227], v235 offset:20480
	s_waitcnt lgkmcnt(6)
	v_mfma_f32_32x32x16_bf16 v[4:19], v[140:143], v[132:135], v[4:19]
	v_mfma_f32_32x32x16_bf16 v[68:83], v[140:143], v[136:139], v[68:83]
	v_mfma_f32_32x32x16_bf16 v[20:35], v[144:147], v[132:135], v[20:35]
	v_mfma_f32_32x32x16_bf16 v[84:99], v[144:147], v[136:139], v[84:99]
	v_mfma_f32_32x32x16_bf16 v[36:51], v[148:151], v[132:135], v[36:51]
	v_mfma_f32_32x32x16_bf16 v[100:115], v[148:151], v[136:139], v[100:115]
	v_mfma_f32_32x32x16_bf16 v[52:67], v[180:183], v[132:135], v[52:67]
	v_mfma_f32_32x32x16_bf16 v[116:131], v[180:183], v[136:139], v[116:131]
	s_waitcnt lgkmcnt(0)
	v_mfma_f32_32x32x16_bf16 v[4:19], v[212:215], v[184:187], v[4:19]
	v_mfma_f32_32x32x16_bf16 v[68:83], v[212:215], v[208:211], v[68:83]
	v_mfma_f32_32x32x16_bf16 v[20:35], v[216:219], v[184:187], v[20:35]
	v_mfma_f32_32x32x16_bf16 v[84:99], v[216:219], v[208:211], v[84:99]
	v_mfma_f32_32x32x16_bf16 v[36:51], v[220:223], v[184:187], v[36:51]
	v_mfma_f32_32x32x16_bf16 v[100:115], v[220:223], v[208:211], v[100:115]
	v_mfma_f32_32x32x16_bf16 v[52:67], v[224:227], v[184:187], v[52:67]
	v_mfma_f32_32x32x16_bf16 v[116:131], v[224:227], v[208:211], v[116:131]
	s_waitcnt vmcnt(0) lgkmcnt(0)
	s_barrier
	ds_read_b128 v[132:135], v228 offset:32768
	ds_read_b128 v[136:139], v228 offset:36864
	ds_read_b128 v[140:143], v232 offset:32768
	ds_read_b128 v[144:147], v232 offset:36864
	ds_read_b128 v[148:151], v232 offset:49152
	ds_read_b128 v[180:183], v232 offset:53248
	s_mov_b32 m0, s44
	s_nop 0
	global_load_lds_dwordx4 v178, s[68:69]
	global_load_lds_dwordx4 v179, s[70:71] offset:1024
	global_load_lds_dwordx4 v178, s[72:73] offset:2048
	global_load_lds_dwordx4 v179, s[74:75] offset:3072
	ds_read_b128 v[184:187], v229 offset:32768
	ds_read_b128 v[208:211], v229 offset:36864
	ds_read_b128 v[212:215], v233 offset:32768
	ds_read_b128 v[216:219], v233 offset:36864
	ds_read_b128 v[220:223], v233 offset:49152
	ds_read_b128 v[224:227], v233 offset:53248
	s_waitcnt lgkmcnt(6)
	v_mfma_f32_32x32x16_bf16 v[4:19], v[140:143], v[132:135], v[4:19]
	v_mfma_f32_32x32x16_bf16 v[68:83], v[140:143], v[136:139], v[68:83]
	v_mfma_f32_32x32x16_bf16 v[20:35], v[144:147], v[132:135], v[20:35]
	v_mfma_f32_32x32x16_bf16 v[84:99], v[144:147], v[136:139], v[84:99]
	v_mfma_f32_32x32x16_bf16 v[36:51], v[148:151], v[132:135], v[36:51]
	v_mfma_f32_32x32x16_bf16 v[100:115], v[148:151], v[136:139], v[100:115]
	v_mfma_f32_32x32x16_bf16 v[52:67], v[180:183], v[132:135], v[52:67]
	v_mfma_f32_32x32x16_bf16 v[116:131], v[180:183], v[136:139], v[116:131]
	s_mov_b32 m0, s46
	s_nop 0
	global_load_lds_dwordx4 v178, s[76:77]
	global_load_lds_dwordx4 v179, s[78:79] offset:1024
	global_load_lds_dwordx4 v178, s[80:81] offset:2048
	global_load_lds_dwordx4 v179, s[82:83] offset:3072
	v_add_u32_e32 v178, 0x80, v178
	v_add_u32_e32 v179, 0x80, v179
	ds_read_b128 v[132:135], v230 offset:32768
	ds_read_b128 v[136:139], v230 offset:36864
	ds_read_b128 v[140:143], v234 offset:32768
	ds_read_b128 v[144:147], v234 offset:36864
	ds_read_b128 v[148:151], v234 offset:49152
	ds_read_b128 v[180:183], v234 offset:53248
	s_waitcnt lgkmcnt(6)
	v_mfma_f32_32x32x16_bf16 v[4:19], v[212:215], v[184:187], v[4:19]
	v_mfma_f32_32x32x16_bf16 v[68:83], v[212:215], v[208:211], v[68:83]
	v_mfma_f32_32x32x16_bf16 v[20:35], v[216:219], v[184:187], v[20:35]
	v_mfma_f32_32x32x16_bf16 v[84:99], v[216:219], v[208:211], v[84:99]
	v_mfma_f32_32x32x16_bf16 v[36:51], v[220:223], v[184:187], v[36:51]
	v_mfma_f32_32x32x16_bf16 v[100:115], v[220:223], v[208:211], v[100:115]
	v_mfma_f32_32x32x16_bf16 v[52:67], v[224:227], v[184:187], v[52:67]
	v_mfma_f32_32x32x16_bf16 v[116:131], v[224:227], v[208:211], v[116:131]
	ds_read_b128 v[184:187], v231 offset:32768
	ds_read_b128 v[208:211], v231 offset:36864
	ds_read_b128 v[212:215], v235 offset:32768
	ds_read_b128 v[216:219], v235 offset:36864
	ds_read_b128 v[220:223], v235 offset:49152
	ds_read_b128 v[224:227], v235 offset:53248
	s_waitcnt lgkmcnt(6)
	v_mfma_f32_32x32x16_bf16 v[4:19], v[140:143], v[132:135], v[4:19]
	v_mfma_f32_32x32x16_bf16 v[68:83], v[140:143], v[136:139], v[68:83]
	v_mfma_f32_32x32x16_bf16 v[20:35], v[144:147], v[132:135], v[20:35]
	v_mfma_f32_32x32x16_bf16 v[84:99], v[144:147], v[136:139], v[84:99]
	v_mfma_f32_32x32x16_bf16 v[36:51], v[148:151], v[132:135], v[36:51]
	v_mfma_f32_32x32x16_bf16 v[100:115], v[148:151], v[136:139], v[100:115]
	v_mfma_f32_32x32x16_bf16 v[52:67], v[180:183], v[132:135], v[52:67]
	v_mfma_f32_32x32x16_bf16 v[116:131], v[180:183], v[136:139], v[116:131]
	s_waitcnt lgkmcnt(0)
	v_mfma_f32_32x32x16_bf16 v[4:19], v[212:215], v[184:187], v[4:19]
	v_mfma_f32_32x32x16_bf16 v[68:83], v[212:215], v[208:211], v[68:83]
	v_mfma_f32_32x32x16_bf16 v[20:35], v[216:219], v[184:187], v[20:35]
	v_mfma_f32_32x32x16_bf16 v[84:99], v[216:219], v[208:211], v[84:99]
	v_mfma_f32_32x32x16_bf16 v[36:51], v[220:223], v[184:187], v[36:51]
	v_mfma_f32_32x32x16_bf16 v[100:115], v[220:223], v[208:211], v[100:115]
	v_mfma_f32_32x32x16_bf16 v[52:67], v[224:227], v[184:187], v[52:67]
	v_mfma_f32_32x32x16_bf16 v[116:131], v[224:227], v[208:211], v[116:131]
	s_waitcnt vmcnt(0) lgkmcnt(0)
	s_barrier
; #define MFMA32(a, b, c) __builtin_amdgcn_mfma_f32_32x32x16_bf16((a), (b), (c), 0, 0, 0)
; template <bool SWAP, class Epi>
; DI void gemm_tile(const u16* __restrict__ A, int lda, const u16* __restrict__ Bw, int ldb, int K, char* lds, Epi epi) {
;     ...
;   auto compute = [&](int st) {
;     const char* as = lds + st * GEMM_STAGE;
;     const char* bs = as + 36864;
; #pragma unroll
;     for (int ks = 0; ks < 4; ++ks) {
;       bf16x8 af[2], bfr[2];
; #pragma unroll
;       for (int mi = 0; mi < 2; ++mi) af[mi] = *(const bf16x8*)(as + ((wm * 64 + mi * 32 + r) * 72 + ks * 16 + 8 * h) * 2);
; #pragma unroll
;       for (int ni = 0; ni < 2; ++ni) bfr[ni] = *(const bf16x8*)(bs + ((wn * 64 + ni * 32 + r) * 72 + ks * 16 + 8 * h) * 2);
; #pragma unroll
;       for (int mi = 0; mi < 2; ++mi)
; #pragma unroll
;         for (int ni = 0; ni < 2; ++ni) {
;           if (SWAP) acc[mi][ni] = MFMA32(bfr[ni], af[mi], acc[mi][ni]);
;           else acc[mi][ni] = MFMA32(af[mi], bfr[ni], acc[mi][ni]);
;         }
;     }
;   };
;   gload(0, ra0, rb0);
;   lstore(0, ra0, rb0);
;   gload(1, ra1, rb1);
;   __syncthreads();
;   for (int kt = 0; kt < nk; kt += 2) {
;     if (kt + 2 < nk) gload(kt + 2, ra0, rb0);
;     compute(0);
;     lstore(1, ra1, rb1);
;     __syncthreads();
;     if (kt + 3 < nk) gload(kt + 3, ra1, rb1);
;     compute(1);
;     if (kt + 2 < nk) lstore(0, ra0, rb0);
;     __syncthreads();
	ds_read_b128 v[132:135], v228 offset:0
	ds_read_b128 v[136:139], v228 offset:4096
	ds_read_b128 v[140:143], v232 offset:0
	ds_read_b128 v[144:147], v232 offset:4096
	ds_read_b128 v[148:151], v232 offset:16384
	ds_read_b128 v[180:183], v232 offset:20480
	s_mov_b32 m0, s45
	s_nop 0
	global_load_lds_dwordx4 v178, s[68:69]
	global_load_lds_dwordx4 v179, s[70:71] offset:1024
	global_load_lds_dwordx4 v178, s[72:73] offset:2048
	global_load_lds_dwordx4 v179, s[74:75] offset:3072
	ds_read_b128 v[184:187], v229 offset:0
	ds_read_b128 v[208:211], v229 offset:4096
	ds_read_b128 v[212:215], v233 offset:0
	ds_read_b128 v[216:219], v233 offset:4096
	ds_read_b128 v[220:223], v233 offset:16384
	ds_read_b128 v[224:227], v233 offset:20480
	s_waitcnt lgkmcnt(6)
	v_mfma_f32_32x32x16_bf16 v[4:19], v[140:143], v[132:135], v[4:19]
	v_mfma_f32_32x32x16_bf16 v[68:83], v[140:143], v[136:139], v[68:83]
	v_mfma_f32_32x32x16_bf16 v[20:35], v[144:147], v[132:135], v[20:35]
	v_mfma_f32_32x32x16_bf16 v[84:99], v[144:147], v[136:139], v[84:99]
	v_mfma_f32_32x32x16_bf16 v[36:51], v[148:151], v[132:135], v[36:51]
	v_mfma_f32_32x32x16_bf16 v[100:115], v[148:151], v[136:139], v[100:115]
	v_mfma_f32_32x32x16_bf16 v[52:67], v[180:183], v[132:135], v[52:67]
	v_mfma_f32_32x32x16_bf16 v[116:131], v[180:183], v[136:139], v[116:131]
	s_mov_b32 m0, s47
	s_nop 0
	global_load_lds_dwordx4 v178, s[76:77]
	global_load_lds_dwordx4 v179, s[78:79] offset:1024
	global_load_lds_dwordx4 v178, s[80:81] offset:2048
	global_load_lds_dwordx4 v179, s[82:83] offset:3072
	v_add_u32_e32 v178, 0x80, v178
	v_add_u32_e32 v179, 0x80, v179
	ds_read_b128 v[132:135], v230 offset:0
	ds_read_b128 v[136:139], v230 offset:4096
	ds_read_b128 v[140:143], v234 offset:0
	ds_read_b128 v[144:147], v234 offset:4096
	ds_read_b128 v[148:151], v234 offset:16384
	ds_read_b128 v[180:183], v234 offset:20480
	s_waitcnt lgkmcnt(6)
	v_mfma_f32_32x32x16_bf16 v[4:19], v[212:215], v[184:187], v[4:19]
	v_mfma_f32_32x32x16_bf16 v[68:83], v[212:215], v[208:211], v[68:83]
	v_mfma_f32_32x32x16_bf16 v[20:35], v[216:219], v[184:187], v[20:35]
	v_mfma_f32_32x32x16_bf16 v[84:99], v[216:219], v[208:211], v[84:99]
	v_mfma_f32_32x32x16_bf16 v[36:51], v[220:223], v[184:187], v[36:51]
	v_mfma_f32_32x32x16_bf16 v[100:115], v[220:223], v[208:211], v[100:115]
	v_mfma_f32_32x32x16_bf16 v[52:67], v[224:227], v[184:187], v[52:67]
	v_mfma_f32_32x32x16_bf16 v[116:131], v[224:227], v[208:211], v[116:131]
	ds_read_b128 v[184:187], v231 offset:0
	ds_read_b128 v[208:211], v231 offset:4096
	ds_read_b128 v[212:215], v235 offset:0
	ds_read_b128 v[216:219], v235 offset:4096
	ds_read_b128 v[220:223], v235 offset:16384
	ds_read_b128 v[224:227], v235 offset:20480
	s_waitcnt lgkmcnt(6)
	v_mfma_f32_32x32x16_bf16 v[4:19], v[140:143], v[132:135], v[4:19]
	v_mfma_f32_32x32x16_bf16 v[68:83], v[140:143], v[136:139], v[68:83]
	v_mfma_f32_32x32x16_bf16 v[20:35], v[144:147], v[132:135], v[20:35]
	v_mfma_f32_32x32x16_bf16 v[84:99], v[144:147], v[136:139], v[84:99]
	v_mfma_f32_32x32x16_bf16 v[36:51], v[148:151], v[132:135], v[36:51]
	v_mfma_f32_32x32x16_bf16 v[100:115], v[148:151], v[136:139], v[100:115]
	v_mfma_f32_32x32x16_bf16 v[52:67], v[180:183], v[132:135], v[52:67]
	v_mfma_f32_32x32x16_bf16 v[116:131], v[180:183], v[136:139], v[116:131]
	s_waitcnt lgkmcnt(0)
	v_mfma_f32_32x32x16_bf16 v[4:19], v[212:215], v[184:187], v[4:19]
	v_mfma_f32_32x32x16_bf16 v[68:83], v[212:215], v[208:211], v[68:83]
	v_mfma_f32_32x32x16_bf16 v[20:35], v[216:219], v[184:187], v[20:35]
	v_mfma_f32_32x32x16_bf16 v[84:99], v[216:219], v[208:211], v[84:99]
	v_mfma_f32_32x32x16_bf16 v[36:51], v[220:223], v[184:187], v[36:51]
	v_mfma_f32_32x32x16_bf16 v[100:115], v[220:223], v[208:211], v[100:115]
	v_mfma_f32_32x32x16_bf16 v[52:67], v[224:227], v[184:187], v[52:67]
	v_mfma_f32_32x32x16_bf16 v[116:131], v[224:227], v[208:211], v[116:131]
	s_waitcnt vmcnt(0) lgkmcnt(0)
	s_barrier
	ds_read_b128 v[132:135], v228 offset:32768
	ds_read_b128 v[136:139], v228 offset:36864
	ds_read_b128 v[140:143], v232 offset:32768
	ds_read_b128 v[144:147], v232 offset:36864
	ds_read_b128 v[148:151], v232 offset:49152
	ds_read_b128 v[180:183], v232 offset:53248
	s_mov_b32 m0, s44
	s_nop 0
	global_load_lds_dwordx4 v178, s[68:69]
	global_load_lds_dwordx4 v179, s[70:71] offset:1024
	global_load_lds_dwordx4 v178, s[72:73] offset:2048
	global_load_lds_dwordx4 v179, s[74:75] offset:3072
	ds_read_b128 v[184:187], v229 offset:32768
	ds_read_b128 v[208:211], v229 offset:36864
	ds_read_b128 v[212:215], v233 offset:32768
	ds_read_b128 v[216:219], v233 offset:36864
	ds_read_b128 v[220:223], v233 offset:49152
	ds_read_b128 v[224:227], v233 offset:53248
	s_waitcnt lgkmcnt(6)
	v_mfma_f32_32x32x16_bf16 v[4:19], v[140:143], v[132:135], v[4:19]
	v_mfma_f32_32x32x16_bf16 v[68:83], v[140:143], v[136:139], v[68:83]
	v_mfma_f32_32x32x16_bf16 v[20:35], v[144:147], v[132:135], v[20:35]
	v_mfma_f32_32x32x16_bf16 v[84:99], v[144:147], v[136:139], v[84:99]
	v_mfma_f32_32x32x16_bf16 v[36:51], v[148:151], v[132:135], v[36:51]
	v_mfma_f32_32x32x16_bf16 v[100:115], v[148:151], v[136:139], v[100:115]
	v_mfma_f32_32x32x16_bf16 v[52:67], v[180:183], v[132:135], v[52:67]
	v_mfma_f32_32x32x16_bf16 v[116:131], v[180:183], v[136:139], v[116:131]
	s_mov_b32 m0, s46
	s_nop 0
	global_load_lds_dwordx4 v178, s[76:77]
	global_load_lds_dwordx4 v179, s[78:79] offset:1024
	global_load_lds_dwordx4 v178, s[80:81] offset:2048
	global_load_lds_dwordx4 v179, s[82:83] offset:3072
	v_add_u32_e32 v178, 0x80, v178
	v_add_u32_e32 v179, 0x80, v179
	ds_read_b128 v[132:135], v230 offset:32768
	ds_read_b128 v[136:139], v230 offset:36864
	ds_read_b128 v[140:143], v234 offset:32768
	ds_read_b128 v[144:147], v234 offset:36864
	ds_read_b128 v[148:151], v234 offset:49152
	ds_read_b128 v[180:183], v234 offset:53248
	s_waitcnt lgkmcnt(6)
; #define MFMA32(a, b, c) __builtin_amdgcn_mfma_f32_32x32x16_bf16((a), (b), (c), 0, 0, 0)
; template <bool SWAP, class Epi>
; DI void gemm_tile(const u16* __restrict__ A, int lda, const u16* __restrict__ Bw, int ldb, int K, char* lds, Epi epi) {
;     ...
;   auto compute = [&](int st) {
;     const char* as = lds + st * GEMM_STAGE;
;     const char* bs = as + 36864;
; #pragma unroll
;     for (int ks = 0; ks < 4; ++ks) {
;       bf16x8 af[2], bfr[2];
; #pragma unroll
;       for (int mi = 0; mi < 2; ++mi) af[mi] = *(const bf16x8*)(as + ((wm * 64 + mi * 32 + r) * 72 + ks * 16 + 8 * h) * 2);
; #pragma unroll
;       for (int ni = 0; ni < 2; ++ni) bfr[ni] = *(const bf16x8*)(bs + ((wn * 64 + ni * 32 + r) * 72 + ks * 16 + 8 * h) * 2);
; #pragma unroll
;       for (int mi = 0; mi < 2; ++mi)
; #pragma unroll
;         for (int ni = 0; ni < 2; ++ni) {
;           if (SWAP) acc[mi][ni] = MFMA32(bfr[ni], af[mi], acc[mi][ni]);
;           else acc[mi][ni] = MFMA32(af[mi], bfr[ni], acc[mi][ni]);
;         }
;     }
;   };
;   gload(0, ra0, rb0);
;   lstore(0, ra0, rb0);
;   gload(1, ra1, rb1);
;   __syncthreads();
;   for (int kt = 0; kt < nk; kt += 2) {
;     if (kt + 2 < nk) gload(kt + 2, ra0, rb0);
;     compute(0);
;     lstore(1, ra1, rb1);
;     __syncthreads();
;     if (kt + 3 < nk) gload(kt + 3, ra1, rb1);
;     compute(1);
;     if (kt + 2 < nk) lstore(0, ra0, rb0);
;     __syncthreads();
	v_mfma_f32_32x32x16_bf16 v[4:19], v[212:215], v[184:187], v[4:19]
	v_mfma_f32_32x32x16_bf16 v[68:83], v[212:215], v[208:211], v[68:83]
	v_mfma_f32_32x32x16_bf16 v[20:35], v[216:219], v[184:187], v[20:35]
	v_mfma_f32_32x32x16_bf16 v[84:99], v[216:219], v[208:211], v[84:99]
	v_mfma_f32_32x32x16_bf16 v[36:51], v[220:223], v[184:187], v[36:51]
	v_mfma_f32_32x32x16_bf16 v[100:115], v[220:223], v[208:211], v[100:115]
	v_mfma_f32_32x32x16_bf16 v[52:67], v[224:227], v[184:187], v[52:67]
	v_mfma_f32_32x32x16_bf16 v[116:131], v[224:227], v[208:211], v[116:131]
	ds_read_b128 v[184:187], v231 offset:32768
	ds_read_b128 v[208:211], v231 offset:36864
	ds_read_b128 v[212:215], v235 offset:32768
	ds_read_b128 v[216:219], v235 offset:36864
	ds_read_b128 v[220:223], v235 offset:49152
	ds_read_b128 v[224:227], v235 offset:53248
	s_waitcnt lgkmcnt(6)
	v_mfma_f32_32x32x16_bf16 v[4:19], v[140:143], v[132:135], v[4:19]
	v_mfma_f32_32x32x16_bf16 v[68:83], v[140:143], v[136:139], v[68:83]
	v_mfma_f32_32x32x16_bf16 v[20:35], v[144:147], v[132:135], v[20:35]
	v_mfma_f32_32x32x16_bf16 v[84:99], v[144:147], v[136:139], v[84:99]
	v_mfma_f32_32x32x16_bf16 v[36:51], v[148:151], v[132:135], v[36:51]
	v_mfma_f32_32x32x16_bf16 v[100:115], v[148:151], v[136:139], v[100:115]
	v_mfma_f32_32x32x16_bf16 v[52:67], v[180:183], v[132:135], v[52:67]
	v_mfma_f32_32x32x16_bf16 v[116:131], v[180:183], v[136:139], v[116:131]
	s_waitcnt lgkmcnt(0)
	v_mfma_f32_32x32x16_bf16 v[4:19], v[212:215], v[184:187], v[4:19]
	v_mfma_f32_32x32x16_bf16 v[68:83], v[212:215], v[208:211], v[68:83]
	v_mfma_f32_32x32x16_bf16 v[20:35], v[216:219], v[184:187], v[20:35]
	v_mfma_f32_32x32x16_bf16 v[84:99], v[216:219], v[208:211], v[84:99]
	v_mfma_f32_32x32x16_bf16 v[36:51], v[220:223], v[184:187], v[36:51]
	v_mfma_f32_32x32x16_bf16 v[100:115], v[220:223], v[208:211], v[100:115]
	v_mfma_f32_32x32x16_bf16 v[52:67], v[224:227], v[184:187], v[52:67]
	v_mfma_f32_32x32x16_bf16 v[116:131], v[224:227], v[208:211], v[116:131]
	s_waitcnt vmcnt(0) lgkmcnt(0)
	s_barrier
	ds_read_b128 v[132:135], v228 offset:0
	ds_read_b128 v[136:139], v228 offset:4096
	ds_read_b128 v[140:143], v232 offset:0
	ds_read_b128 v[144:147], v232 offset:4096
	ds_read_b128 v[148:151], v232 offset:16384
	ds_read_b128 v[180:183], v232 offset:20480
	s_mov_b32 m0, s45
	s_nop 0
	global_load_lds_dwordx4 v178, s[68:69]
	global_load_lds_dwordx4 v179, s[70:71] offset:1024
	global_load_lds_dwordx4 v178, s[72:73] offset:2048
	global_load_lds_dwordx4 v179, s[74:75] offset:3072
	ds_read_b128 v[184:187], v229 offset:0
	ds_read_b128 v[208:211], v229 offset:4096
	ds_read_b128 v[212:215], v233 offset:0
	ds_read_b128 v[216:219], v233 offset:4096
	ds_read_b128 v[220:223], v233 offset:16384
	ds_read_b128 v[224:227], v233 offset:20480
	s_waitcnt lgkmcnt(6)
	v_mfma_f32_32x32x16_bf16 v[4:19], v[140:143], v[132:135], v[4:19]
	v_mfma_f32_32x32x16_bf16 v[68:83], v[140:143], v[136:139], v[68:83]
	v_mfma_f32_32x32x16_bf16 v[20:35], v[144:147], v[132:135], v[20:35]
	v_mfma_f32_32x32x16_bf16 v[84:99], v[144:147], v[136:139], v[84:99]
	v_mfma_f32_32x32x16_bf16 v[36:51], v[148:151], v[132:135], v[36:51]
	v_mfma_f32_32x32x16_bf16 v[100:115], v[148:151], v[136:139], v[100:115]
	v_mfma_f32_32x32x16_bf16 v[52:67], v[180:183], v[132:135], v[52:67]
	v_mfma_f32_32x32x16_bf16 v[116:131], v[180:183], v[136:139], v[116:131]
	s_mov_b32 m0, s47
	s_nop 0
	global_load_lds_dwordx4 v178, s[76:77]
	global_load_lds_dwordx4 v179, s[78:79] offset:1024
	global_load_lds_dwordx4 v178, s[80:81] offset:2048
	global_load_lds_dwordx4 v179, s[82:83] offset:3072
	v_add_u32_e32 v178, 0x80, v178
	v_add_u32_e32 v179, 0x80, v179
	ds_read_b128 v[132:135], v230 offset:0
	ds_read_b128 v[136:139], v230 offset:4096
	ds_read_b128 v[140:143], v234 offset:0
	ds_read_b128 v[144:147], v234 offset:4096
	ds_read_b128 v[148:151], v234 offset:16384
	ds_read_b128 v[180:183], v234 offset:20480
	s_waitcnt lgkmcnt(6)
	v_mfma_f32_32x32x16_bf16 v[4:19], v[212:215], v[184:187], v[4:19]
	v_mfma_f32_32x32x16_bf16 v[68:83], v[212:215], v[208:211], v[68:83]
	v_mfma_f32_32x32x16_bf16 v[20:35], v[216:219], v[184:187], v[20:35]
	v_mfma_f32_32x32x16_bf16 v[84:99], v[216:219], v[208:211], v[84:99]
	v_mfma_f32_32x32x16_bf16 v[36:51], v[220:223], v[184:187], v[36:51]
	v_mfma_f32_32x32x16_bf16 v[100:115], v[220:223], v[208:211], v[100:115]
	v_mfma_f32_32x32x16_bf16 v[52:67], v[224:227], v[184:187], v[52:67]
	v_mfma_f32_32x32x16_bf16 v[116:131], v[224:227], v[208:211], v[116:131]
	ds_read_b128 v[184:187], v231 offset:0
	ds_read_b128 v[208:211], v231 offset:4096
	ds_read_b128 v[212:215], v235 offset:0
	ds_read_b128 v[216:219], v235 offset:4096
	ds_read_b128 v[220:223], v235 offset:16384
	ds_read_b128 v[224:227], v235 offset:20480
	s_waitcnt lgkmcnt(6)
	v_mfma_f32_32x32x16_bf16 v[4:19], v[140:143], v[132:135], v[4:19]
	v_mfma_f32_32x32x16_bf16 v[68:83], v[140:143], v[136:139], v[68:83]
	v_mfma_f32_32x32x16_bf16 v[20:35], v[144:147], v[132:135], v[20:35]
	v_mfma_f32_32x32x16_bf16 v[84:99], v[144:147], v[136:139], v[84:99]
	v_mfma_f32_32x32x16_bf16 v[36:51], v[148:151], v[132:135], v[36:51]
	v_mfma_f32_32x32x16_bf16 v[100:115], v[148:151], v[136:139], v[100:115]
	v_mfma_f32_32x32x16_bf16 v[52:67], v[180:183], v[132:135], v[52:67]
	v_mfma_f32_32x32x16_bf16 v[116:131], v[180:183], v[136:139], v[116:131]
	s_waitcnt lgkmcnt(0)
	v_mfma_f32_32x32x16_bf16 v[4:19], v[212:215], v[184:187], v[4:19]
	v_mfma_f32_32x32x16_bf16 v[68:83], v[212:215], v[208:211], v[68:83]
	v_mfma_f32_32x32x16_bf16 v[20:35], v[216:219], v[184:187], v[20:35]
	v_mfma_f32_32x32x16_bf16 v[84:99], v[216:219], v[208:211], v[84:99]
	v_mfma_f32_32x32x16_bf16 v[36:51], v[220:223], v[184:187], v[36:51]
	v_mfma_f32_32x32x16_bf16 v[100:115], v[220:223], v[208:211], v[100:115]
	v_mfma_f32_32x32x16_bf16 v[52:67], v[224:227], v[184:187], v[52:67]
	v_mfma_f32_32x32x16_bf16 v[116:131], v[224:227], v[208:211], v[116:131]
	s_waitcnt vmcnt(0) lgkmcnt(0)
	s_barrier
; #define MFMA32(a, b, c) __builtin_amdgcn_mfma_f32_32x32x16_bf16((a), (b), (c), 0, 0, 0)
; template <bool SWAP, class Epi>
; DI void gemm_tile(const u16* __restrict__ A, int lda, const u16* __restrict__ Bw, int ldb, int K, char* lds, Epi epi) {
;     ...
;   auto compute = [&](int st) {
;     const char* as = lds + st * GEMM_STAGE;
;     const char* bs = as + 36864;
; #pragma unroll
;     for (int ks = 0; ks < 4; ++ks) {
;       bf16x8 af[2], bfr[2];
; #pragma unroll
;       for (int mi = 0; mi < 2; ++mi) af[mi] = *(const bf16x8*)(as + ((wm * 64 + mi * 32 + r) * 72 + ks * 16 + 8 * h) * 2);
; #pragma unroll
;       for (int ni = 0; ni < 2; ++ni) bfr[ni] = *(const bf16x8*)(bs + ((wn * 64 + ni * 32 + r) * 72 + ks * 16 + 8 * h) * 2);
; #pragma unroll
;       for (int mi = 0; mi < 2; ++mi)
; #pragma unroll
;         for (int ni = 0; ni < 2; ++ni) {
;           if (SWAP) acc[mi][ni] = MFMA32(bfr[ni], af[mi], acc[mi][ni]);
;           else acc[mi][ni] = MFMA32(af[mi], bfr[ni], acc[mi][ni]);
;         }
;     }
;   };
;   gload(0, ra0, rb0);
;   lstore(0, ra0, rb0);
;   gload(1, ra1, rb1);
;   __syncthreads();
;   for (int kt = 0; kt < nk; kt += 2) {
;     if (kt + 2 < nk) gload(kt + 2, ra0, rb0);
;     compute(0);
;     lstore(1, ra1, rb1);
;     __syncthreads();
;     if (kt + 3 < nk) gload(kt + 3, ra1, rb1);
;     compute(1);
;     if (kt + 2 < nk) lstore(0, ra0, rb0);
;     __syncthreads();
	ds_read_b128 v[132:135], v228 offset:32768
	ds_read_b128 v[136:139], v228 offset:36864
	ds_read_b128 v[140:143], v232 offset:32768
	ds_read_b128 v[144:147], v232 offset:36864
	ds_read_b128 v[148:151], v232 offset:49152
	ds_read_b128 v[180:183], v232 offset:53248
	s_mov_b32 m0, s44
	s_nop 0
	global_load_lds_dwordx4 v178, s[68:69]
	global_load_lds_dwordx4 v179, s[70:71] offset:1024
	global_load_lds_dwordx4 v178, s[72:73] offset:2048
	global_load_lds_dwordx4 v179, s[74:75] offset:3072
	ds_read_b128 v[184:187], v229 offset:32768
	ds_read_b128 v[208:211], v229 offset:36864
	ds_read_b128 v[212:215], v233 offset:32768
	ds_read_b128 v[216:219], v233 offset:36864
	ds_read_b128 v[220:223], v233 offset:49152
	ds_read_b128 v[224:227], v233 offset:53248
	s_waitcnt lgkmcnt(6)
	v_mfma_f32_32x32x16_bf16 v[4:19], v[140:143], v[132:135], v[4:19]
	v_mfma_f32_32x32x16_bf16 v[68:83], v[140:143], v[136:139], v[68:83]
	v_mfma_f32_32x32x16_bf16 v[20:35], v[144:147], v[132:135], v[20:35]
	v_mfma_f32_32x32x16_bf16 v[84:99], v[144:147], v[136:139], v[84:99]
	v_mfma_f32_32x32x16_bf16 v[36:51], v[148:151], v[132:135], v[36:51]
	v_mfma_f32_32x32x16_bf16 v[100:115], v[148:151], v[136:139], v[100:115]
	v_mfma_f32_32x32x16_bf16 v[52:67], v[180:183], v[132:135], v[52:67]
	v_mfma_f32_32x32x16_bf16 v[116:131], v[180:183], v[136:139], v[116:131]
	s_mov_b32 m0, s46
	s_nop 0
	global_load_lds_dwordx4 v178, s[76:77]
	global_load_lds_dwordx4 v179, s[78:79] offset:1024
	global_load_lds_dwordx4 v178, s[80:81] offset:2048
	global_load_lds_dwordx4 v179, s[82:83] offset:3072
	v_add_u32_e32 v178, 0x80, v178
	v_add_u32_e32 v179, 0x80, v179
	ds_read_b128 v[132:135], v230 offset:32768
	ds_read_b128 v[136:139], v230 offset:36864
	ds_read_b128 v[140:143], v234 offset:32768
	ds_read_b128 v[144:147], v234 offset:36864
	ds_read_b128 v[148:151], v234 offset:49152
	ds_read_b128 v[180:183], v234 offset:53248
	s_waitcnt lgkmcnt(6)
	v_mfma_f32_32x32x16_bf16 v[4:19], v[212:215], v[184:187], v[4:19]
	v_mfma_f32_32x32x16_bf16 v[68:83], v[212:215], v[208:211], v[68:83]
	v_mfma_f32_32x32x16_bf16 v[20:35], v[216:219], v[184:187], v[20:35]
	v_mfma_f32_32x32x16_bf16 v[84:99], v[216:219], v[208:211], v[84:99]
	v_mfma_f32_32x32x16_bf16 v[36:51], v[220:223], v[184:187], v[36:51]
	v_mfma_f32_32x32x16_bf16 v[100:115], v[220:223], v[208:211], v[100:115]
	v_mfma_f32_32x32x16_bf16 v[52:67], v[224:227], v[184:187], v[52:67]
	v_mfma_f32_32x32x16_bf16 v[116:131], v[224:227], v[208:211], v[116:131]
	ds_read_b128 v[184:187], v231 offset:32768
	ds_read_b128 v[208:211], v231 offset:36864
	ds_read_b128 v[212:215], v235 offset:32768
	ds_read_b128 v[216:219], v235 offset:36864
	ds_read_b128 v[220:223], v235 offset:49152
	ds_read_b128 v[224:227], v235 offset:53248
	s_waitcnt lgkmcnt(6)
	v_mfma_f32_32x32x16_bf16 v[4:19], v[140:143], v[132:135], v[4:19]
	v_mfma_f32_32x32x16_bf16 v[68:83], v[140:143], v[136:139], v[68:83]
	v_mfma_f32_32x32x16_bf16 v[20:35], v[144:147], v[132:135], v[20:35]
	v_mfma_f32_32x32x16_bf16 v[84:99], v[144:147], v[136:139], v[84:99]
	v_mfma_f32_32x32x16_bf16 v[36:51], v[148:151], v[132:135], v[36:51]
	v_mfma_f32_32x32x16_bf16 v[100:115], v[148:151], v[136:139], v[100:115]
	v_mfma_f32_32x32x16_bf16 v[52:67], v[180:183], v[132:135], v[52:67]
	v_mfma_f32_32x32x16_bf16 v[116:131], v[180:183], v[136:139], v[116:131]
	s_waitcnt lgkmcnt(0)
	v_mfma_f32_32x32x16_bf16 v[4:19], v[212:215], v[184:187], v[4:19]
	v_mfma_f32_32x32x16_bf16 v[68:83], v[212:215], v[208:211], v[68:83]
	v_mfma_f32_32x32x16_bf16 v[20:35], v[216:219], v[184:187], v[20:35]
	v_mfma_f32_32x32x16_bf16 v[84:99], v[216:219], v[208:211], v[84:99]
	v_mfma_f32_32x32x16_bf16 v[36:51], v[220:223], v[184:187], v[36:51]
	v_mfma_f32_32x32x16_bf16 v[100:115], v[220:223], v[208:211], v[100:115]
	v_mfma_f32_32x32x16_bf16 v[52:67], v[224:227], v[184:187], v[52:67]
	v_mfma_f32_32x32x16_bf16 v[116:131], v[224:227], v[208:211], v[116:131]
	s_waitcnt vmcnt(0) lgkmcnt(0)
	s_barrier
	ds_read_b128 v[132:135], v228 offset:0
	ds_read_b128 v[136:139], v228 offset:4096
	ds_read_b128 v[140:143], v232 offset:0
	ds_read_b128 v[144:147], v232 offset:4096
	ds_read_b128 v[148:151], v232 offset:16384
	ds_read_b128 v[180:183], v232 offset:20480
	s_mov_b32 m0, s45
	s_nop 0
	global_load_lds_dwordx4 v178, s[68:69]
	global_load_lds_dwordx4 v179, s[70:71] offset:1024
	global_load_lds_dwordx4 v178, s[72:73] offset:2048
	global_load_lds_dwordx4 v179, s[74:75] offset:3072
	ds_read_b128 v[184:187], v229 offset:0
	ds_read_b128 v[208:211], v229 offset:4096
	ds_read_b128 v[212:215], v233 offset:0
	ds_read_b128 v[216:219], v233 offset:4096
	ds_read_b128 v[220:223], v233 offset:16384
	ds_read_b128 v[224:227], v233 offset:20480
	s_waitcnt lgkmcnt(6)
	v_mfma_f32_32x32x16_bf16 v[4:19], v[140:143], v[132:135], v[4:19]
	v_mfma_f32_32x32x16_bf16 v[68:83], v[140:143], v[136:139], v[68:83]
	v_mfma_f32_32x32x16_bf16 v[20:35], v[144:147], v[132:135], v[20:35]
	v_mfma_f32_32x32x16_bf16 v[84:99], v[144:147], v[136:139], v[84:99]
	v_mfma_f32_32x32x16_bf16 v[36:51], v[148:151], v[132:135], v[36:51]
	v_mfma_f32_32x32x16_bf16 v[100:115], v[148:151], v[136:139], v[100:115]
	v_mfma_f32_32x32x16_bf16 v[52:67], v[180:183], v[132:135], v[52:67]
	v_mfma_f32_32x32x16_bf16 v[116:131], v[180:183], v[136:139], v[116:131]
	s_mov_b32 m0, s47
	s_nop 0
	global_load_lds_dwordx4 v178, s[76:77]
	global_load_lds_dwordx4 v179, s[78:79] offset:1024
	global_load_lds_dwordx4 v178, s[80:81] offset:2048
	global_load_lds_dwordx4 v179, s[82:83] offset:3072
	v_add_u32_e32 v178, 0x80, v178
	v_add_u32_e32 v179, 0x80, v179
	ds_read_b128 v[132:135], v230 offset:0
	ds_read_b128 v[136:139], v230 offset:4096
	ds_read_b128 v[140:143], v234 offset:0
	ds_read_b128 v[144:147], v234 offset:4096
	ds_read_b128 v[148:151], v234 offset:16384
	ds_read_b128 v[180:183], v234 offset:20480
	s_waitcnt lgkmcnt(6)
; #define MFMA32(a, b, c) __builtin_amdgcn_mfma_f32_32x32x16_bf16((a), (b), (c), 0, 0, 0)
; template <bool SWAP, class Epi>
; DI void gemm_tile(const u16* __restrict__ A, int lda, const u16* __restrict__ Bw, int ldb, int K, char* lds, Epi epi) {
;     ...
;   auto compute = [&](int st) {
;     const char* as = lds + st * GEMM_STAGE;
;     const char* bs = as + 36864;
; #pragma unroll
;     for (int ks = 0; ks < 4; ++ks) {
;       bf16x8 af[2], bfr[2];
; #pragma unroll
;       for (int mi = 0; mi < 2; ++mi) af[mi] = *(const bf16x8*)(as + ((wm * 64 + mi * 32 + r) * 72 + ks * 16 + 8 * h) * 2);
; #pragma unroll
;       for (int ni = 0; ni < 2; ++ni) bfr[ni] = *(const bf16x8*)(bs + ((wn * 64 + ni * 32 + r) * 72 + ks * 16 + 8 * h) * 2);
; #pragma unroll
;       for (int mi = 0; mi < 2; ++mi)
; #pragma unroll
;         for (int ni = 0; ni < 2; ++ni) {
;           if (SWAP) acc[mi][ni] = MFMA32(bfr[ni], af[mi], acc[mi][ni]);
;           else acc[mi][ni] = MFMA32(af[mi], bfr[ni], acc[mi][ni]);
;         }
;     }
;   };
;   gload(0, ra0, rb0);
;   lstore(0, ra0, rb0);
;   gload(1, ra1, rb1);
;   __syncthreads();
;   for (int kt = 0; kt < nk; kt += 2) {
;     if (kt + 2 < nk) gload(kt + 2, ra0, rb0);
;     compute(0);
;     lstore(1, ra1, rb1);
;     __syncthreads();
;     if (kt + 3 < nk) gload(kt + 3, ra1, rb1);
;     compute(1);
;     if (kt + 2 < nk) lstore(0, ra0, rb0);
;     __syncthreads();
	v_mfma_f32_32x32x16_bf16 v[4:19], v[212:215], v[184:187], v[4:19]
	v_mfma_f32_32x32x16_bf16 v[68:83], v[212:215], v[208:211], v[68:83]
	v_mfma_f32_32x32x16_bf16 v[20:35], v[216:219], v[184:187], v[20:35]
	v_mfma_f32_32x32x16_bf16 v[84:99], v[216:219], v[208:211], v[84:99]
	v_mfma_f32_32x32x16_bf16 v[36:51], v[220:223], v[184:187], v[36:51]
	v_mfma_f32_32x32x16_bf16 v[100:115], v[220:223], v[208:211], v[100:115]
	v_mfma_f32_32x32x16_bf16 v[52:67], v[224:227], v[184:187], v[52:67]
	v_mfma_f32_32x32x16_bf16 v[116:131], v[224:227], v[208:211], v[116:131]
	ds_read_b128 v[184:187], v231 offset:0
	ds_read_b128 v[208:211], v231 offset:4096
	ds_read_b128 v[212:215], v235 offset:0
	ds_read_b128 v[216:219], v235 offset:4096
	ds_read_b128 v[220:223], v235 offset:16384
	ds_read_b128 v[224:227], v235 offset:20480
	s_waitcnt lgkmcnt(6)
	v_mfma_f32_32x32x16_bf16 v[4:19], v[140:143], v[132:135], v[4:19]
	v_mfma_f32_32x32x16_bf16 v[68:83], v[140:143], v[136:139], v[68:83]
	v_mfma_f32_32x32x16_bf16 v[20:35], v[144:147], v[132:135], v[20:35]
	v_mfma_f32_32x32x16_bf16 v[84:99], v[144:147], v[136:139], v[84:99]
	v_mfma_f32_32x32x16_bf16 v[36:51], v[148:151], v[132:135], v[36:51]
	v_mfma_f32_32x32x16_bf16 v[100:115], v[148:151], v[136:139], v[100:115]
	v_mfma_f32_32x32x16_bf16 v[52:67], v[180:183], v[132:135], v[52:67]
	v_mfma_f32_32x32x16_bf16 v[116:131], v[180:183], v[136:139], v[116:131]
	s_waitcnt lgkmcnt(0)
	v_mfma_f32_32x32x16_bf16 v[4:19], v[212:215], v[184:187], v[4:19]
	v_mfma_f32_32x32x16_bf16 v[68:83], v[212:215], v[208:211], v[68:83]
	v_mfma_f32_32x32x16_bf16 v[20:35], v[216:219], v[184:187], v[20:35]
	v_mfma_f32_32x32x16_bf16 v[84:99], v[216:219], v[208:211], v[84:99]
	v_mfma_f32_32x32x16_bf16 v[36:51], v[220:223], v[184:187], v[36:51]
	v_mfma_f32_32x32x16_bf16 v[100:115], v[220:223], v[208:211], v[100:115]
	v_mfma_f32_32x32x16_bf16 v[52:67], v[224:227], v[184:187], v[52:67]
	v_mfma_f32_32x32x16_bf16 v[116:131], v[224:227], v[208:211], v[116:131]
	s_waitcnt vmcnt(0) lgkmcnt(0)
	s_barrier
	ds_read_b128 v[132:135], v228 offset:32768
	ds_read_b128 v[136:139], v228 offset:36864
	ds_read_b128 v[140:143], v232 offset:32768
	ds_read_b128 v[144:147], v232 offset:36864
	ds_read_b128 v[148:151], v232 offset:49152
	ds_read_b128 v[180:183], v232 offset:53248
	ds_read_b128 v[184:187], v229 offset:32768
	ds_read_b128 v[208:211], v229 offset:36864
	ds_read_b128 v[212:215], v233 offset:32768
	ds_read_b128 v[216:219], v233 offset:36864
	ds_read_b128 v[220:223], v233 offset:49152
	ds_read_b128 v[224:227], v233 offset:53248
	s_waitcnt lgkmcnt(6)
	v_mfma_f32_32x32x16_bf16 v[4:19], v[140:143], v[132:135], v[4:19]
	v_mfma_f32_32x32x16_bf16 v[68:83], v[140:143], v[136:139], v[68:83]
	v_mfma_f32_32x32x16_bf16 v[20:35], v[144:147], v[132:135], v[20:35]
	v_mfma_f32_32x32x16_bf16 v[84:99], v[144:147], v[136:139], v[84:99]
	v_mfma_f32_32x32x16_bf16 v[36:51], v[148:151], v[132:135], v[36:51]
	v_mfma_f32_32x32x16_bf16 v[100:115], v[148:151], v[136:139], v[100:115]
	v_mfma_f32_32x32x16_bf16 v[52:67], v[180:183], v[132:135], v[52:67]
	v_mfma_f32_32x32x16_bf16 v[116:131], v[180:183], v[136:139], v[116:131]
	ds_read_b128 v[132:135], v230 offset:32768
	ds_read_b128 v[136:139], v230 offset:36864
	ds_read_b128 v[140:143], v234 offset:32768
	ds_read_b128 v[144:147], v234 offset:36864
	ds_read_b128 v[148:151], v234 offset:49152
	ds_read_b128 v[180:183], v234 offset:53248
	s_waitcnt lgkmcnt(6)
	v_mfma_f32_32x32x16_bf16 v[4:19], v[212:215], v[184:187], v[4:19]
	v_mfma_f32_32x32x16_bf16 v[68:83], v[212:215], v[208:211], v[68:83]
	v_mfma_f32_32x32x16_bf16 v[20:35], v[216:219], v[184:187], v[20:35]
	v_mfma_f32_32x32x16_bf16 v[84:99], v[216:219], v[208:211], v[84:99]
	v_mfma_f32_32x32x16_bf16 v[36:51], v[220:223], v[184:187], v[36:51]
	v_mfma_f32_32x32x16_bf16 v[100:115], v[220:223], v[208:211], v[100:115]
	v_mfma_f32_32x32x16_bf16 v[52:67], v[224:227], v[184:187], v[52:67]
	v_mfma_f32_32x32x16_bf16 v[116:131], v[224:227], v[208:211], v[116:131]
	ds_read_b128 v[184:187], v231 offset:32768
	ds_read_b128 v[208:211], v231 offset:36864
	ds_read_b128 v[212:215], v235 offset:32768
	ds_read_b128 v[216:219], v235 offset:36864
	ds_read_b128 v[220:223], v235 offset:49152
	ds_read_b128 v[224:227], v235 offset:53248
	s_waitcnt lgkmcnt(6)
	v_mfma_f32_32x32x16_bf16 v[4:19], v[140:143], v[132:135], v[4:19]
	v_mfma_f32_32x32x16_bf16 v[68:83], v[140:143], v[136:139], v[68:83]
	v_mfma_f32_32x32x16_bf16 v[20:35], v[144:147], v[132:135], v[20:35]
	v_mfma_f32_32x32x16_bf16 v[84:99], v[144:147], v[136:139], v[84:99]
	v_mfma_f32_32x32x16_bf16 v[36:51], v[148:151], v[132:135], v[36:51]
	v_mfma_f32_32x32x16_bf16 v[100:115], v[148:151], v[136:139], v[100:115]
	v_mfma_f32_32x32x16_bf16 v[52:67], v[180:183], v[132:135], v[52:67]
	v_mfma_f32_32x32x16_bf16 v[116:131], v[180:183], v[136:139], v[116:131]
	s_waitcnt lgkmcnt(0)
	v_mfma_f32_32x32x16_bf16 v[4:19], v[212:215], v[184:187], v[4:19]
	v_mfma_f32_32x32x16_bf16 v[68:83], v[212:215], v[208:211], v[68:83]
	v_mfma_f32_32x32x16_bf16 v[20:35], v[216:219], v[184:187], v[20:35]
	v_mfma_f32_32x32x16_bf16 v[84:99], v[216:219], v[208:211], v[84:99]
	v_mfma_f32_32x32x16_bf16 v[36:51], v[220:223], v[184:187], v[36:51]
	v_mfma_f32_32x32x16_bf16 v[100:115], v[220:223], v[208:211], v[100:115]
	v_mfma_f32_32x32x16_bf16 v[52:67], v[224:227], v[184:187], v[52:67]
	v_mfma_f32_32x32x16_bf16 v[116:131], v[224:227], v[208:211], v[116:131]
	s_waitcnt lgkmcnt(0)
	s_barrier
; DI void outproj_tile(const Params& p, int l, int mt, int nt, char* lds, int khalf) {
;     ...
;     gemm_tile<true>(A, 2048, Bw, 2048, klen, lds, [&](int mi, int ni, const f32x16& a) {
;       const int tok = m0 + wm * 64 + mi * 32 + r;
;       float* rp = p.R + (size_t)tok * DM + nt * 128 + wn * 64 + ni * 32;
; #pragma unroll
;       for (int g = 0; g < 4; ++g) {
;         f32x4 v = *(const f32x4*)(rp + 8 * g + 4 * h);
; #pragma unroll
;         for (int e = 0; e < 4; ++e) v[e] = ALPHA * v[e] + a[4 * g + e];
;         *(f32x4*)(rp + 8 * g + 4 * h) = v;
;       }
	s_mov_b32 s16, 0x3fd744fd
	s_nop 7
	s_nop 7
	global_load_dwordx4 v[132:135], v242, s[24:25]
	global_load_dwordx4 v[136:139], v242, s[24:25] offset:32
	global_load_dwordx4 v[140:143], v242, s[24:25] offset:64
	global_load_dwordx4 v[144:147], v242, s[24:25] offset:96
	global_load_dwordx4 v[148:151], v242, s[24:25] offset:128
	global_load_dwordx4 v[180:183], v242, s[24:25] offset:160
	global_load_dwordx4 v[184:187], v242, s[24:25] offset:192
	global_load_dwordx4 v[208:211], v242, s[24:25] offset:224
	s_waitcnt vmcnt(7)
	v_pk_fma_f32 v[4:5], v[132:133], s[16:17], v[4:5] op_sel_hi:[1,0,1]
	v_pk_fma_f32 v[6:7], v[134:135], s[16:17], v[6:7] op_sel_hi:[1,0,1]
	global_store_dwordx4 v242, v[4:7], s[24:25]
	s_waitcnt vmcnt(7)
	v_pk_fma_f32 v[8:9], v[136:137], s[16:17], v[8:9] op_sel_hi:[1,0,1]
	v_pk_fma_f32 v[10:11], v[138:139], s[16:17], v[10:11] op_sel_hi:[1,0,1]
	global_store_dwordx4 v242, v[8:11], s[24:25] offset:32
	s_waitcnt vmcnt(7)
	v_pk_fma_f32 v[12:13], v[140:141], s[16:17], v[12:13] op_sel_hi:[1,0,1]
	v_pk_fma_f32 v[14:15], v[142:143], s[16:17], v[14:15] op_sel_hi:[1,0,1]
	global_store_dwordx4 v242, v[12:15], s[24:25] offset:64
	s_waitcnt vmcnt(7)
	v_pk_fma_f32 v[16:17], v[144:145], s[16:17], v[16:17] op_sel_hi:[1,0,1]
	v_pk_fma_f32 v[18:19], v[146:147], s[16:17], v[18:19] op_sel_hi:[1,0,1]
	global_store_dwordx4 v242, v[16:19], s[24:25] offset:96
	s_waitcnt vmcnt(7)
	v_pk_fma_f32 v[20:21], v[148:149], s[16:17], v[20:21] op_sel_hi:[1,0,1]
	v_pk_fma_f32 v[22:23], v[150:151], s[16:17], v[22:23] op_sel_hi:[1,0,1]
	global_store_dwordx4 v242, v[20:23], s[24:25] offset:128
	s_waitcnt vmcnt(7)
	v_pk_fma_f32 v[24:25], v[180:181], s[16:17], v[24:25] op_sel_hi:[1,0,1]
	v_pk_fma_f32 v[26:27], v[182:183], s[16:17], v[26:27] op_sel_hi:[1,0,1]
	global_store_dwordx4 v242, v[24:27], s[24:25] offset:160
	s_waitcnt vmcnt(7)
	v_pk_fma_f32 v[28:29], v[184:185], s[16:17], v[28:29] op_sel_hi:[1,0,1]
	v_pk_fma_f32 v[30:31], v[186:187], s[16:17], v[30:31] op_sel_hi:[1,0,1]
	global_store_dwordx4 v242, v[28:31], s[24:25] offset:192
	s_waitcnt vmcnt(7)
	v_pk_fma_f32 v[32:33], v[208:209], s[16:17], v[32:33] op_sel_hi:[1,0,1]
	v_pk_fma_f32 v[34:35], v[210:211], s[16:17], v[34:35] op_sel_hi:[1,0,1]
	global_store_dwordx4 v242, v[32:35], s[24:25] offset:224
	global_load_dwordx4 v[132:135], v242, s[24:25] offset:512
	global_load_dwordx4 v[136:139], v242, s[24:25] offset:544
	global_load_dwordx4 v[140:143], v242, s[24:25] offset:576
	global_load_dwordx4 v[144:147], v242, s[24:25] offset:608
	global_load_dwordx4 v[148:151], v242, s[24:25] offset:640
	global_load_dwordx4 v[180:183], v242, s[24:25] offset:672
	global_load_dwordx4 v[184:187], v242, s[24:25] offset:704
	global_load_dwordx4 v[208:211], v242, s[24:25] offset:736
	s_waitcnt vmcnt(7)
	v_pk_fma_f32 v[36:37], v[132:133], s[16:17], v[36:37] op_sel_hi:[1,0,1]
	v_pk_fma_f32 v[38:39], v[134:135], s[16:17], v[38:39] op_sel_hi:[1,0,1]
	global_store_dwordx4 v242, v[36:39], s[24:25] offset:512
	s_waitcnt vmcnt(7)
	v_pk_fma_f32 v[40:41], v[136:137], s[16:17], v[40:41] op_sel_hi:[1,0,1]
	v_pk_fma_f32 v[42:43], v[138:139], s[16:17], v[42:43] op_sel_hi:[1,0,1]
	global_store_dwordx4 v242, v[40:43], s[24:25] offset:544
	s_waitcnt vmcnt(7)
	v_pk_fma_f32 v[44:45], v[140:141], s[16:17], v[44:45] op_sel_hi:[1,0,1]
	v_pk_fma_f32 v[46:47], v[142:143], s[16:17], v[46:47] op_sel_hi:[1,0,1]
	global_store_dwordx4 v242, v[44:47], s[24:25] offset:576
	s_waitcnt vmcnt(7)
	v_pk_fma_f32 v[48:49], v[144:145], s[16:17], v[48:49] op_sel_hi:[1,0,1]
	v_pk_fma_f32 v[50:51], v[146:147], s[16:17], v[50:51] op_sel_hi:[1,0,1]
	global_store_dwordx4 v242, v[48:51], s[24:25] offset:608
	s_waitcnt vmcnt(7)
	v_pk_fma_f32 v[52:53], v[148:149], s[16:17], v[52:53] op_sel_hi:[1,0,1]
	v_pk_fma_f32 v[54:55], v[150:151], s[16:17], v[54:55] op_sel_hi:[1,0,1]
	global_store_dwordx4 v242, v[52:55], s[24:25] offset:640
	s_waitcnt vmcnt(7)
	v_pk_fma_f32 v[56:57], v[180:181], s[16:17], v[56:57] op_sel_hi:[1,0,1]
	v_pk_fma_f32 v[58:59], v[182:183], s[16:17], v[58:59] op_sel_hi:[1,0,1]
	global_store_dwordx4 v242, v[56:59], s[24:25] offset:672
	s_waitcnt vmcnt(7)
	v_pk_fma_f32 v[60:61], v[184:185], s[16:17], v[60:61] op_sel_hi:[1,0,1]
	v_pk_fma_f32 v[62:63], v[186:187], s[16:17], v[62:63] op_sel_hi:[1,0,1]
	global_store_dwordx4 v242, v[60:63], s[24:25] offset:704
	s_waitcnt vmcnt(7)
	v_pk_fma_f32 v[64:65], v[208:209], s[16:17], v[64:65] op_sel_hi:[1,0,1]
	v_pk_fma_f32 v[66:67], v[210:211], s[16:17], v[66:67] op_sel_hi:[1,0,1]
	global_store_dwordx4 v242, v[64:67], s[24:25] offset:736
	global_load_dwordx4 v[132:135], v243, s[24:25]
	global_load_dwordx4 v[136:139], v243, s[24:25] offset:32
	global_load_dwordx4 v[140:143], v243, s[24:25] offset:64
	global_load_dwordx4 v[144:147], v243, s[24:25] offset:96
	global_load_dwordx4 v[148:151], v243, s[24:25] offset:128
	global_load_dwordx4 v[180:183], v243, s[24:25] offset:160
	global_load_dwordx4 v[184:187], v243, s[24:25] offset:192
	global_load_dwordx4 v[208:211], v243, s[24:25] offset:224
	s_waitcnt vmcnt(7)
; DI void outproj_tile(const Params& p, int l, int mt, int nt, char* lds, int khalf) {
;     ...
;       float* rp = p.R + (size_t)tok * DM + nt * 128 + wn * 64 + ni * 32;
; #pragma unroll
;       for (int g = 0; g < 4; ++g) {
;         f32x4 v = *(const f32x4*)(rp + 8 * g + 4 * h);
; #pragma unroll
;         for (int e = 0; e < 4; ++e) v[e] = ALPHA * v[e] + a[4 * g + e];
;         *(f32x4*)(rp + 8 * g + 4 * h) = v;
;       }
; __global__ void __launch_bounds__(NTHREADS) mega(Params p) {
;     ...
;     for (int j = blockIdx.x; j < 512; j += gridDim.x) {
;       const int x = j & 7, a = j >> 3;
;       outproj_tile(p, l, 2 * (a >> 1) + (x >> 2), 2 * (x & 3) + (a & 1), lds, -1);
	v_pk_fma_f32 v[68:69], v[132:133], s[16:17], v[68:69] op_sel_hi:[1,0,1]
	v_pk_fma_f32 v[70:71], v[134:135], s[16:17], v[70:71] op_sel_hi:[1,0,1]
	global_store_dwordx4 v243, v[68:71], s[24:25]
	s_waitcnt vmcnt(7)
	v_pk_fma_f32 v[72:73], v[136:137], s[16:17], v[72:73] op_sel_hi:[1,0,1]
	v_pk_fma_f32 v[74:75], v[138:139], s[16:17], v[74:75] op_sel_hi:[1,0,1]
	global_store_dwordx4 v243, v[72:75], s[24:25] offset:32
	s_waitcnt vmcnt(7)
	v_pk_fma_f32 v[76:77], v[140:141], s[16:17], v[76:77] op_sel_hi:[1,0,1]
	v_pk_fma_f32 v[78:79], v[142:143], s[16:17], v[78:79] op_sel_hi:[1,0,1]
	global_store_dwordx4 v243, v[76:79], s[24:25] offset:64
	s_waitcnt vmcnt(7)
	v_pk_fma_f32 v[80:81], v[144:145], s[16:17], v[80:81] op_sel_hi:[1,0,1]
	v_pk_fma_f32 v[82:83], v[146:147], s[16:17], v[82:83] op_sel_hi:[1,0,1]
	global_store_dwordx4 v243, v[80:83], s[24:25] offset:96
	s_waitcnt vmcnt(7)
	v_pk_fma_f32 v[84:85], v[148:149], s[16:17], v[84:85] op_sel_hi:[1,0,1]
	v_pk_fma_f32 v[86:87], v[150:151], s[16:17], v[86:87] op_sel_hi:[1,0,1]
	global_store_dwordx4 v243, v[84:87], s[24:25] offset:128
	s_waitcnt vmcnt(7)
	v_pk_fma_f32 v[88:89], v[180:181], s[16:17], v[88:89] op_sel_hi:[1,0,1]
	v_pk_fma_f32 v[90:91], v[182:183], s[16:17], v[90:91] op_sel_hi:[1,0,1]
	global_store_dwordx4 v243, v[88:91], s[24:25] offset:160
	s_waitcnt vmcnt(7)
	v_pk_fma_f32 v[92:93], v[184:185], s[16:17], v[92:93] op_sel_hi:[1,0,1]
	v_pk_fma_f32 v[94:95], v[186:187], s[16:17], v[94:95] op_sel_hi:[1,0,1]
	global_store_dwordx4 v243, v[92:95], s[24:25] offset:192
	s_waitcnt vmcnt(7)
	v_pk_fma_f32 v[96:97], v[208:209], s[16:17], v[96:97] op_sel_hi:[1,0,1]
	v_pk_fma_f32 v[98:99], v[210:211], s[16:17], v[98:99] op_sel_hi:[1,0,1]
	global_store_dwordx4 v243, v[96:99], s[24:25] offset:224
	global_load_dwordx4 v[132:135], v243, s[24:25] offset:512
	global_load_dwordx4 v[136:139], v243, s[24:25] offset:544
	global_load_dwordx4 v[140:143], v243, s[24:25] offset:576
	global_load_dwordx4 v[144:147], v243, s[24:25] offset:608
	global_load_dwordx4 v[148:151], v243, s[24:25] offset:640
	global_load_dwordx4 v[180:183], v243, s[24:25] offset:672
	global_load_dwordx4 v[184:187], v243, s[24:25] offset:704
	global_load_dwordx4 v[208:211], v243, s[24:25] offset:736
	s_waitcnt vmcnt(7)
	v_pk_fma_f32 v[100:101], v[132:133], s[16:17], v[100:101] op_sel_hi:[1,0,1]
	v_pk_fma_f32 v[102:103], v[134:135], s[16:17], v[102:103] op_sel_hi:[1,0,1]
	global_store_dwordx4 v243, v[100:103], s[24:25] offset:512
	s_waitcnt vmcnt(7)
	v_pk_fma_f32 v[104:105], v[136:137], s[16:17], v[104:105] op_sel_hi:[1,0,1]
	v_pk_fma_f32 v[106:107], v[138:139], s[16:17], v[106:107] op_sel_hi:[1,0,1]
	global_store_dwordx4 v243, v[104:107], s[24:25] offset:544
	s_waitcnt vmcnt(7)
	v_pk_fma_f32 v[108:109], v[140:141], s[16:17], v[108:109] op_sel_hi:[1,0,1]
	v_pk_fma_f32 v[110:111], v[142:143], s[16:17], v[110:111] op_sel_hi:[1,0,1]
	global_store_dwordx4 v243, v[108:111], s[24:25] offset:576
	s_waitcnt vmcnt(7)
	v_pk_fma_f32 v[112:113], v[144:145], s[16:17], v[112:113] op_sel_hi:[1,0,1]
	v_pk_fma_f32 v[114:115], v[146:147], s[16:17], v[114:115] op_sel_hi:[1,0,1]
	global_store_dwordx4 v243, v[112:115], s[24:25] offset:608
	s_waitcnt vmcnt(7)
	v_pk_fma_f32 v[116:117], v[148:149], s[16:17], v[116:117] op_sel_hi:[1,0,1]
	v_pk_fma_f32 v[118:119], v[150:151], s[16:17], v[118:119] op_sel_hi:[1,0,1]
	global_store_dwordx4 v243, v[116:119], s[24:25] offset:640
	s_waitcnt vmcnt(7)
	v_pk_fma_f32 v[120:121], v[180:181], s[16:17], v[120:121] op_sel_hi:[1,0,1]
	v_pk_fma_f32 v[122:123], v[182:183], s[16:17], v[122:123] op_sel_hi:[1,0,1]
	global_store_dwordx4 v243, v[120:123], s[24:25] offset:672
	s_waitcnt vmcnt(7)
	v_pk_fma_f32 v[124:125], v[184:185], s[16:17], v[124:125] op_sel_hi:[1,0,1]
	v_pk_fma_f32 v[126:127], v[186:187], s[16:17], v[126:127] op_sel_hi:[1,0,1]
	global_store_dwordx4 v243, v[124:127], s[24:25] offset:704
	s_waitcnt vmcnt(7)
	v_pk_fma_f32 v[128:129], v[208:209], s[16:17], v[128:129] op_sel_hi:[1,0,1]
	v_pk_fma_f32 v[130:131], v[210:211], s[16:17], v[130:131] op_sel_hi:[1,0,1]
	global_store_dwordx4 v243, v[128:131], s[24:25] offset:736
	v_readlane_b32 s9, v238, 16
	s_bfe_u32 s1, s9, 0x10003
	s_bfe_u32 s0, s9, 0x10002
	s_lshl_b32 s11, s0, 8
	s_lshl_b32 s2, s9, 1
	s_and_b32 s2, s2, 6
	s_or_b32 s10, s2, s1
	s_addk_i32 s9, 0x200
	v_readlane_b32 s0, v238, 18
	s_lshl_b32 s0, s0, 1
	s_add_i32 s8, s8, s0
	v_readlane_b32 s27, v240, 16
	v_readlane_b32 s12, v241, 40
	v_readlane_b32 s20, v240, 9
	v_readlane_b32 s22, v240, 11
	v_readlane_b32 s23, v240, 12
	v_readlane_b32 s13, v241, 41
	v_readlane_b32 s17, v241, 45
	s_branch .LBB0_2492
